# GEMM epilogues of phases G, I, J: residual / row-scale loads prefetched several pieces ahead into dead MFMA fragment registers behind counted vmcnt waits; hot loop heads pinned mod 64 B with s_nop pad
# speedup vs baseline: 1.0399x; 1.0050x over previous
; #define LAS __attribute__((address_space(3)))
; __device__ __forceinline__ float wave_max(float v) { v = fmaxf(v, __shfl_xor(v, 1)); v = fmaxf(v, __shfl_xor(v, 2)); v = fmaxf(v, __shfl_xor(v, 4)); v = fmaxf(v, __shfl_xor(v, 8)); v = fmaxf(v, __shfl_xor(v, 16)); v = fmaxf(v, __shfl_xor(v, 32)); return v; }
; #define INP(k) ({ int k_ = (k); LAUNDER_S(k_); (const float*)(const GAS float*)P.in[k_]; })
; __global__ void __launch_bounds__(512, 2) hybrid_fwd(Params P) {
;     ...
;         { PHASE_BEGIN
;             LAS unsigned* misc = (LAS unsigned*)(lds + ATT_MISC); LAS float* btab = (LAS float*)(lds + ATT_BT);
;             const float* rel_bias = INP(1);
;             __syncthreads();
;             if (wave == 0) { const float* mqn = INP(4) + L * 64; const float* mkn = INP(5) + L * 64; const float* nqn = INP(6) + L * 64; const float* nkn = INP(7) + L * 192;
;                 float gq = fmaxf(fabsf(mqn[lane]), fabsf(nqn[lane])); float gk = fmaxf(fmaxf(fabsf(mkn[lane]), fabsf(nkn[lane])), fmaxf(fabsf(nkn[64 + lane]), fabsf(nkn[128 + lane])));
;                 float bm = 0.f;
; #pragma unroll
;                 for (int i = 0; i < 6; ++i) bm = fmaxf(bm, fabsf(rel_bias[lane + 64 * i]));
;                 gq = wave_max(gq); gk = wave_max(gk); bm = wave_max(bm);
;                 if (lane == 0) ((LAS float*)misc)[2] = 8.0f * gq * gk + bm; }
.LBB0_794:
	s_or_b64 exec, exec, s[4:5]
	v_readlane_b32 s4, v255, 17
	s_mov_b64 s[6:7], s[58:59]
	s_mov_b32 s5, s69
	s_barrier
	v_lshrrev_b32_e32 v0, 8, v146
	s_nop 0
	v_readfirstlane_b32 s98, v0
	s_cmp_eq_u32 s98, 0
	s_cbranch_scc1 .Lprio_skip_4
	s_setprio 1
.Lprio_skip_4:
	s_mov_b32 s5, s2
	v_mov_b32_e32 v210, v146
	s_mov_b32 s8, 1
	s_ashr_i32 s9, s8, 31
	s_lshl_b64 s[8:9], s[8:9], 3
	s_add_u32 s8, s0, s8
	s_addc_u32 s9, s1, s9
	s_load_dwordx2 s[8:9], s[8:9], 0x0
	v_readfirstlane_b32 s5, v210
	s_cmp_lt_u32 s5, 64
	s_waitcnt lgkmcnt(0)
	s_barrier
	s_cbranch_scc0 .LBB0_798
	s_mov_b32 s10, 4
	s_ashr_i32 s11, s10, 31
	s_lshl_b64 s[10:11], s[10:11], 3
	s_add_u32 s10, s0, s10
	s_addc_u32 s11, s1, s11
	s_load_dwordx2 s[12:13], s[10:11], 0x0
	s_lshl_b32 s10, s4, 6
	s_ashr_i32 s11, s10, 31
	s_lshl_b64 s[10:11], s[10:11], 2
	s_mov_b32 s14, 5
	s_waitcnt lgkmcnt(0)
	s_add_u32 s12, s12, s10
	s_addc_u32 s13, s13, s11
	s_ashr_i32 s15, s14, 31
	s_lshl_b64 s[14:15], s[14:15], 3
	s_add_u32 s14, s0, s14
	s_addc_u32 s15, s1, s15
	s_load_dwordx2 s[14:15], s[14:15], 0x0
	s_mov_b32 s16, 6
	v_and_b32_e32 v0, 63, v210
	v_lshlrev_b32_e32 v1, 2, v0
	s_waitcnt lgkmcnt(0)
	s_add_u32 s18, s14, s10
	s_addc_u32 s19, s15, s11
	s_ashr_i32 s17, s16, 31
	s_lshl_b64 s[14:15], s[16:17], 3
	s_add_u32 s14, s0, s14
	s_addc_u32 s15, s1, s15
	s_load_dwordx2 s[14:15], s[14:15], 0x0
	s_mov_b32 s16, 7
	global_load_dword v2, v1, s[18:19]
	global_load_dword v3, v1, s[8:9]
	global_load_dword v4, v1, s[8:9] offset:256
	global_load_dword v5, v1, s[8:9] offset:512
	global_load_dword v6, v1, s[8:9] offset:768
	global_load_dword v7, v1, s[8:9] offset:1024
	global_load_dword v8, v1, s[8:9] offset:1280
	global_load_dword v9, v1, s[12:13]
	s_mul_i32 s12, s4, 0xc0
	s_waitcnt lgkmcnt(0)
	s_add_u32 s10, s14, s10
	s_addc_u32 s11, s15, s11
	s_ashr_i32 s17, s16, 31
	global_load_dword v10, v1, s[10:11]
	s_lshl_b64 s[10:11], s[16:17], 3
	s_add_u32 s10, s0, s10
	s_addc_u32 s11, s1, s11
	s_load_dwordx2 s[10:11], s[10:11], 0x0
	s_ashr_i32 s13, s12, 31
	s_lshl_b64 s[12:13], s[12:13], 2
	v_mbcnt_hi_u32_b32 v13, -1, v167
	v_and_b32_e32 v15, 64, v13
	s_waitcnt lgkmcnt(0)
	s_add_u32 s10, s10, s12
	s_addc_u32 s11, s11, s13
	global_load_dword v11, v1, s[10:11] offset:512
	global_load_dword v12, v1, s[10:11] offset:256
	s_nop 0
	global_load_dword v1, v1, s[10:11]
	v_xor_b32_e32 v14, 1, v13
	v_add_u32_e32 v15, 64, v15
	v_cmp_lt_i32_e32 vcc, v14, v15
	v_xor_b32_e32 v16, 2, v13
	v_xor_b32_e32 v17, 4, v13
	v_cndmask_b32_e32 v14, v13, v14, vcc
	v_lshlrev_b32_e32 v14, 2, v14
	v_cmp_lt_i32_e32 vcc, v16, v15
	v_xor_b32_e32 v18, 8, v13
	v_xor_b32_e32 v19, 16, v13
	v_cndmask_b32_e32 v16, v13, v16, vcc
	v_cmp_lt_i32_e32 vcc, v17, v15
	v_xor_b32_e32 v20, 32, v13
	s_waitcnt vmcnt(9)
	v_max3_f32 v3, |v3|, 0, |v4|
	v_cndmask_b32_e32 v17, v13, v17, vcc
	s_waitcnt vmcnt(7)
	v_max3_f32 v3, v3, |v5|, |v6|
	v_cmp_lt_i32_e32 vcc, v18, v15
	s_waitcnt vmcnt(5)
	v_max3_f32 v3, v3, |v7|, |v8|
	ds_bpermute_b32 v4, v14, v3
	v_cndmask_b32_e32 v18, v13, v18, vcc
	v_cmp_lt_i32_e32 vcc, v19, v15
	s_waitcnt vmcnt(4)
	v_max_f32_e64 v6, |v9|, |v9|
	v_lshlrev_b32_e32 v5, 2, v18
	s_waitcnt lgkmcnt(0)
	v_max_f32_e32 v4, v4, v4
	v_cndmask_b32_e32 v19, v13, v19, vcc
	v_cmp_lt_i32_e32 vcc, v20, v15
	v_lshlrev_b32_e32 v15, 2, v16
	v_max_f32_e32 v3, v3, v4
	ds_bpermute_b32 v4, v15, v3
	s_waitcnt vmcnt(3)
	v_max_f32_e64 v7, |v10|, |v10|
	v_max_f32_e32 v6, v6, v7
	ds_bpermute_b32 v7, v14, v6
	v_lshlrev_b32_e32 v16, 2, v17
	s_waitcnt lgkmcnt(1)
	v_max_f32_e32 v4, v4, v4
	v_max_f32_e32 v3, v3, v4
	s_waitcnt vmcnt(2)
	v_max_f32_e64 v4, |v11|, |v11|
	s_waitcnt vmcnt(1)
	v_max_f32_e64 v10, |v12|, |v12|
	v_max_f32_e32 v4, v10, v4
	s_waitcnt vmcnt(0)
	v_max3_f32 v1, |v2|, |v1|, v4
	ds_bpermute_b32 v2, v14, v1
	s_waitcnt lgkmcnt(1)
	v_max_f32_e32 v7, v7, v7
	v_max_f32_e32 v6, v6, v7
	ds_bpermute_b32 v7, v15, v6
	ds_bpermute_b32 v11, v16, v3
	s_waitcnt lgkmcnt(2)
	v_max_f32_e32 v2, v2, v2
	v_max_f32_e32 v1, v1, v2
	ds_bpermute_b32 v2, v15, v1
	s_waitcnt lgkmcnt(2)
	v_max_f32_e32 v4, v7, v7
	v_max_f32_e32 v4, v6, v4
	s_waitcnt lgkmcnt(1)
	v_max_f32_e32 v6, v11, v11
	ds_bpermute_b32 v7, v16, v4
	s_waitcnt lgkmcnt(1)
	v_max_f32_e32 v2, v2, v2
	v_max_f32_e32 v1, v1, v2
	v_max_f32_e32 v3, v3, v6
	ds_bpermute_b32 v2, v16, v1
	ds_bpermute_b32 v6, v5, v3
	s_waitcnt lgkmcnt(2)
	v_max_f32_e32 v7, v7, v7
	v_max_f32_e32 v4, v4, v7
	ds_bpermute_b32 v7, v5, v4
	s_waitcnt lgkmcnt(2)
	v_max_f32_e32 v2, v2, v2
	s_waitcnt lgkmcnt(1)
	v_max_f32_e32 v6, v6, v6
	v_max_f32_e32 v1, v1, v2
	v_lshlrev_b32_e32 v8, 2, v19
	v_max_f32_e32 v3, v3, v6
	ds_bpermute_b32 v2, v5, v1
	ds_bpermute_b32 v6, v8, v3
	s_waitcnt lgkmcnt(2)
	v_max_f32_e32 v5, v7, v7
	v_max_f32_e32 v4, v4, v5
	v_cndmask_b32_e32 v13, v13, v20, vcc
	s_waitcnt lgkmcnt(1)
	v_max_f32_e32 v2, v2, v2
	s_waitcnt lgkmcnt(0)
	v_max_f32_e32 v5, v6, v6
	ds_bpermute_b32 v6, v8, v4
	v_max_f32_e32 v2, v1, v2
	ds_bpermute_b32 v7, v8, v2
	v_max_f32_e32 v1, v3, v5
	v_lshlrev_b32_e32 v9, 2, v13
	s_waitcnt lgkmcnt(1)
	v_max_f32_e32 v3, v6, v6
	v_max_f32_e32 v3, v4, v3
	s_waitcnt lgkmcnt(0)
	v_max_f32_e32 v4, v7, v7
	v_max_f32_e32 v2, v2, v4
	ds_bpermute_b32 v5, v9, v3
	ds_bpermute_b32 v4, v9, v2
	ds_bpermute_b32 v6, v9, v1
	v_cmp_eq_u32_e32 vcc, 0, v0
	s_and_saveexec_b64 s[10:11], vcc
	s_cbranch_execz .LBB0_797
	s_waitcnt lgkmcnt(2)
	v_max_f32_e32 v0, v5, v5
	v_max_f32_e32 v3, v3, v3
	v_max_f32_e32 v0, v3, v0
	s_waitcnt lgkmcnt(1)
	v_max_f32_e32 v3, v4, v4
	v_max_f32_e32 v2, v2, v2
	v_max_f32_e32 v2, v2, v3
	s_waitcnt lgkmcnt(0)
	v_max_f32_e32 v3, v6, v6
	v_max_f32_e32 v1, v1, v1
	v_mul_f32_e32 v0, 0x41000000, v0
	v_max_f32_e32 v1, v1, v3
	v_fmac_f32_e32 v1, v0, v2
	ds_write_b32 v165, v1 offset:50696

; __global__ void __launch_bounds__(512, 2) hybrid_fwd(Params P) {
;     ...
;         grid.sync();
.LBB0_1075:
	s_waitcnt vmcnt(0)
	s_setprio 0
	s_barrier
	s_mov_b64 s[4:5], exec
	v_readlane_b32 s6, v255, 5
	v_readlane_b32 s7, v255, 6
	s_and_b64 s[6:7], s[4:5], s[6:7]
	v_readlane_b32 s34, v255, 17
	s_mov_b64 exec, s[6:7]
	s_cbranch_execz .LBB0_1085
	buffer_wbl2 sc1
	s_waitcnt vmcnt(0)
	v_readlane_b32 s8, v255, 17
	v_mov_b32_e32 v1, 0
	v_mov_b32_e32 v0, 1
	s_lshl_b32 s8, s8, 5
	s_add_u32 s6, s58, s8
	s_addc_u32 s7, s59, 0
	s_mov_b32 s10, 0
	global_atomic_add v1, v0, s[6:7] offset:80

; __device__ __forceinline__ unsigned pk2(float lo, float hi) { f32x2_t v = {lo, hi}; bf16x2_t b = __builtin_convertvector(v, bf16x2_t); return __builtin_bit_cast(unsigned, b); }
; __device__ __forceinline__ float bflo(unsigned w) { return __uint_as_float(w << 16); }
; __device__ __forceinline__ float bfhi(unsigned w) { return __uint_as_float(w & 0xffff0000u); }
;     __device__ __forceinline__ void operator()(const f32x4 (&acc)[2][2][4][2], const pg8::Unit& u, int wr, int wc, int fr_, int fq_) const {
;     ...
;             for (int m = 0; m < 4; ++m) { const unsigned row = (unsigned)(u.pm * 256 + 128 * ai + 64 * wr + 16 * m + fr); float ss = 0.f;
; #pragma unroll
;                 for (int bj = 0; bj < 2; ++bj) { const unsigned o = row * 1024u + (unsigned)(u.pn * 256 + 64 * wc + 32 * bj + 8 * fq);
;                     const u32x4 rb = *(const u32x4*)(resb + o); const f32x4 a0 = acc[ai][bj][m][0], a1 = acc[ai][bj][m][1];
;                     const float y0 = bflo(rb.x) + a0[0], y1 = bfhi(rb.x) + a0[1], y2 = bflo(rb.y) + a0[2], y3 = bfhi(rb.y) + a0[3];
;                     const float y4 = bflo(rb.z) + a1[0], y5 = bfhi(rb.z) + a1[1], y6 = bflo(rb.w) + a1[2], y7 = bfhi(rb.w) + a1[3];
;                     u32x4 w; w.x = pk2(y0, y1); w.y = pk2(y2, y3); w.z = pk2(y4, y5); w.w = pk2(y6, y7);
;                     *(u32x4*)(xb + o) = w;
;                     ss += (y0 * y0 + y1 * y1) + (y2 * y2 + y3 * y3) + (y4 * y4 + y5 * y5) + (y6 * y6 + y7 * y7); }
;                 ss += __shfl_xor(ss, 16); ss += __shfl_xor(ss, 32);
;                 if (fq == 0) atomicAdd(ssq + row, ss);
.LBB0_1129:
	v_mov_b32_e32 v80, v142
	v_mov_b32_e32 v139, v141
	s_lshl_b32 s17, s26, 8
	s_add_i32 s17, s17, s46
	v_and_b32_e32 v145, 64, v195
	v_add_u32_e32 v138, s17, v80
	v_xor_b32_e32 v80, 16, v195
	v_add_u32_e32 v145, 64, v145
	v_cmp_lt_i32_e32 vcc, v80, v145
	s_lshl_b32 s17, s24, 8
	s_or_b32 s17, s17, s49
	v_cndmask_b32_e32 v80, v195, v80, vcc
	v_lshlrev_b32_e32 v152, 2, v80
	v_xor_b32_e32 v80, 32, v195
	v_cmp_lt_i32_e32 vcc, v80, v145
	v_lshl_add_u32 v153, v139, 3, s17
	v_readlane_b32 s56, v255, 10
	v_cndmask_b32_e32 v80, v195, v80, vcc
	v_lshlrev_b32_e32 v145, 2, v80
	v_lshl_add_u32 v80, v138, 10, v153
	v_lshlrev_b64 v[158:159], 1, v[80:81]
	v_readlane_b32 s57, v255, 11
	v_add_u32_e32 v80, 32, v80
	v_cmp_eq_u32_e32 vcc, 0, v139
	v_lshl_add_u64 v[154:155], s[56:57], 0, v[158:159]
	v_mov_b32_e32 v232, v154
	v_mov_b32_e32 v233, v155
	global_load_dwordx4 v[172:175], v[232:233], off offset:0
	global_load_dwordx4 v[176:179], v[232:233], off offset:64
	s_mov_b64 s[98:99], 0x8000
	v_lshl_add_u64 v[232:233], v[232:233], 0, s[98:99]
	global_load_dwordx4 v[180:183], v[232:233], off offset:0
	global_load_dwordx4 v[212:215], v[232:233], off offset:64
	s_mov_b64 s[98:99], 0x8000
	v_lshl_add_u64 v[232:233], v[232:233], 0, s[98:99]
	global_load_dwordx4 v[216:219], v[232:233], off offset:0
	global_load_dwordx4 v[220:223], v[232:233], off offset:64
	s_mov_b64 s[98:99], 0x8000
	v_lshl_add_u64 v[232:233], v[232:233], 0, s[98:99]
	global_load_dwordx4 v[224:227], v[232:233], off offset:0
	global_load_dwordx4 v[228:231], v[232:233], off offset:64
	v_lshl_add_u64 v[158:159], s[10:11], 0, v[158:159]
	v_readlane_b32 s58, v255, 12
	v_readlane_b32 s59, v255, 13
	s_waitcnt vmcnt(7)
	v_mov_b32_e32 v154, v172
	v_mov_b32_e32 v155, v173
	v_mov_b32_e32 v156, v174
	v_mov_b32_e32 v157, v175
	v_lshlrev_b32_e32 v160, 16, v154
	v_and_b32_e32 v161, 0xffff0000, v154
	v_lshlrev_b32_e32 v154, 16, v155
	v_and_b32_e32 v155, 0xffff0000, v155
	v_pk_add_f32 v[128:129], v[128:129], v[154:155]
	v_lshlrev_b32_e32 v154, 16, v156
	v_and_b32_e32 v155, 0xffff0000, v156
	v_pk_add_f32 v[154:155], v[122:123], v[154:155]
	v_lshlrev_b32_e32 v122, 16, v157
	v_and_b32_e32 v123, 0xffff0000, v157
	v_pk_add_f32 v[126:127], v[126:127], v[160:161]
	v_pk_add_f32 v[156:157], v[124:125], v[122:123]
	v_cvt_pk_bf16_f32 v122, v126, v127
	v_cvt_pk_bf16_f32 v123, v128, v129
	v_cvt_pk_bf16_f32 v124, v154, v155
	v_cvt_pk_bf16_f32 v125, v156, v157
	global_store_dwordx4 v[158:159], v[122:125], off
	v_lshlrev_b64 v[158:159], 1, v[80:81]
	s_nop 0
	v_pk_mul_f32 v[122:123], v[154:155], v[154:155]
	v_lshl_add_u64 v[154:155], s[56:57], 0, v[158:159]
	v_pk_mul_f32 v[124:125], v[126:127], v[126:127]
	v_pk_mul_f32 v[126:127], v[128:129], v[128:129]
	v_pk_mul_f32 v[128:129], v[156:157], v[156:157]
	s_mov_b64 s[98:99], 0x28000
	v_lshl_add_u64 v[232:233], v[232:233], 0, s[98:99]
	global_load_dwordx4 v[172:175], v[232:233], off offset:0
	v_lshl_add_u64 v[158:159], s[10:11], 0, v[158:159]
	v_add_f32_e32 v126, v126, v127
	v_add_f32_e32 v124, v124, v125
	v_add_f32_e32 v124, v124, v126
	v_add_f32_e32 v122, v122, v123
	v_add_f32_e32 v80, v128, v129
	v_add_f32_e32 v122, v122, v124
	v_add_f32_e32 v80, v80, v122
	s_waitcnt vmcnt(8)
	v_mov_b32_e32 v154, v176
	v_mov_b32_e32 v155, v177
	v_mov_b32_e32 v156, v178
	v_mov_b32_e32 v157, v179
	v_lshlrev_b32_e32 v160, 16, v154
	v_and_b32_e32 v161, 0xffff0000, v154
	v_lshlrev_b32_e32 v154, 16, v155
	v_and_b32_e32 v155, 0xffff0000, v155
	v_pk_add_f32 v[120:121], v[120:121], v[154:155]
	v_lshlrev_b32_e32 v154, 16, v156
	v_and_b32_e32 v155, 0xffff0000, v156
	v_pk_add_f32 v[154:155], v[114:115], v[154:155]
	v_lshlrev_b32_e32 v114, 16, v157
	v_and_b32_e32 v115, 0xffff0000, v157
	v_pk_add_f32 v[118:119], v[118:119], v[160:161]
	v_pk_add_f32 v[156:157], v[116:117], v[114:115]
	v_cvt_pk_bf16_f32 v114, v118, v119
	v_cvt_pk_bf16_f32 v115, v120, v121
	v_cvt_pk_bf16_f32 v116, v154, v155
	v_cvt_pk_bf16_f32 v117, v156, v157
	global_store_dwordx4 v[158:159], v[114:117], off
	s_nop 1
	v_pk_mul_f32 v[114:115], v[118:119], v[118:119]
	v_pk_mul_f32 v[116:117], v[120:121], v[120:121]
	v_pk_mul_f32 v[118:119], v[154:155], v[154:155]
	v_add_f32_e32 v116, v116, v117
	v_add_f32_e32 v114, v114, v115
	v_pk_mul_f32 v[120:121], v[156:157], v[156:157]
	v_add_f32_e32 v114, v114, v116
	v_add_f32_e32 v115, v118, v119
	v_add_f32_e32 v120, v120, v121
	v_add_f32_e32 v114, v115, v114
	v_add_f32_e32 v114, v120, v114
	v_add_f32_e32 v80, v80, v114
	ds_bpermute_b32 v114, v152, v80
	s_waitcnt lgkmcnt(0)
	v_add_f32_e32 v80, v80, v114
	ds_bpermute_b32 v114, v145, v80
	s_and_saveexec_b64 s[24:25], vcc
	s_cbranch_execz .LBB0_1131
	v_mov_b32_e32 v139, v81
	v_lshl_add_u64 v[116:117], v[138:139], 2, s[12:13]
	s_waitcnt lgkmcnt(0)
	v_add_f32_e32 v80, v80, v114
	global_atomic_add_f32 v[116:117], v80, off
; __device__ __forceinline__ unsigned pk2(float lo, float hi) { f32x2_t v = {lo, hi}; bf16x2_t b = __builtin_convertvector(v, bf16x2_t); return __builtin_bit_cast(unsigned, b); }
; __device__ __forceinline__ float bflo(unsigned w) { return __uint_as_float(w << 16); }
; __device__ __forceinline__ float bfhi(unsigned w) { return __uint_as_float(w & 0xffff0000u); }
;     __device__ __forceinline__ void operator()(const f32x4 (&acc)[2][2][4][2], const pg8::Unit& u, int wr, int wc, int fr_, int fq_) const {
;     ...
;             for (int m = 0; m < 4; ++m) { const unsigned row = (unsigned)(u.pm * 256 + 128 * ai + 64 * wr + 16 * m + fr); float ss = 0.f;
; #pragma unroll
;                 for (int bj = 0; bj < 2; ++bj) { const unsigned o = row * 1024u + (unsigned)(u.pn * 256 + 64 * wc + 32 * bj + 8 * fq);
;                     const u32x4 rb = *(const u32x4*)(resb + o); const f32x4 a0 = acc[ai][bj][m][0], a1 = acc[ai][bj][m][1];
;                     const float y0 = bflo(rb.x) + a0[0], y1 = bfhi(rb.x) + a0[1], y2 = bflo(rb.y) + a0[2], y3 = bfhi(rb.y) + a0[3];
;                     const float y4 = bflo(rb.z) + a1[0], y5 = bfhi(rb.z) + a1[1], y6 = bflo(rb.w) + a1[2], y7 = bfhi(rb.w) + a1[3];
;                     u32x4 w; w.x = pk2(y0, y1); w.y = pk2(y2, y3); w.z = pk2(y4, y5); w.w = pk2(y6, y7);
;                     *(u32x4*)(xb + o) = w;
;                     ss += (y0 * y0 + y1 * y1) + (y2 * y2 + y3 * y3) + (y4 * y4 + y5 * y5) + (y6 * y6 + y7 * y7); }
;                 ss += __shfl_xor(ss, 16); ss += __shfl_xor(ss, 32);
;                 if (fq == 0) atomicAdd(ssq + row, ss);
.LBB0_1131:
	s_or_b64 exec, exec, s[24:25]
	s_waitcnt lgkmcnt(0)
	v_add_u32_e32 v114, 16, v138
	v_lshl_add_u32 v80, v114, 10, v153
	v_lshlrev_b64 v[120:121], 1, v[80:81]
	v_lshl_add_u64 v[116:117], s[56:57], 0, v[120:121]
	global_load_dwordx4 v[176:179], v[232:233], off offset:64
	v_lshl_add_u64 v[120:121], s[10:11], 0, v[120:121]
	v_add_u32_e32 v80, 32, v80
	s_waitcnt vmcnt(9)
	v_mov_b32_e32 v116, v180
	v_mov_b32_e32 v117, v181
	v_mov_b32_e32 v118, v182
	v_mov_b32_e32 v119, v183
	v_lshlrev_b32_e32 v122, 16, v116
	v_and_b32_e32 v123, 0xffff0000, v116
	v_lshlrev_b32_e32 v116, 16, v117
	v_and_b32_e32 v117, 0xffff0000, v117
	v_pk_add_f32 v[112:113], v[112:113], v[116:117]
	v_lshlrev_b32_e32 v116, 16, v118
	v_and_b32_e32 v117, 0xffff0000, v118
	v_pk_add_f32 v[116:117], v[106:107], v[116:117]
	v_lshlrev_b32_e32 v106, 16, v119
	v_and_b32_e32 v107, 0xffff0000, v119
	v_pk_add_f32 v[110:111], v[110:111], v[122:123]
	v_pk_add_f32 v[118:119], v[108:109], v[106:107]
	v_cvt_pk_bf16_f32 v106, v110, v111
	v_cvt_pk_bf16_f32 v107, v112, v113
	v_cvt_pk_bf16_f32 v108, v116, v117
	v_cvt_pk_bf16_f32 v109, v118, v119
	global_store_dwordx4 v[120:121], v[106:109], off
	v_lshlrev_b64 v[120:121], 1, v[80:81]
	v_pk_mul_f32 v[110:111], v[110:111], v[110:111]
	v_pk_mul_f32 v[108:109], v[116:117], v[116:117]
	v_lshl_add_u64 v[116:117], s[56:57], 0, v[120:121]
	v_pk_mul_f32 v[106:107], v[118:119], v[118:119]
	s_mov_b64 s[98:99], 0x8000
	v_lshl_add_u64 v[232:233], v[232:233], 0, s[98:99]
	global_load_dwordx4 v[180:183], v[232:233], off offset:0
	v_lshl_add_u64 v[120:121], s[10:11], 0, v[120:121]
	v_pk_mul_f32 v[112:113], v[112:113], v[112:113]
	v_add_f32_e32 v110, v110, v111
	v_add_f32_e32 v80, v112, v113
	v_add_f32_e32 v80, v110, v80
	v_add_f32_e32 v108, v108, v109
	v_add_f32_e32 v80, v108, v80
	v_add_f32_e32 v106, v106, v107
	v_add_f32_e32 v80, v106, v80
	s_waitcnt vmcnt(10)
	v_mov_b32_e32 v116, v212
	v_mov_b32_e32 v117, v213
	v_mov_b32_e32 v118, v214
	v_mov_b32_e32 v119, v215
	v_lshlrev_b32_e32 v122, 16, v116
	v_and_b32_e32 v123, 0xffff0000, v116
	v_lshlrev_b32_e32 v116, 16, v117
	v_and_b32_e32 v117, 0xffff0000, v117
	v_pk_add_f32 v[104:105], v[104:105], v[116:117]
	v_lshlrev_b32_e32 v116, 16, v118
	v_and_b32_e32 v117, 0xffff0000, v118
	v_pk_add_f32 v[116:117], v[98:99], v[116:117]
	v_lshlrev_b32_e32 v98, 16, v119
	v_and_b32_e32 v99, 0xffff0000, v119
	v_pk_add_f32 v[102:103], v[102:103], v[122:123]
	v_pk_add_f32 v[118:119], v[100:101], v[98:99]
	v_cvt_pk_bf16_f32 v98, v102, v103
	v_cvt_pk_bf16_f32 v99, v104, v105
	v_cvt_pk_bf16_f32 v100, v116, v117
	v_cvt_pk_bf16_f32 v101, v118, v119
	global_store_dwordx4 v[120:121], v[98:101], off
	s_nop 1
	v_pk_mul_f32 v[98:99], v[102:103], v[102:103]
	v_pk_mul_f32 v[100:101], v[104:105], v[104:105]
	v_pk_mul_f32 v[102:103], v[116:117], v[116:117]
	v_add_f32_e32 v100, v100, v101
	v_add_f32_e32 v98, v98, v99
	v_pk_mul_f32 v[104:105], v[118:119], v[118:119]
	v_add_f32_e32 v98, v98, v100
	v_add_f32_e32 v99, v102, v103
	v_add_f32_e32 v98, v99, v98
	v_add_f32_e32 v99, v104, v105
	v_add_f32_e32 v98, v99, v98
	v_add_f32_e32 v80, v80, v98
	ds_bpermute_b32 v98, v152, v80
	s_waitcnt lgkmcnt(0)
	v_add_f32_e32 v80, v80, v98
	ds_bpermute_b32 v98, v145, v80
	s_and_saveexec_b64 s[24:25], vcc
	s_cbranch_execz .LBB0_1133
	v_mov_b32_e32 v115, v81
	v_lshl_add_u64 v[100:101], v[114:115], 2, s[12:13]
	s_waitcnt lgkmcnt(0)
	v_add_f32_e32 v80, v80, v98
	global_atomic_add_f32 v[100:101], v80, off
.LBB0_1133:
	s_or_b64 exec, exec, s[24:25]
	s_waitcnt lgkmcnt(0)
	v_add_u32_e32 v98, 32, v138
	v_lshl_add_u32 v80, v98, 10, v153
	v_lshlrev_b64 v[104:105], 1, v[80:81]
	v_lshl_add_u64 v[100:101], s[56:57], 0, v[104:105]
	global_load_dwordx4 v[212:215], v[232:233], off offset:64
	v_lshl_add_u64 v[104:105], s[10:11], 0, v[104:105]
	v_add_u32_e32 v80, 32, v80
	s_waitcnt vmcnt(11)
	v_mov_b32_e32 v100, v216
	v_mov_b32_e32 v101, v217
	v_mov_b32_e32 v102, v218
	v_mov_b32_e32 v103, v219
	v_lshlrev_b32_e32 v106, 16, v100
	v_and_b32_e32 v107, 0xffff0000, v100
	v_lshlrev_b32_e32 v100, 16, v101
	v_and_b32_e32 v101, 0xffff0000, v101
	v_pk_add_f32 v[96:97], v[96:97], v[100:101]
	v_lshlrev_b32_e32 v100, 16, v102
	v_and_b32_e32 v101, 0xffff0000, v102
	v_pk_add_f32 v[100:101], v[90:91], v[100:101]
	v_lshlrev_b32_e32 v90, 16, v103
	v_and_b32_e32 v91, 0xffff0000, v103
	v_pk_add_f32 v[94:95], v[94:95], v[106:107]
	v_pk_add_f32 v[102:103], v[92:93], v[90:91]
	v_cvt_pk_bf16_f32 v90, v94, v95
	v_cvt_pk_bf16_f32 v91, v96, v97
	v_cvt_pk_bf16_f32 v92, v100, v101
	v_cvt_pk_bf16_f32 v93, v102, v103
	global_store_dwordx4 v[104:105], v[90:93], off
	v_lshlrev_b64 v[104:105], 1, v[80:81]
	v_pk_mul_f32 v[94:95], v[94:95], v[94:95]
	v_pk_mul_f32 v[92:93], v[100:101], v[100:101]
	v_lshl_add_u64 v[100:101], s[56:57], 0, v[104:105]
	v_pk_mul_f32 v[90:91], v[102:103], v[102:103]
	s_mov_b64 s[98:99], 0x8000
	v_lshl_add_u64 v[232:233], v[232:233], 0, s[98:99]
	global_load_dwordx4 v[216:219], v[232:233], off offset:0
	v_lshl_add_u64 v[104:105], s[10:11], 0, v[104:105]
	v_pk_mul_f32 v[96:97], v[96:97], v[96:97]
	v_add_f32_e32 v94, v94, v95
	v_add_f32_e32 v80, v96, v97
	v_add_f32_e32 v80, v94, v80
	v_add_f32_e32 v92, v92, v93
	v_add_f32_e32 v80, v92, v80
	v_add_f32_e32 v90, v90, v91
	v_add_f32_e32 v80, v90, v80
	s_waitcnt vmcnt(12)
	v_mov_b32_e32 v100, v220
	v_mov_b32_e32 v101, v221
	v_mov_b32_e32 v102, v222
	v_mov_b32_e32 v103, v223
	v_lshlrev_b32_e32 v106, 16, v100
	v_and_b32_e32 v107, 0xffff0000, v100
	v_lshlrev_b32_e32 v100, 16, v101
	v_and_b32_e32 v101, 0xffff0000, v101
	v_pk_add_f32 v[88:89], v[88:89], v[100:101]
	v_lshlrev_b32_e32 v100, 16, v102
	v_and_b32_e32 v101, 0xffff0000, v102
	v_pk_add_f32 v[100:101], v[82:83], v[100:101]
	v_lshlrev_b32_e32 v82, 16, v103
	v_and_b32_e32 v83, 0xffff0000, v103
	v_pk_add_f32 v[86:87], v[86:87], v[106:107]
	v_pk_add_f32 v[102:103], v[84:85], v[82:83]
	v_cvt_pk_bf16_f32 v82, v86, v87
	v_cvt_pk_bf16_f32 v83, v88, v89
	v_cvt_pk_bf16_f32 v84, v100, v101
	v_cvt_pk_bf16_f32 v85, v102, v103
	global_store_dwordx4 v[104:105], v[82:85], off
	s_nop 1
	v_pk_mul_f32 v[82:83], v[86:87], v[86:87]
	v_pk_mul_f32 v[84:85], v[88:89], v[88:89]
	v_pk_mul_f32 v[86:87], v[100:101], v[100:101]
	v_add_f32_e32 v84, v84, v85
	v_add_f32_e32 v82, v82, v83
	v_pk_mul_f32 v[88:89], v[102:103], v[102:103]
	v_add_f32_e32 v82, v82, v84
	v_add_f32_e32 v83, v86, v87
	v_add_f32_e32 v82, v83, v82
	v_add_f32_e32 v83, v88, v89
	v_add_f32_e32 v82, v83, v82
	v_add_f32_e32 v80, v80, v82
	ds_bpermute_b32 v82, v152, v80
	s_waitcnt lgkmcnt(0)
	v_add_f32_e32 v80, v80, v82
	ds_bpermute_b32 v82, v145, v80
	s_and_saveexec_b64 s[24:25], vcc
	s_cbranch_execz .LBB0_1135
	v_mov_b32_e32 v99, v81
	v_lshl_add_u64 v[84:85], v[98:99], 2, s[12:13]
	s_waitcnt lgkmcnt(0)
	v_add_f32_e32 v80, v80, v82
	global_atomic_add_f32 v[84:85], v80, off
; __device__ __forceinline__ unsigned pk2(float lo, float hi) { f32x2_t v = {lo, hi}; bf16x2_t b = __builtin_convertvector(v, bf16x2_t); return __builtin_bit_cast(unsigned, b); }
; __device__ __forceinline__ float bflo(unsigned w) { return __uint_as_float(w << 16); }
; __device__ __forceinline__ float bfhi(unsigned w) { return __uint_as_float(w & 0xffff0000u); }
;     __device__ __forceinline__ void operator()(const f32x4 (&acc)[2][2][4][2], const pg8::Unit& u, int wr, int wc, int fr_, int fq_) const {
;     ...
;             for (int m = 0; m < 4; ++m) { const unsigned row = (unsigned)(u.pm * 256 + 128 * ai + 64 * wr + 16 * m + fr); float ss = 0.f;
; #pragma unroll
;                 for (int bj = 0; bj < 2; ++bj) { const unsigned o = row * 1024u + (unsigned)(u.pn * 256 + 64 * wc + 32 * bj + 8 * fq);
;                     const u32x4 rb = *(const u32x4*)(resb + o); const f32x4 a0 = acc[ai][bj][m][0], a1 = acc[ai][bj][m][1];
;                     const float y0 = bflo(rb.x) + a0[0], y1 = bfhi(rb.x) + a0[1], y2 = bflo(rb.y) + a0[2], y3 = bfhi(rb.y) + a0[3];
;                     const float y4 = bflo(rb.z) + a1[0], y5 = bfhi(rb.z) + a1[1], y6 = bflo(rb.w) + a1[2], y7 = bfhi(rb.w) + a1[3];
;                     u32x4 w; w.x = pk2(y0, y1); w.y = pk2(y2, y3); w.z = pk2(y4, y5); w.w = pk2(y6, y7);
;                     *(u32x4*)(xb + o) = w;
;                     ss += (y0 * y0 + y1 * y1) + (y2 * y2 + y3 * y3) + (y4 * y4 + y5 * y5) + (y6 * y6 + y7 * y7); }
;                 ss += __shfl_xor(ss, 16); ss += __shfl_xor(ss, 32);
;                 if (fq == 0) atomicAdd(ssq + row, ss);
.LBB0_1135:
	s_or_b64 exec, exec, s[24:25]
	s_waitcnt lgkmcnt(0)
	v_add_u32_e32 v82, 48, v138
	v_lshl_add_u32 v80, v82, 10, v153
	v_lshlrev_b64 v[88:89], 1, v[80:81]
	v_lshl_add_u64 v[84:85], s[56:57], 0, v[88:89]
	global_load_dwordx4 v[220:223], v[232:233], off offset:64
	v_lshl_add_u64 v[88:89], s[10:11], 0, v[88:89]
	v_add_u32_e32 v80, 32, v80
	s_waitcnt vmcnt(13)
	v_mov_b32_e32 v84, v224
	v_mov_b32_e32 v85, v225
	v_mov_b32_e32 v86, v226
	v_mov_b32_e32 v87, v227
	v_lshlrev_b32_e32 v90, 16, v84
	v_and_b32_e32 v91, 0xffff0000, v84
	v_lshlrev_b32_e32 v84, 16, v85
	v_and_b32_e32 v85, 0xffff0000, v85
	v_pk_add_f32 v[78:79], v[78:79], v[84:85]
	v_lshlrev_b32_e32 v84, 16, v86
	v_and_b32_e32 v85, 0xffff0000, v86
	v_pk_add_f32 v[84:85], v[72:73], v[84:85]
	v_lshlrev_b32_e32 v72, 16, v87
	v_and_b32_e32 v73, 0xffff0000, v87
	v_pk_add_f32 v[76:77], v[76:77], v[90:91]
	v_pk_add_f32 v[86:87], v[74:75], v[72:73]
	v_cvt_pk_bf16_f32 v72, v76, v77
	v_cvt_pk_bf16_f32 v73, v78, v79
	v_cvt_pk_bf16_f32 v74, v84, v85
	v_cvt_pk_bf16_f32 v75, v86, v87
	global_store_dwordx4 v[88:89], v[72:75], off
	v_lshlrev_b64 v[88:89], 1, v[80:81]
	v_pk_mul_f32 v[76:77], v[76:77], v[76:77]
	v_pk_mul_f32 v[74:75], v[84:85], v[84:85]
	v_lshl_add_u64 v[84:85], s[56:57], 0, v[88:89]
	v_pk_mul_f32 v[72:73], v[86:87], v[86:87]
	s_mov_b64 s[98:99], 0x8000
	v_lshl_add_u64 v[232:233], v[232:233], 0, s[98:99]
	global_load_dwordx4 v[224:227], v[232:233], off offset:0
	v_lshl_add_u64 v[88:89], s[10:11], 0, v[88:89]
	v_pk_mul_f32 v[78:79], v[78:79], v[78:79]
	v_add_f32_e32 v76, v76, v77
	v_add_f32_e32 v78, v78, v79
	v_add_f32_e32 v76, v76, v78
	v_add_f32_e32 v74, v74, v75
	v_add_f32_e32 v74, v74, v76
	v_add_f32_e32 v72, v72, v73
	v_add_f32_e32 v72, v72, v74
	s_waitcnt vmcnt(14)
	v_mov_b32_e32 v84, v228
	v_mov_b32_e32 v85, v229
	v_mov_b32_e32 v86, v230
	v_mov_b32_e32 v87, v231
	v_lshlrev_b32_e32 v90, 16, v84
	v_and_b32_e32 v91, 0xffff0000, v84
	v_lshlrev_b32_e32 v84, 16, v85
	v_and_b32_e32 v85, 0xffff0000, v85
	v_pk_add_f32 v[70:71], v[70:71], v[84:85]
	v_lshlrev_b32_e32 v84, 16, v86
	v_and_b32_e32 v85, 0xffff0000, v86
	v_pk_add_f32 v[84:85], v[64:65], v[84:85]
	v_lshlrev_b32_e32 v64, 16, v87
	v_and_b32_e32 v65, 0xffff0000, v87
	v_pk_add_f32 v[68:69], v[68:69], v[90:91]
	v_pk_add_f32 v[86:87], v[66:67], v[64:65]
	v_cvt_pk_bf16_f32 v64, v68, v69
	v_cvt_pk_bf16_f32 v65, v70, v71
	v_cvt_pk_bf16_f32 v66, v84, v85
	v_cvt_pk_bf16_f32 v67, v86, v87
	global_store_dwordx4 v[88:89], v[64:67], off
	s_nop 1
	v_pk_mul_f32 v[64:65], v[68:69], v[68:69]
	v_pk_mul_f32 v[66:67], v[70:71], v[70:71]
	v_pk_mul_f32 v[68:69], v[84:85], v[84:85]
	v_add_f32_e32 v66, v66, v67
	v_add_f32_e32 v64, v64, v65
	v_pk_mul_f32 v[70:71], v[86:87], v[86:87]
	v_add_f32_e32 v64, v64, v66
	v_add_f32_e32 v65, v68, v69
	v_add_f32_e32 v64, v65, v64
	v_add_f32_e32 v65, v70, v71
	v_add_f32_e32 v64, v65, v64
	v_add_f32_e32 v64, v72, v64
	ds_bpermute_b32 v65, v152, v64
	s_waitcnt lgkmcnt(0)
	v_add_f32_e32 v64, v64, v65
	ds_bpermute_b32 v65, v145, v64
	s_and_saveexec_b64 s[24:25], vcc
	s_cbranch_execz .LBB0_1137
	v_mov_b32_e32 v83, v81
	v_lshl_add_u64 v[66:67], v[82:83], 2, s[12:13]
	s_waitcnt lgkmcnt(0)
	v_add_f32_e32 v64, v64, v65
	global_atomic_add_f32 v[66:67], v64, off
.LBB0_1137:
	s_or_b64 exec, exec, s[24:25]
	v_add_u32_e32 v64, 0x80, v138
	v_lshl_add_u32 v80, v64, 10, v153
	v_lshlrev_b64 v[70:71], 1, v[80:81]
	v_lshl_add_u64 v[66:67], s[56:57], 0, v[70:71]
	global_load_dwordx4 v[228:231], v[232:233], off offset:64
	v_lshl_add_u64 v[70:71], s[10:11], 0, v[70:71]
	v_add_u32_e32 v80, 32, v80
	s_waitcnt vmcnt(14)
	v_mov_b32_e32 v66, v172
	v_mov_b32_e32 v67, v173
	v_mov_b32_e32 v68, v174
	v_mov_b32_e32 v69, v175
	v_lshlrev_b32_e32 v72, 16, v66
	v_and_b32_e32 v73, 0xffff0000, v66
	v_lshlrev_b32_e32 v66, 16, v67
	v_and_b32_e32 v67, 0xffff0000, v67
	v_pk_add_f32 v[62:63], v[62:63], v[66:67]
	v_lshlrev_b32_e32 v66, 16, v68
	v_and_b32_e32 v67, 0xffff0000, v68
	v_pk_add_f32 v[66:67], v[56:57], v[66:67]
	v_lshlrev_b32_e32 v56, 16, v69
	v_and_b32_e32 v57, 0xffff0000, v69
	v_pk_add_f32 v[60:61], v[60:61], v[72:73]
	v_pk_add_f32 v[68:69], v[58:59], v[56:57]
	v_cvt_pk_bf16_f32 v56, v60, v61
	v_cvt_pk_bf16_f32 v57, v62, v63
	v_cvt_pk_bf16_f32 v58, v66, v67
	v_cvt_pk_bf16_f32 v59, v68, v69
	global_store_dwordx4 v[70:71], v[56:59], off
	v_lshlrev_b64 v[70:71], 1, v[80:81]
	v_pk_mul_f32 v[60:61], v[60:61], v[60:61]
	v_pk_mul_f32 v[58:59], v[66:67], v[66:67]
	v_lshl_add_u64 v[66:67], s[56:57], 0, v[70:71]
	v_pk_mul_f32 v[56:57], v[68:69], v[68:69]
	v_lshl_add_u64 v[70:71], s[10:11], 0, v[70:71]
	v_pk_mul_f32 v[62:63], v[62:63], v[62:63]
	v_add_f32_e32 v60, v60, v61
	v_add_f32_e32 v62, v62, v63
	v_add_f32_e32 v60, v60, v62
	v_add_f32_e32 v58, v58, v59
	v_add_f32_e32 v58, v58, v60
	v_add_f32_e32 v56, v56, v57
	v_add_f32_e32 v56, v56, v58
	s_waitcnt vmcnt(13)
	v_mov_b32_e32 v66, v176
	v_mov_b32_e32 v67, v177
	v_mov_b32_e32 v68, v178
	v_mov_b32_e32 v69, v179
	v_lshlrev_b32_e32 v72, 16, v66
	v_and_b32_e32 v73, 0xffff0000, v66
	v_lshlrev_b32_e32 v66, 16, v67
	v_and_b32_e32 v67, 0xffff0000, v67
	v_pk_add_f32 v[54:55], v[54:55], v[66:67]
	v_lshlrev_b32_e32 v66, 16, v68
	v_and_b32_e32 v67, 0xffff0000, v68
	v_pk_add_f32 v[66:67], v[48:49], v[66:67]
	v_lshlrev_b32_e32 v48, 16, v69
	v_and_b32_e32 v49, 0xffff0000, v69
	v_pk_add_f32 v[52:53], v[52:53], v[72:73]
	v_pk_add_f32 v[68:69], v[50:51], v[48:49]
	v_cvt_pk_bf16_f32 v48, v52, v53
	v_cvt_pk_bf16_f32 v49, v54, v55
	v_cvt_pk_bf16_f32 v50, v66, v67
	v_cvt_pk_bf16_f32 v51, v68, v69
	global_store_dwordx4 v[70:71], v[48:51], off
	s_nop 1
	v_pk_mul_f32 v[48:49], v[52:53], v[52:53]
	v_pk_mul_f32 v[50:51], v[54:55], v[54:55]
	v_pk_mul_f32 v[52:53], v[66:67], v[66:67]
	v_add_f32_e32 v50, v50, v51
	v_add_f32_e32 v48, v48, v49
	v_pk_mul_f32 v[54:55], v[68:69], v[68:69]
	v_add_f32_e32 v48, v48, v50
	v_add_f32_e32 v49, v52, v53
	v_add_f32_e32 v48, v49, v48
	v_add_f32_e32 v49, v54, v55
	v_add_f32_e32 v48, v49, v48
	v_add_f32_e32 v48, v56, v48
	ds_bpermute_b32 v49, v152, v48
	s_waitcnt lgkmcnt(0)
	v_add_f32_e32 v48, v48, v49
	ds_bpermute_b32 v49, v145, v48
	s_and_saveexec_b64 s[24:25], vcc
	s_cbranch_execz .LBB0_1139
	v_mov_b32_e32 v65, v81
	v_lshl_add_u64 v[50:51], v[64:65], 2, s[12:13]
	s_waitcnt lgkmcnt(0)
	v_add_f32_e32 v48, v48, v49
	global_atomic_add_f32 v[50:51], v48, off
; __device__ __forceinline__ unsigned pk2(float lo, float hi) { f32x2_t v = {lo, hi}; bf16x2_t b = __builtin_convertvector(v, bf16x2_t); return __builtin_bit_cast(unsigned, b); }
; __device__ __forceinline__ float bflo(unsigned w) { return __uint_as_float(w << 16); }
; __device__ __forceinline__ float bfhi(unsigned w) { return __uint_as_float(w & 0xffff0000u); }
;     __device__ __forceinline__ void operator()(const f32x4 (&acc)[2][2][4][2], const pg8::Unit& u, int wr, int wc, int fr_, int fq_) const {
;     ...
;             for (int m = 0; m < 4; ++m) { const unsigned row = (unsigned)(u.pm * 256 + 128 * ai + 64 * wr + 16 * m + fr); float ss = 0.f;
; #pragma unroll
;                 for (int bj = 0; bj < 2; ++bj) { const unsigned o = row * 1024u + (unsigned)(u.pn * 256 + 64 * wc + 32 * bj + 8 * fq);
;                     const u32x4 rb = *(const u32x4*)(resb + o); const f32x4 a0 = acc[ai][bj][m][0], a1 = acc[ai][bj][m][1];
;                     const float y0 = bflo(rb.x) + a0[0], y1 = bfhi(rb.x) + a0[1], y2 = bflo(rb.y) + a0[2], y3 = bfhi(rb.y) + a0[3];
;                     const float y4 = bflo(rb.z) + a1[0], y5 = bfhi(rb.z) + a1[1], y6 = bflo(rb.w) + a1[2], y7 = bfhi(rb.w) + a1[3];
;                     u32x4 w; w.x = pk2(y0, y1); w.y = pk2(y2, y3); w.z = pk2(y4, y5); w.w = pk2(y6, y7);
;                     *(u32x4*)(xb + o) = w;
;                     ss += (y0 * y0 + y1 * y1) + (y2 * y2 + y3 * y3) + (y4 * y4 + y5 * y5) + (y6 * y6 + y7 * y7); }
;                 ss += __shfl_xor(ss, 16); ss += __shfl_xor(ss, 32);
;                 if (fq == 0) atomicAdd(ssq + row, ss);
.LBB0_1139:
	s_or_b64 exec, exec, s[24:25]
	v_add_u32_e32 v48, 0x90, v138
	v_lshl_add_u32 v80, v48, 10, v153
	v_lshlrev_b64 v[54:55], 1, v[80:81]
	v_lshl_add_u64 v[50:51], s[56:57], 0, v[54:55]
	v_lshl_add_u64 v[54:55], s[10:11], 0, v[54:55]
	v_add_u32_e32 v80, 32, v80
	s_waitcnt vmcnt(12)
	v_mov_b32_e32 v50, v180
	v_mov_b32_e32 v51, v181
	v_mov_b32_e32 v52, v182
	v_mov_b32_e32 v53, v183
	v_lshlrev_b32_e32 v56, 16, v50
	v_and_b32_e32 v57, 0xffff0000, v50
	v_lshlrev_b32_e32 v50, 16, v51
	v_and_b32_e32 v51, 0xffff0000, v51
	v_pk_add_f32 v[46:47], v[46:47], v[50:51]
	v_lshlrev_b32_e32 v50, 16, v52
	v_and_b32_e32 v51, 0xffff0000, v52
	v_pk_add_f32 v[50:51], v[40:41], v[50:51]
	v_lshlrev_b32_e32 v40, 16, v53
	v_and_b32_e32 v41, 0xffff0000, v53
	v_pk_add_f32 v[44:45], v[44:45], v[56:57]
	v_pk_add_f32 v[52:53], v[42:43], v[40:41]
	v_cvt_pk_bf16_f32 v40, v44, v45
	v_cvt_pk_bf16_f32 v41, v46, v47
	v_cvt_pk_bf16_f32 v42, v50, v51
	v_cvt_pk_bf16_f32 v43, v52, v53
	global_store_dwordx4 v[54:55], v[40:43], off
	v_lshlrev_b64 v[54:55], 1, v[80:81]
	v_pk_mul_f32 v[44:45], v[44:45], v[44:45]
	v_pk_mul_f32 v[42:43], v[50:51], v[50:51]
	v_lshl_add_u64 v[50:51], s[56:57], 0, v[54:55]
	v_pk_mul_f32 v[40:41], v[52:53], v[52:53]
	v_lshl_add_u64 v[54:55], s[10:11], 0, v[54:55]
	v_pk_mul_f32 v[46:47], v[46:47], v[46:47]
	v_add_f32_e32 v44, v44, v45
	v_add_f32_e32 v46, v46, v47
	v_add_f32_e32 v44, v44, v46
	v_add_f32_e32 v42, v42, v43
	v_add_f32_e32 v42, v42, v44
	v_add_f32_e32 v40, v40, v41
	v_add_f32_e32 v40, v40, v42
	s_waitcnt vmcnt(11)
	v_mov_b32_e32 v50, v212
	v_mov_b32_e32 v51, v213
	v_mov_b32_e32 v52, v214
	v_mov_b32_e32 v53, v215
	v_lshlrev_b32_e32 v56, 16, v50
	v_and_b32_e32 v57, 0xffff0000, v50
	v_lshlrev_b32_e32 v50, 16, v51
	v_and_b32_e32 v51, 0xffff0000, v51
	v_pk_add_f32 v[38:39], v[38:39], v[50:51]
	v_lshlrev_b32_e32 v50, 16, v52
	v_and_b32_e32 v51, 0xffff0000, v52
	v_pk_add_f32 v[50:51], v[32:33], v[50:51]
	v_lshlrev_b32_e32 v32, 16, v53
	v_and_b32_e32 v33, 0xffff0000, v53
	v_pk_add_f32 v[36:37], v[36:37], v[56:57]
	v_pk_add_f32 v[52:53], v[34:35], v[32:33]
	v_cvt_pk_bf16_f32 v32, v36, v37
	v_cvt_pk_bf16_f32 v33, v38, v39
	v_cvt_pk_bf16_f32 v34, v50, v51
	v_cvt_pk_bf16_f32 v35, v52, v53
	global_store_dwordx4 v[54:55], v[32:35], off
	s_nop 1
	v_pk_mul_f32 v[32:33], v[36:37], v[36:37]
	v_pk_mul_f32 v[34:35], v[38:39], v[38:39]
	v_pk_mul_f32 v[36:37], v[50:51], v[50:51]
	v_add_f32_e32 v34, v34, v35
	v_add_f32_e32 v32, v32, v33
	v_pk_mul_f32 v[38:39], v[52:53], v[52:53]
	v_add_f32_e32 v32, v32, v34
	v_add_f32_e32 v33, v36, v37
	v_add_f32_e32 v32, v33, v32
	v_add_f32_e32 v33, v38, v39
	v_add_f32_e32 v32, v33, v32
	v_add_f32_e32 v32, v40, v32
	ds_bpermute_b32 v33, v152, v32
	s_waitcnt lgkmcnt(0)
	v_add_f32_e32 v32, v32, v33
	ds_bpermute_b32 v33, v145, v32
	s_and_saveexec_b64 s[24:25], vcc
	s_cbranch_execz .LBB0_1141
	v_mov_b32_e32 v49, v81
	v_lshl_add_u64 v[34:35], v[48:49], 2, s[12:13]
	s_waitcnt lgkmcnt(0)
	v_add_f32_e32 v32, v32, v33
	global_atomic_add_f32 v[34:35], v32, off
; __device__ __forceinline__ unsigned pk2(float lo, float hi) { f32x2_t v = {lo, hi}; bf16x2_t b = __builtin_convertvector(v, bf16x2_t); return __builtin_bit_cast(unsigned, b); }
; __device__ __forceinline__ float bflo(unsigned w) { return __uint_as_float(w << 16); }
; __device__ __forceinline__ float bfhi(unsigned w) { return __uint_as_float(w & 0xffff0000u); }
;     __device__ __forceinline__ void operator()(const f32x4 (&acc)[2][2][4][2], const pg8::Unit& u, int wr, int wc, int fr_, int fq_) const {
;     ...
;             for (int m = 0; m < 4; ++m) { const unsigned row = (unsigned)(u.pm * 256 + 128 * ai + 64 * wr + 16 * m + fr); float ss = 0.f;
; #pragma unroll
;                 for (int bj = 0; bj < 2; ++bj) { const unsigned o = row * 1024u + (unsigned)(u.pn * 256 + 64 * wc + 32 * bj + 8 * fq);
;                     const u32x4 rb = *(const u32x4*)(resb + o); const f32x4 a0 = acc[ai][bj][m][0], a1 = acc[ai][bj][m][1];
;                     const float y0 = bflo(rb.x) + a0[0], y1 = bfhi(rb.x) + a0[1], y2 = bflo(rb.y) + a0[2], y3 = bfhi(rb.y) + a0[3];
;                     const float y4 = bflo(rb.z) + a1[0], y5 = bfhi(rb.z) + a1[1], y6 = bflo(rb.w) + a1[2], y7 = bfhi(rb.w) + a1[3];
;                     u32x4 w; w.x = pk2(y0, y1); w.y = pk2(y2, y3); w.z = pk2(y4, y5); w.w = pk2(y6, y7);
;                     *(u32x4*)(xb + o) = w;
;                     ss += (y0 * y0 + y1 * y1) + (y2 * y2 + y3 * y3) + (y4 * y4 + y5 * y5) + (y6 * y6 + y7 * y7); }
;                 ss += __shfl_xor(ss, 16); ss += __shfl_xor(ss, 32);
;                 if (fq == 0) atomicAdd(ssq + row, ss);
.LBB0_1141:
	s_or_b64 exec, exec, s[24:25]
	v_add_u32_e32 v32, 0xa0, v138
	v_lshl_add_u32 v80, v32, 10, v153
	v_lshlrev_b64 v[38:39], 1, v[80:81]
	v_lshl_add_u64 v[34:35], s[56:57], 0, v[38:39]
	v_lshl_add_u64 v[38:39], s[10:11], 0, v[38:39]
	v_add_u32_e32 v80, 32, v80
	s_waitcnt vmcnt(10)
	v_mov_b32_e32 v34, v216
	v_mov_b32_e32 v35, v217
	v_mov_b32_e32 v36, v218
	v_mov_b32_e32 v37, v219
	v_lshlrev_b32_e32 v40, 16, v34
	v_and_b32_e32 v41, 0xffff0000, v34
	v_lshlrev_b32_e32 v34, 16, v35
	v_and_b32_e32 v35, 0xffff0000, v35
	v_pk_add_f32 v[30:31], v[30:31], v[34:35]
	v_lshlrev_b32_e32 v34, 16, v36
	v_and_b32_e32 v35, 0xffff0000, v36
	v_pk_add_f32 v[34:35], v[24:25], v[34:35]
	v_lshlrev_b32_e32 v24, 16, v37
	v_and_b32_e32 v25, 0xffff0000, v37
	v_pk_add_f32 v[28:29], v[28:29], v[40:41]
	v_pk_add_f32 v[36:37], v[26:27], v[24:25]
	v_cvt_pk_bf16_f32 v24, v28, v29
	v_cvt_pk_bf16_f32 v25, v30, v31
	v_cvt_pk_bf16_f32 v26, v34, v35
	v_cvt_pk_bf16_f32 v27, v36, v37
	global_store_dwordx4 v[38:39], v[24:27], off
	v_lshlrev_b64 v[38:39], 1, v[80:81]
	v_pk_mul_f32 v[28:29], v[28:29], v[28:29]
	v_pk_mul_f32 v[26:27], v[34:35], v[34:35]
	v_lshl_add_u64 v[34:35], s[56:57], 0, v[38:39]
	v_pk_mul_f32 v[24:25], v[36:37], v[36:37]
	v_lshl_add_u64 v[38:39], s[10:11], 0, v[38:39]
	v_pk_mul_f32 v[30:31], v[30:31], v[30:31]
	v_add_f32_e32 v28, v28, v29
	v_add_f32_e32 v30, v30, v31
	v_add_f32_e32 v28, v28, v30
	v_add_f32_e32 v26, v26, v27
	v_add_f32_e32 v26, v26, v28
	v_add_f32_e32 v24, v24, v25
	v_add_f32_e32 v24, v24, v26
	s_waitcnt vmcnt(9)
	v_mov_b32_e32 v34, v220
	v_mov_b32_e32 v35, v221
	v_mov_b32_e32 v36, v222
	v_mov_b32_e32 v37, v223
	v_lshlrev_b32_e32 v40, 16, v34
	v_and_b32_e32 v41, 0xffff0000, v34
	v_lshlrev_b32_e32 v34, 16, v35
	v_and_b32_e32 v35, 0xffff0000, v35
	v_pk_add_f32 v[22:23], v[22:23], v[34:35]
	v_lshlrev_b32_e32 v34, 16, v36
	v_and_b32_e32 v35, 0xffff0000, v36
	v_pk_add_f32 v[34:35], v[16:17], v[34:35]
	v_lshlrev_b32_e32 v16, 16, v37
	v_and_b32_e32 v17, 0xffff0000, v37
	v_pk_add_f32 v[20:21], v[20:21], v[40:41]
	v_pk_add_f32 v[36:37], v[18:19], v[16:17]
	v_cvt_pk_bf16_f32 v16, v20, v21
	v_cvt_pk_bf16_f32 v17, v22, v23
	v_cvt_pk_bf16_f32 v18, v34, v35
	v_cvt_pk_bf16_f32 v19, v36, v37
	global_store_dwordx4 v[38:39], v[16:19], off
	s_nop 1
	v_pk_mul_f32 v[16:17], v[20:21], v[20:21]
	v_pk_mul_f32 v[18:19], v[22:23], v[22:23]
	v_pk_mul_f32 v[20:21], v[34:35], v[34:35]
	v_add_f32_e32 v18, v18, v19
	v_add_f32_e32 v16, v16, v17
	v_pk_mul_f32 v[22:23], v[36:37], v[36:37]
	v_add_f32_e32 v16, v16, v18
	v_add_f32_e32 v17, v20, v21
	v_add_f32_e32 v16, v17, v16
	v_add_f32_e32 v17, v22, v23
	v_add_f32_e32 v16, v17, v16
	v_add_f32_e32 v16, v24, v16
	ds_bpermute_b32 v17, v152, v16
	s_waitcnt lgkmcnt(0)
	v_add_f32_e32 v16, v16, v17
	ds_bpermute_b32 v17, v145, v16
	s_and_saveexec_b64 s[24:25], vcc
	s_cbranch_execz .LBB0_1143
	v_mov_b32_e32 v33, v81
	v_lshl_add_u64 v[18:19], v[32:33], 2, s[12:13]
	s_waitcnt lgkmcnt(0)
	v_add_f32_e32 v16, v16, v17
	global_atomic_add_f32 v[18:19], v16, off
.LBB0_1143:
	s_or_b64 exec, exec, s[24:25]
	v_add_u32_e32 v16, 0xb0, v138
	v_lshl_add_u32 v80, v16, 10, v153
	v_lshlrev_b64 v[22:23], 1, v[80:81]
	v_lshl_add_u64 v[18:19], s[56:57], 0, v[22:23]
	v_lshl_add_u64 v[22:23], s[10:11], 0, v[22:23]
	v_add_u32_e32 v80, 32, v80
	s_waitcnt vmcnt(8)
	v_mov_b32_e32 v18, v224
	v_mov_b32_e32 v19, v225
	v_mov_b32_e32 v20, v226
	v_mov_b32_e32 v21, v227
	v_lshlrev_b32_e32 v24, 16, v18
	v_and_b32_e32 v25, 0xffff0000, v18
	v_lshlrev_b32_e32 v18, 16, v19
	v_and_b32_e32 v19, 0xffff0000, v19
	v_pk_add_f32 v[14:15], v[14:15], v[18:19]
	v_lshlrev_b32_e32 v18, 16, v20
	v_and_b32_e32 v19, 0xffff0000, v20
	v_pk_add_f32 v[18:19], v[8:9], v[18:19]
	v_lshlrev_b32_e32 v8, 16, v21
	v_and_b32_e32 v9, 0xffff0000, v21
	v_pk_add_f32 v[12:13], v[12:13], v[24:25]
	v_pk_add_f32 v[20:21], v[10:11], v[8:9]
	v_cvt_pk_bf16_f32 v8, v12, v13
	v_cvt_pk_bf16_f32 v9, v14, v15
	v_cvt_pk_bf16_f32 v10, v18, v19
	v_cvt_pk_bf16_f32 v11, v20, v21
	global_store_dwordx4 v[22:23], v[8:11], off
	v_lshlrev_b64 v[22:23], 1, v[80:81]
	v_pk_mul_f32 v[12:13], v[12:13], v[12:13]
	v_pk_mul_f32 v[10:11], v[18:19], v[18:19]
	v_lshl_add_u64 v[18:19], s[56:57], 0, v[22:23]
	v_pk_mul_f32 v[8:9], v[20:21], v[20:21]
	v_lshl_add_u64 v[22:23], s[10:11], 0, v[22:23]
	v_pk_mul_f32 v[14:15], v[14:15], v[14:15]
	v_add_f32_e32 v12, v12, v13
	v_add_f32_e32 v14, v14, v15
	v_add_f32_e32 v12, v12, v14
	v_add_f32_e32 v10, v10, v11
	v_add_f32_e32 v10, v10, v12
	v_add_f32_e32 v8, v8, v9
	v_add_f32_e32 v8, v8, v10
	s_waitcnt vmcnt(7)
	v_mov_b32_e32 v18, v228
	v_mov_b32_e32 v19, v229
	v_mov_b32_e32 v20, v230
	v_mov_b32_e32 v21, v231
	v_lshlrev_b32_e32 v24, 16, v18
	v_and_b32_e32 v25, 0xffff0000, v18
	v_lshlrev_b32_e32 v18, 16, v19
	v_and_b32_e32 v19, 0xffff0000, v19
	v_pk_add_f32 v[6:7], v[6:7], v[18:19]
	v_lshlrev_b32_e32 v18, 16, v20
	v_and_b32_e32 v19, 0xffff0000, v20
	v_pk_add_f32 v[18:19], v[0:1], v[18:19]
	v_lshlrev_b32_e32 v0, 16, v21
	v_and_b32_e32 v1, 0xffff0000, v21
	v_pk_add_f32 v[4:5], v[4:5], v[24:25]
	v_pk_add_f32 v[20:21], v[2:3], v[0:1]
	v_cvt_pk_bf16_f32 v0, v4, v5
	v_cvt_pk_bf16_f32 v1, v6, v7
	v_cvt_pk_bf16_f32 v2, v18, v19
	v_cvt_pk_bf16_f32 v3, v20, v21
	global_store_dwordx4 v[22:23], v[0:3], off
	s_nop 1
	v_pk_mul_f32 v[0:1], v[4:5], v[4:5]
	v_pk_mul_f32 v[2:3], v[6:7], v[6:7]
	v_pk_mul_f32 v[4:5], v[18:19], v[18:19]
	v_add_f32_e32 v2, v2, v3
	v_add_f32_e32 v0, v0, v1
	v_pk_mul_f32 v[6:7], v[20:21], v[20:21]
	v_add_f32_e32 v0, v0, v2
	v_add_f32_e32 v1, v4, v5
	v_add_f32_e32 v0, v1, v0
	v_add_f32_e32 v1, v6, v7
	v_add_f32_e32 v0, v1, v0
	v_add_f32_e32 v0, v8, v0
	ds_bpermute_b32 v1, v152, v0
	s_waitcnt lgkmcnt(0)
	v_add_f32_e32 v0, v0, v1
	ds_bpermute_b32 v1, v145, v0
	s_and_saveexec_b64 s[24:25], vcc
	s_cbranch_execz .LBB0_1145
	v_mov_b32_e32 v17, v81
	v_lshl_add_u64 v[2:3], v[16:17], 2, s[12:13]
	s_waitcnt lgkmcnt(0)
	v_add_f32_e32 v0, v0, v1
	global_atomic_add_f32 v[2:3], v0, off

;     __host__ __device__ bool next(int i, Unit& u) const {
;         const long L = (long)i * G + c; if (L >= nwg) return false;
;         int wgid = (int)L; { const int q = nwg / NXCD, r = nwg % NXCD, xcd = wgid % NXCD, off = wgid / NXCD; wgid = (xcd < r ? xcd * (q + 1) : r * (q + 1) + (xcd - r) * q) + off; }
;         const int nig = WGM * nN, gid = wgid / nig, fm = gid * WGM, gsz = (nM - fm) < WGM ? (nM - fm) : WGM;
;         u.pm = fm + ((wgid % nig) % gsz); u.pn = (wgid % nig) / gsz; return true;
; template <class Epi, class Sched, bool ALIGN_EPI = false, bool SP2 = false>
; __device__ __forceinline__ void gemm_phase(PG8_LAS unsigned char* lds, const Gemm g, const Sched& S, const Epi& E, int tid_in) {
;     ...
;         const bool has_next = S.next(ui + 1, nxt);
;         const char* nA = has_next ? (const char*)g.A + (size_t)nxt.pm * tstepA : cA; const char* nB = has_next ? (const char*)g.Bt + (size_t)nxt.pn * tstepB : cB;
.LBB0_1163:
	s_nop 0
	s_nop 0
	s_add_i32 s52, s52, 1
	s_mul_i32 s4, s52, s50
	s_mul_hi_u32 s5, s52, s36
	s_add_i32 s5, s5, s4
	s_mul_i32 s4, s52, s36
	s_add_u32 s20, s4, s37
	s_addc_u32 s21, s5, s51
	v_cmp_gt_i64_e32 vcc, s[20:21], v[150:151]
	v_cmp_lt_i64_e64 s[4:5], s[20:21], v[148:149]
	s_cbranch_vccnz .LBB0_1169
	s_ashr_i32 s16, s20, 31
	s_lshr_b32 s16, s16, 29
	s_add_i32 s18, s20, s16
	s_and_b32 s16, s18, -8
	s_sub_i32 s19, s20, s16
	s_cmp_gt_i32 s19, -1
	s_mov_b64 s[16:17], -1
	s_cbranch_scc0 .LBB0_1166
	s_lshl_b32 s20, s19, 6
	s_mov_b64 s[16:17], 0

; __device__ __forceinline__ unsigned pk2(float lo, float hi) { f32x2_t v = {lo, hi}; bf16x2_t b = __builtin_convertvector(v, bf16x2_t); return __builtin_bit_cast(unsigned, b); }
;     __device__ __forceinline__ void operator()(const f32x4 (&acc)[2][2][4][2], const pg8::Unit& u, int wr, int wc, int fr_, int fq_) const {
;     ...
;             for (int m = 0; m < 4; ++m) { const unsigned row = (unsigned)(u.pm * 256 + 128 * ai + 64 * wr + 16 * m + fr); float ss = 0.f;
; #pragma unroll
;                 for (int bj = 0; bj < 2; ++bj) { const unsigned o = row * 1024u + (unsigned)(u.pn * 256 + 64 * wc + 32 * bj + 8 * fq);
;                     const f32x4 r0 = *(const f32x4*)(res + o), r1 = *(const f32x4*)(res + o + 4);
;                     const f32x4 x0 = r0 + acc[ai][bj][m][0], x1 = r1 + acc[ai][bj][m][1];
;                     u32x4 w; w.x = pk2(x0[0], x0[1]); w.y = pk2(x0[2], x0[3]); w.z = pk2(x1[0], x1[1]); w.w = pk2(x1[2], x1[3]);
;                     *(u32x4*)(xb + o) = w;
;                     ss += (x0[0] * x0[0] + x0[1] * x0[1]) + (x0[2] * x0[2] + x0[3] * x0[3]) + (x1[0] * x1[0] + x1[1] * x1[1]) + (x1[2] * x1[2] + x1[3] * x1[3]); }
;                 ss += __shfl_xor(ss, 16); ss += __shfl_xor(ss, 32);
;                 if (fq == 0) atomicAdd(ssq + row, ss);
.LBB0_1173:
	v_mov_b32_e32 v80, v141
	v_mov_b32_e32 v139, v142
	s_lshl_b32 s17, s26, 8
	s_add_i32 s17, s17, s46
	v_and_b32_e32 v144, 64, v195
	v_add_u32_e32 v138, s17, v80
	v_xor_b32_e32 v80, 16, v195
	v_add_u32_e32 v144, 64, v144
	v_cmp_lt_i32_e32 vcc, v80, v144
	s_lshl_b32 s17, s24, 8
	s_or_b32 s17, s17, s49
	v_cndmask_b32_e32 v80, v195, v80, vcc
	v_lshlrev_b32_e32 v145, 2, v80
	v_xor_b32_e32 v80, 32, v195
	v_cmp_lt_i32_e32 vcc, v80, v144
	v_lshl_add_u32 v152, v139, 3, s17
	s_nop 0
	v_cndmask_b32_e32 v80, v195, v80, vcc
	v_lshlrev_b32_e32 v144, 2, v80
	v_lshl_add_u32 v80, v138, 10, v152
	v_lshl_add_u64 v[158:159], v[80:81], 2, s[8:9]
	v_mov_b32_e32 v232, v158
	v_mov_b32_e32 v233, v159
	global_load_dwordx4 v[172:175], v[232:233], off offset:16
	global_load_dwordx4 v[176:179], v[232:233], off offset:0
	global_load_dwordx4 v[180:183], v[232:233], off offset:144
	global_load_dwordx4 v[212:215], v[232:233], off offset:128
	s_mov_b64 s[98:99], 0x10000
	v_lshl_add_u64 v[232:233], v[232:233], 0, s[98:99]
	global_load_dwordx4 v[216:219], v[232:233], off offset:16
	global_load_dwordx4 v[220:223], v[232:233], off offset:0
	global_load_dwordx4 v[224:227], v[232:233], off offset:144
	global_load_dwordx4 v[228:231], v[232:233], off offset:128
	s_nop 0
	v_cmp_eq_u32_e32 vcc, 0, v139
	s_waitcnt vmcnt(6)
	v_mov_b32_e32 v154, v172
	v_mov_b32_e32 v155, v173
	v_mov_b32_e32 v156, v174
	v_mov_b32_e32 v157, v175
	v_mov_b32_e32 v158, v176
	v_mov_b32_e32 v159, v177
	v_mov_b32_e32 v160, v178
	v_mov_b32_e32 v161, v179
	v_pk_add_f32 v[156:157], v[124:125], v[156:157]
	v_pk_add_f32 v[128:129], v[128:129], v[160:161]
	v_pk_add_f32 v[126:127], v[126:127], v[158:159]
	v_pk_add_f32 v[154:155], v[122:123], v[154:155]
	v_cvt_pk_bf16_f32 v122, v126, v127
	v_cvt_pk_bf16_f32 v123, v128, v129
	v_cvt_pk_bf16_f32 v124, v154, v155
	v_cvt_pk_bf16_f32 v125, v156, v157
	v_lshl_add_u64 v[158:159], v[80:81], 1, s[12:13]
	global_store_dwordx4 v[158:159], v[122:125], off
	v_add_u32_e32 v80, 32, v80
	s_nop 0
	v_mul_f32_e32 v122, v127, v127
	v_mul_f32_e32 v123, v129, v129
	v_fmac_f32_e32 v122, v126, v126
	v_fmac_f32_e32 v123, v128, v128
	v_add_f32_e32 v122, v122, v123
	v_mul_f32_e32 v123, v155, v155
	v_fmac_f32_e32 v123, v154, v154
	v_add_f32_e32 v122, v122, v123
	v_mul_f32_e32 v123, v157, v157
	v_fmac_f32_e32 v123, v156, v156
	v_lshl_add_u64 v[126:127], v[80:81], 2, s[8:9]
	v_add_f32_e32 v139, v123, v122
	s_mov_b64 s[98:99], 0x10000
	v_lshl_add_u64 v[232:233], v[232:233], 0, s[98:99]
	global_load_dwordx4 v[172:175], v[232:233], off offset:16
	global_load_dwordx4 v[176:179], v[232:233], off offset:0
	s_nop 0
	s_waitcnt vmcnt(7)
	v_mov_b32_e32 v122, v180
	v_mov_b32_e32 v123, v181
	v_mov_b32_e32 v124, v182
	v_mov_b32_e32 v125, v183
	v_mov_b32_e32 v126, v212
	v_mov_b32_e32 v127, v213
	v_mov_b32_e32 v128, v214
	v_mov_b32_e32 v129, v215
	v_pk_add_f32 v[124:125], v[116:117], v[124:125]
	v_pk_add_f32 v[120:121], v[120:121], v[128:129]
	v_pk_add_f32 v[118:119], v[118:119], v[126:127]
	v_pk_add_f32 v[122:123], v[114:115], v[122:123]
	v_cvt_pk_bf16_f32 v114, v118, v119
	v_cvt_pk_bf16_f32 v115, v120, v121
	v_cvt_pk_bf16_f32 v116, v122, v123
	v_cvt_pk_bf16_f32 v117, v124, v125
	v_lshl_add_u64 v[126:127], v[80:81], 1, s[12:13]
	global_store_dwordx4 v[126:127], v[114:117], off
	v_mul_f32_e32 v80, v119, v119
	v_fmac_f32_e32 v80, v118, v118
	v_mul_f32_e32 v114, v121, v121
	v_fmac_f32_e32 v114, v120, v120
	v_add_f32_e32 v80, v80, v114
	v_mul_f32_e32 v114, v123, v123
	v_fmac_f32_e32 v114, v122, v122
	v_add_f32_e32 v80, v80, v114
	v_mul_f32_e32 v114, v125, v125
	v_fmac_f32_e32 v114, v124, v124
	v_add_f32_e32 v80, v114, v80
	v_add_f32_e32 v80, v139, v80
	ds_bpermute_b32 v114, v145, v80
	s_waitcnt lgkmcnt(0)
	v_add_f32_e32 v80, v80, v114
	ds_bpermute_b32 v114, v144, v80
	s_and_saveexec_b64 s[24:25], vcc
	v_readlane_b32 s56, v255, 10
	v_readlane_b32 s57, v255, 11
	v_readlane_b32 s58, v255, 12
	v_readlane_b32 s59, v255, 13
	s_cbranch_execz .LBB0_1175
	v_mov_b32_e32 v139, v81
	v_lshl_add_u64 v[116:117], v[138:139], 2, s[6:7]
	s_waitcnt lgkmcnt(0)
	v_add_f32_e32 v80, v80, v114
	global_atomic_add_f32 v[116:117], v80, off
.LBB0_1175:
	s_or_b64 exec, exec, s[24:25]
	s_waitcnt lgkmcnt(0)
	v_add_u32_e32 v114, 16, v138
	v_lshl_add_u32 v80, v114, 10, v152
	v_lshl_add_u64 v[120:121], v[80:81], 2, s[8:9]
	global_load_dwordx4 v[180:183], v[232:233], off offset:144
	global_load_dwordx4 v[212:215], v[232:233], off offset:128
	s_nop 0
	s_waitcnt vmcnt(8)
	v_mov_b32_e32 v116, v216
	v_mov_b32_e32 v117, v217
	v_mov_b32_e32 v118, v218
	v_mov_b32_e32 v119, v219
	v_mov_b32_e32 v120, v220
	v_mov_b32_e32 v121, v221
	v_mov_b32_e32 v122, v222
	v_mov_b32_e32 v123, v223
	v_pk_add_f32 v[118:119], v[108:109], v[118:119]
	v_pk_add_f32 v[112:113], v[112:113], v[122:123]
	v_pk_add_f32 v[110:111], v[110:111], v[120:121]
	v_pk_add_f32 v[116:117], v[106:107], v[116:117]
	v_cvt_pk_bf16_f32 v106, v110, v111
	v_cvt_pk_bf16_f32 v107, v112, v113
	v_cvt_pk_bf16_f32 v108, v116, v117
	v_cvt_pk_bf16_f32 v109, v118, v119
	v_lshl_add_u64 v[120:121], v[80:81], 1, s[12:13]
	global_store_dwordx4 v[120:121], v[106:109], off
	v_add_u32_e32 v80, 32, v80
	s_nop 0
	v_mul_f32_e32 v106, v111, v111
	v_mul_f32_e32 v107, v113, v113
	v_fmac_f32_e32 v106, v110, v110
	v_fmac_f32_e32 v107, v112, v112
	v_add_f32_e32 v106, v106, v107
	v_mul_f32_e32 v107, v117, v117
	v_fmac_f32_e32 v107, v116, v116
	v_add_f32_e32 v106, v106, v107
	v_mul_f32_e32 v107, v119, v119
	v_fmac_f32_e32 v107, v118, v118
	v_lshl_add_u64 v[110:111], v[80:81], 2, s[8:9]
	v_add_f32_e32 v115, v107, v106
	s_mov_b64 s[98:99], 0x10000
	v_lshl_add_u64 v[232:233], v[232:233], 0, s[98:99]
	global_load_dwordx4 v[216:219], v[232:233], off offset:16
	global_load_dwordx4 v[220:223], v[232:233], off offset:0
	s_nop 0
	s_waitcnt vmcnt(9)
	v_mov_b32_e32 v106, v224
	v_mov_b32_e32 v107, v225
	v_mov_b32_e32 v108, v226
	v_mov_b32_e32 v109, v227
	v_mov_b32_e32 v110, v228
	v_mov_b32_e32 v111, v229
	v_mov_b32_e32 v112, v230
	v_mov_b32_e32 v113, v231
	v_pk_add_f32 v[108:109], v[100:101], v[108:109]
	v_pk_add_f32 v[104:105], v[104:105], v[112:113]
	v_pk_add_f32 v[102:103], v[102:103], v[110:111]
	v_pk_add_f32 v[106:107], v[98:99], v[106:107]
	v_cvt_pk_bf16_f32 v98, v102, v103
	v_cvt_pk_bf16_f32 v99, v104, v105
	v_cvt_pk_bf16_f32 v100, v106, v107
	v_cvt_pk_bf16_f32 v101, v108, v109
	v_lshl_add_u64 v[110:111], v[80:81], 1, s[12:13]
	global_store_dwordx4 v[110:111], v[98:101], off
	v_mul_f32_e32 v80, v103, v103
	v_fmac_f32_e32 v80, v102, v102
	v_mul_f32_e32 v98, v105, v105
	v_fmac_f32_e32 v98, v104, v104
	v_add_f32_e32 v80, v80, v98
	v_mul_f32_e32 v98, v107, v107
	v_fmac_f32_e32 v98, v106, v106
	v_add_f32_e32 v80, v80, v98
	v_mul_f32_e32 v98, v109, v109
	v_fmac_f32_e32 v98, v108, v108
	v_add_f32_e32 v80, v98, v80
	v_add_f32_e32 v80, v115, v80
	ds_bpermute_b32 v98, v145, v80
	s_waitcnt lgkmcnt(0)
	v_add_f32_e32 v80, v80, v98
	ds_bpermute_b32 v98, v144, v80
	s_and_saveexec_b64 s[24:25], vcc
	s_cbranch_execz .LBB0_1177
; __device__ __forceinline__ unsigned pk2(float lo, float hi) { f32x2_t v = {lo, hi}; bf16x2_t b = __builtin_convertvector(v, bf16x2_t); return __builtin_bit_cast(unsigned, b); }
;     __device__ __forceinline__ void operator()(const f32x4 (&acc)[2][2][4][2], const pg8::Unit& u, int wr, int wc, int fr_, int fq_) const {
;     ...
;             for (int m = 0; m < 4; ++m) { const unsigned row = (unsigned)(u.pm * 256 + 128 * ai + 64 * wr + 16 * m + fr); float ss = 0.f;
; #pragma unroll
;                 for (int bj = 0; bj < 2; ++bj) { const unsigned o = row * 1024u + (unsigned)(u.pn * 256 + 64 * wc + 32 * bj + 8 * fq);
;                     const f32x4 r0 = *(const f32x4*)(res + o), r1 = *(const f32x4*)(res + o + 4);
;                     const f32x4 x0 = r0 + acc[ai][bj][m][0], x1 = r1 + acc[ai][bj][m][1];
;                     u32x4 w; w.x = pk2(x0[0], x0[1]); w.y = pk2(x0[2], x0[3]); w.z = pk2(x1[0], x1[1]); w.w = pk2(x1[2], x1[3]);
;                     *(u32x4*)(xb + o) = w;
;                     ss += (x0[0] * x0[0] + x0[1] * x0[1]) + (x0[2] * x0[2] + x0[3] * x0[3]) + (x1[0] * x1[0] + x1[1] * x1[1]) + (x1[2] * x1[2] + x1[3] * x1[3]); }
;                 ss += __shfl_xor(ss, 16); ss += __shfl_xor(ss, 32);
;                 if (fq == 0) atomicAdd(ssq + row, ss);
	v_mov_b32_e32 v115, v81
	v_lshl_add_u64 v[100:101], v[114:115], 2, s[6:7]
	s_waitcnt lgkmcnt(0)
	v_add_f32_e32 v80, v80, v98
	global_atomic_add_f32 v[100:101], v80, off
.LBB0_1177:
	s_or_b64 exec, exec, s[24:25]
	s_waitcnt lgkmcnt(0)
	v_add_u32_e32 v98, 32, v138
	v_lshl_add_u32 v80, v98, 10, v152
	v_lshl_add_u64 v[104:105], v[80:81], 2, s[8:9]
	global_load_dwordx4 v[224:227], v[232:233], off offset:144
	global_load_dwordx4 v[228:231], v[232:233], off offset:128
	s_nop 0
	s_waitcnt vmcnt(9)
	v_mov_b32_e32 v100, v172
	v_mov_b32_e32 v101, v173
	v_mov_b32_e32 v102, v174
	v_mov_b32_e32 v103, v175
	v_mov_b32_e32 v104, v176
	v_mov_b32_e32 v105, v177
	v_mov_b32_e32 v106, v178
	v_mov_b32_e32 v107, v179
	v_pk_add_f32 v[102:103], v[92:93], v[102:103]
	v_pk_add_f32 v[96:97], v[96:97], v[106:107]
	v_pk_add_f32 v[94:95], v[94:95], v[104:105]
	v_pk_add_f32 v[100:101], v[90:91], v[100:101]
	v_cvt_pk_bf16_f32 v90, v94, v95
	v_cvt_pk_bf16_f32 v91, v96, v97
	v_cvt_pk_bf16_f32 v92, v100, v101
	v_cvt_pk_bf16_f32 v93, v102, v103
	v_lshl_add_u64 v[104:105], v[80:81], 1, s[12:13]
	global_store_dwordx4 v[104:105], v[90:93], off
	v_add_u32_e32 v80, 32, v80
	s_nop 0
	v_mul_f32_e32 v90, v95, v95
	v_mul_f32_e32 v91, v97, v97
	v_fmac_f32_e32 v90, v94, v94
	v_fmac_f32_e32 v91, v96, v96
	v_add_f32_e32 v90, v90, v91
	v_mul_f32_e32 v91, v101, v101
	v_fmac_f32_e32 v91, v100, v100
	v_add_f32_e32 v90, v90, v91
	v_mul_f32_e32 v91, v103, v103
	v_fmac_f32_e32 v91, v102, v102
	v_lshl_add_u64 v[94:95], v[80:81], 2, s[8:9]
	v_add_f32_e32 v99, v91, v90
	s_mov_b64 s[98:99], 0x50000
	v_lshl_add_u64 v[232:233], v[232:233], 0, s[98:99]
	global_load_dwordx4 v[172:175], v[232:233], off offset:16
	global_load_dwordx4 v[176:179], v[232:233], off offset:0
	s_nop 0
	s_waitcnt vmcnt(9)
	v_mov_b32_e32 v90, v180
	v_mov_b32_e32 v91, v181
	v_mov_b32_e32 v92, v182
	v_mov_b32_e32 v93, v183
	v_mov_b32_e32 v94, v212
	v_mov_b32_e32 v95, v213
	v_mov_b32_e32 v96, v214
	v_mov_b32_e32 v97, v215
	v_pk_add_f32 v[92:93], v[84:85], v[92:93]
	v_pk_add_f32 v[88:89], v[88:89], v[96:97]
	v_pk_add_f32 v[86:87], v[86:87], v[94:95]
	v_pk_add_f32 v[90:91], v[82:83], v[90:91]
	v_cvt_pk_bf16_f32 v82, v86, v87
	v_cvt_pk_bf16_f32 v83, v88, v89
	v_cvt_pk_bf16_f32 v84, v90, v91
	v_cvt_pk_bf16_f32 v85, v92, v93
	v_lshl_add_u64 v[94:95], v[80:81], 1, s[12:13]
	global_store_dwordx4 v[94:95], v[82:85], off
	v_mul_f32_e32 v80, v87, v87
	v_fmac_f32_e32 v80, v86, v86
	v_mul_f32_e32 v82, v89, v89
	v_fmac_f32_e32 v82, v88, v88
	v_add_f32_e32 v80, v80, v82
	v_mul_f32_e32 v82, v91, v91
	v_fmac_f32_e32 v82, v90, v90
	v_add_f32_e32 v80, v80, v82
	v_mul_f32_e32 v82, v93, v93
	v_fmac_f32_e32 v82, v92, v92
	v_add_f32_e32 v80, v82, v80
	v_add_f32_e32 v80, v99, v80
	ds_bpermute_b32 v82, v145, v80
	s_waitcnt lgkmcnt(0)
	v_add_f32_e32 v80, v80, v82
	ds_bpermute_b32 v82, v144, v80
	s_and_saveexec_b64 s[24:25], vcc
	s_cbranch_execz .LBB0_1179
	v_mov_b32_e32 v99, v81
	v_lshl_add_u64 v[84:85], v[98:99], 2, s[6:7]
	s_waitcnt lgkmcnt(0)
	v_add_f32_e32 v80, v80, v82
	global_atomic_add_f32 v[84:85], v80, off
.LBB0_1179:
	s_or_b64 exec, exec, s[24:25]
	s_waitcnt lgkmcnt(0)
	v_add_u32_e32 v82, 48, v138
	v_lshl_add_u32 v80, v82, 10, v152
	v_lshl_add_u64 v[88:89], v[80:81], 2, s[8:9]
	global_load_dwordx4 v[180:183], v[232:233], off offset:144
	global_load_dwordx4 v[212:215], v[232:233], off offset:128
	s_nop 0
	s_waitcnt vmcnt(9)
	v_mov_b32_e32 v84, v216
	v_mov_b32_e32 v85, v217
	v_mov_b32_e32 v86, v218
	v_mov_b32_e32 v87, v219
	v_mov_b32_e32 v88, v220
	v_mov_b32_e32 v89, v221
	v_mov_b32_e32 v90, v222
	v_mov_b32_e32 v91, v223
	v_pk_add_f32 v[86:87], v[74:75], v[86:87]
	v_pk_add_f32 v[78:79], v[78:79], v[90:91]
	v_pk_add_f32 v[76:77], v[76:77], v[88:89]
	v_pk_add_f32 v[84:85], v[72:73], v[84:85]
	v_cvt_pk_bf16_f32 v72, v76, v77
	v_cvt_pk_bf16_f32 v73, v78, v79
	v_cvt_pk_bf16_f32 v74, v84, v85
	v_cvt_pk_bf16_f32 v75, v86, v87
	v_lshl_add_u64 v[88:89], v[80:81], 1, s[12:13]
	global_store_dwordx4 v[88:89], v[72:75], off
	v_add_u32_e32 v80, 32, v80
	s_nop 0
	v_mul_f32_e32 v72, v77, v77
	v_mul_f32_e32 v73, v79, v79
	v_fmac_f32_e32 v72, v76, v76
	v_fmac_f32_e32 v73, v78, v78
	v_add_f32_e32 v72, v72, v73
	v_mul_f32_e32 v73, v85, v85
	v_fmac_f32_e32 v73, v84, v84
	v_add_f32_e32 v72, v72, v73
	v_mul_f32_e32 v73, v87, v87
	v_fmac_f32_e32 v73, v86, v86
	v_lshl_add_u64 v[76:77], v[80:81], 2, s[8:9]
	v_add_f32_e32 v83, v73, v72
	s_mov_b64 s[98:99], 0x10000
	v_lshl_add_u64 v[232:233], v[232:233], 0, s[98:99]
	global_load_dwordx4 v[216:219], v[232:233], off offset:16
	global_load_dwordx4 v[220:223], v[232:233], off offset:0
	s_nop 0
	s_waitcnt vmcnt(9)
	v_mov_b32_e32 v72, v224
	v_mov_b32_e32 v73, v225
	v_mov_b32_e32 v74, v226
	v_mov_b32_e32 v75, v227
	v_mov_b32_e32 v76, v228
	v_mov_b32_e32 v77, v229
	v_mov_b32_e32 v78, v230
	v_mov_b32_e32 v79, v231
	v_pk_add_f32 v[74:75], v[66:67], v[74:75]
	v_pk_add_f32 v[70:71], v[70:71], v[78:79]
	v_pk_add_f32 v[68:69], v[68:69], v[76:77]
	v_pk_add_f32 v[72:73], v[64:65], v[72:73]
	v_cvt_pk_bf16_f32 v64, v68, v69
	v_cvt_pk_bf16_f32 v65, v70, v71
	v_cvt_pk_bf16_f32 v66, v72, v73
	v_cvt_pk_bf16_f32 v67, v74, v75
	v_lshl_add_u64 v[76:77], v[80:81], 1, s[12:13]
	global_store_dwordx4 v[76:77], v[64:67], off
	s_nop 1
	v_mul_f32_e32 v64, v69, v69
	v_mul_f32_e32 v65, v71, v71
	v_fmac_f32_e32 v64, v68, v68
	v_fmac_f32_e32 v65, v70, v70
	v_add_f32_e32 v64, v64, v65
	v_mul_f32_e32 v65, v73, v73
	v_fmac_f32_e32 v65, v72, v72
	v_add_f32_e32 v64, v64, v65
	v_mul_f32_e32 v65, v75, v75
	v_fmac_f32_e32 v65, v74, v74
	v_add_f32_e32 v64, v65, v64
	v_add_f32_e32 v64, v83, v64
	ds_bpermute_b32 v65, v145, v64
	s_waitcnt lgkmcnt(0)
	v_add_f32_e32 v64, v64, v65
	ds_bpermute_b32 v65, v144, v64
	s_and_saveexec_b64 s[24:25], vcc
	s_cbranch_execz .LBB0_1181
	v_mov_b32_e32 v83, v81
	v_lshl_add_u64 v[66:67], v[82:83], 2, s[6:7]
	s_waitcnt lgkmcnt(0)
	v_add_f32_e32 v64, v64, v65
	global_atomic_add_f32 v[66:67], v64, off
; __device__ __forceinline__ unsigned pk2(float lo, float hi) { f32x2_t v = {lo, hi}; bf16x2_t b = __builtin_convertvector(v, bf16x2_t); return __builtin_bit_cast(unsigned, b); }
;     __device__ __forceinline__ void operator()(const f32x4 (&acc)[2][2][4][2], const pg8::Unit& u, int wr, int wc, int fr_, int fq_) const {
;     ...
;             for (int m = 0; m < 4; ++m) { const unsigned row = (unsigned)(u.pm * 256 + 128 * ai + 64 * wr + 16 * m + fr); float ss = 0.f;
; #pragma unroll
;                 for (int bj = 0; bj < 2; ++bj) { const unsigned o = row * 1024u + (unsigned)(u.pn * 256 + 64 * wc + 32 * bj + 8 * fq);
;                     const f32x4 r0 = *(const f32x4*)(res + o), r1 = *(const f32x4*)(res + o + 4);
;                     const f32x4 x0 = r0 + acc[ai][bj][m][0], x1 = r1 + acc[ai][bj][m][1];
;                     u32x4 w; w.x = pk2(x0[0], x0[1]); w.y = pk2(x0[2], x0[3]); w.z = pk2(x1[0], x1[1]); w.w = pk2(x1[2], x1[3]);
;                     *(u32x4*)(xb + o) = w;
;                     ss += (x0[0] * x0[0] + x0[1] * x0[1]) + (x0[2] * x0[2] + x0[3] * x0[3]) + (x1[0] * x1[0] + x1[1] * x1[1]) + (x1[2] * x1[2] + x1[3] * x1[3]); }
;                 ss += __shfl_xor(ss, 16); ss += __shfl_xor(ss, 32);
;                 if (fq == 0) atomicAdd(ssq + row, ss);
.LBB0_1181:
	s_or_b64 exec, exec, s[24:25]
	v_add_u32_e32 v64, 0x80, v138
	v_lshl_add_u32 v80, v64, 10, v152
	v_lshl_add_u64 v[70:71], v[80:81], 2, s[8:9]
	global_load_dwordx4 v[224:227], v[232:233], off offset:144
	global_load_dwordx4 v[228:231], v[232:233], off offset:128
	s_nop 0
	s_waitcnt vmcnt(9)
	v_mov_b32_e32 v66, v172
	v_mov_b32_e32 v67, v173
	v_mov_b32_e32 v68, v174
	v_mov_b32_e32 v69, v175
	v_mov_b32_e32 v70, v176
	v_mov_b32_e32 v71, v177
	v_mov_b32_e32 v72, v178
	v_mov_b32_e32 v73, v179
	v_pk_add_f32 v[68:69], v[58:59], v[68:69]
	v_pk_add_f32 v[62:63], v[62:63], v[72:73]
	v_pk_add_f32 v[60:61], v[60:61], v[70:71]
	v_pk_add_f32 v[66:67], v[56:57], v[66:67]
	v_cvt_pk_bf16_f32 v56, v60, v61
	v_cvt_pk_bf16_f32 v57, v62, v63
	v_cvt_pk_bf16_f32 v58, v66, v67
	v_cvt_pk_bf16_f32 v59, v68, v69
	v_lshl_add_u64 v[70:71], v[80:81], 1, s[12:13]
	global_store_dwordx4 v[70:71], v[56:59], off
	v_add_u32_e32 v80, 32, v80
	s_nop 0
	v_mul_f32_e32 v56, v61, v61
	v_mul_f32_e32 v57, v63, v63
	v_fmac_f32_e32 v56, v60, v60
	v_fmac_f32_e32 v57, v62, v62
	v_add_f32_e32 v56, v56, v57
	v_mul_f32_e32 v57, v67, v67
	v_fmac_f32_e32 v57, v66, v66
	v_add_f32_e32 v56, v56, v57
	v_mul_f32_e32 v57, v69, v69
	v_fmac_f32_e32 v57, v68, v68
	v_lshl_add_u64 v[60:61], v[80:81], 2, s[8:9]
	s_waitcnt lgkmcnt(0)
	v_add_f32_e32 v65, v57, v56
	s_mov_b64 s[98:99], 0x10000
	v_lshl_add_u64 v[232:233], v[232:233], 0, s[98:99]
	global_load_dwordx4 v[172:175], v[232:233], off offset:16
	global_load_dwordx4 v[176:179], v[232:233], off offset:0
	s_nop 0
	s_waitcnt vmcnt(9)
	v_mov_b32_e32 v56, v180
	v_mov_b32_e32 v57, v181
	v_mov_b32_e32 v58, v182
	v_mov_b32_e32 v59, v183
	v_mov_b32_e32 v60, v212
	v_mov_b32_e32 v61, v213
	v_mov_b32_e32 v62, v214
	v_mov_b32_e32 v63, v215
	v_pk_add_f32 v[58:59], v[50:51], v[58:59]
	v_pk_add_f32 v[54:55], v[54:55], v[62:63]
	v_pk_add_f32 v[52:53], v[52:53], v[60:61]
	v_pk_add_f32 v[56:57], v[48:49], v[56:57]
	v_cvt_pk_bf16_f32 v48, v52, v53
	v_cvt_pk_bf16_f32 v49, v54, v55
	v_cvt_pk_bf16_f32 v50, v56, v57
	v_cvt_pk_bf16_f32 v51, v58, v59
	v_lshl_add_u64 v[60:61], v[80:81], 1, s[12:13]
	global_store_dwordx4 v[60:61], v[48:51], off
	s_nop 1
	v_mul_f32_e32 v48, v53, v53
	v_mul_f32_e32 v49, v55, v55
	v_fmac_f32_e32 v48, v52, v52
	v_fmac_f32_e32 v49, v54, v54
	v_add_f32_e32 v48, v48, v49
	v_mul_f32_e32 v49, v57, v57
	v_fmac_f32_e32 v49, v56, v56
	v_add_f32_e32 v48, v48, v49
	v_mul_f32_e32 v49, v59, v59
	v_fmac_f32_e32 v49, v58, v58
	v_add_f32_e32 v48, v49, v48
	v_add_f32_e32 v48, v65, v48
	ds_bpermute_b32 v49, v145, v48
	s_waitcnt lgkmcnt(0)
	v_add_f32_e32 v48, v48, v49
	ds_bpermute_b32 v49, v144, v48
	s_and_saveexec_b64 s[24:25], vcc
	s_cbranch_execz .LBB0_1183
	v_mov_b32_e32 v65, v81
	v_lshl_add_u64 v[50:51], v[64:65], 2, s[6:7]
	s_waitcnt lgkmcnt(0)
	v_add_f32_e32 v48, v48, v49
	global_atomic_add_f32 v[50:51], v48, off
.LBB0_1183:
	s_or_b64 exec, exec, s[24:25]
	v_add_u32_e32 v48, 0x90, v138
	v_lshl_add_u32 v80, v48, 10, v152
	v_lshl_add_u64 v[54:55], v[80:81], 2, s[8:9]
	global_load_dwordx4 v[180:183], v[232:233], off offset:144
	global_load_dwordx4 v[212:215], v[232:233], off offset:128
	s_nop 0
	s_waitcnt vmcnt(9)
	v_mov_b32_e32 v50, v216
	v_mov_b32_e32 v51, v217
	v_mov_b32_e32 v52, v218
	v_mov_b32_e32 v53, v219
	v_mov_b32_e32 v54, v220
	v_mov_b32_e32 v55, v221
	v_mov_b32_e32 v56, v222
	v_mov_b32_e32 v57, v223
	v_pk_add_f32 v[52:53], v[42:43], v[52:53]
	v_pk_add_f32 v[46:47], v[46:47], v[56:57]
	v_pk_add_f32 v[44:45], v[44:45], v[54:55]
	v_pk_add_f32 v[50:51], v[40:41], v[50:51]
	v_cvt_pk_bf16_f32 v40, v44, v45
	v_cvt_pk_bf16_f32 v41, v46, v47
	v_cvt_pk_bf16_f32 v42, v50, v51
	v_cvt_pk_bf16_f32 v43, v52, v53
	v_lshl_add_u64 v[54:55], v[80:81], 1, s[12:13]
	global_store_dwordx4 v[54:55], v[40:43], off
	v_add_u32_e32 v80, 32, v80
	s_nop 0
	v_mul_f32_e32 v40, v45, v45
	v_mul_f32_e32 v41, v47, v47
	v_fmac_f32_e32 v40, v44, v44
	v_fmac_f32_e32 v41, v46, v46
	v_add_f32_e32 v40, v40, v41
	v_mul_f32_e32 v41, v51, v51
	v_fmac_f32_e32 v41, v50, v50
	v_add_f32_e32 v40, v40, v41
	v_mul_f32_e32 v41, v53, v53
	v_fmac_f32_e32 v41, v52, v52
	v_lshl_add_u64 v[44:45], v[80:81], 2, s[8:9]
	s_waitcnt lgkmcnt(0)
	v_add_f32_e32 v49, v41, v40
	s_mov_b64 s[98:99], 0x10000
	v_lshl_add_u64 v[232:233], v[232:233], 0, s[98:99]
	global_load_dwordx4 v[216:219], v[232:233], off offset:16
	global_load_dwordx4 v[220:223], v[232:233], off offset:0
	s_nop 0
	s_waitcnt vmcnt(9)
	v_mov_b32_e32 v40, v224
	v_mov_b32_e32 v41, v225
	v_mov_b32_e32 v42, v226
	v_mov_b32_e32 v43, v227
	v_mov_b32_e32 v44, v228
	v_mov_b32_e32 v45, v229
	v_mov_b32_e32 v46, v230
	v_mov_b32_e32 v47, v231
	v_pk_add_f32 v[42:43], v[34:35], v[42:43]
	v_pk_add_f32 v[38:39], v[38:39], v[46:47]
	v_pk_add_f32 v[36:37], v[36:37], v[44:45]
	v_pk_add_f32 v[40:41], v[32:33], v[40:41]
	v_cvt_pk_bf16_f32 v32, v36, v37
	v_cvt_pk_bf16_f32 v33, v38, v39
	v_cvt_pk_bf16_f32 v34, v40, v41
	v_cvt_pk_bf16_f32 v35, v42, v43
	v_lshl_add_u64 v[44:45], v[80:81], 1, s[12:13]
	global_store_dwordx4 v[44:45], v[32:35], off
	s_nop 1
	v_mul_f32_e32 v32, v37, v37
	v_mul_f32_e32 v33, v39, v39
	v_fmac_f32_e32 v32, v36, v36
	v_fmac_f32_e32 v33, v38, v38
	v_add_f32_e32 v32, v32, v33
	v_mul_f32_e32 v33, v41, v41
	v_fmac_f32_e32 v33, v40, v40
	v_add_f32_e32 v32, v32, v33
	v_mul_f32_e32 v33, v43, v43
	v_fmac_f32_e32 v33, v42, v42
	v_add_f32_e32 v32, v33, v32
	v_add_f32_e32 v32, v49, v32
	ds_bpermute_b32 v33, v145, v32
	s_waitcnt lgkmcnt(0)
	v_add_f32_e32 v32, v32, v33
	ds_bpermute_b32 v33, v144, v32
	s_and_saveexec_b64 s[24:25], vcc
	s_cbranch_execz .LBB0_1185
	v_mov_b32_e32 v49, v81
	v_lshl_add_u64 v[34:35], v[48:49], 2, s[6:7]
	s_waitcnt lgkmcnt(0)
	v_add_f32_e32 v32, v32, v33
	global_atomic_add_f32 v[34:35], v32, off
; __device__ __forceinline__ unsigned pk2(float lo, float hi) { f32x2_t v = {lo, hi}; bf16x2_t b = __builtin_convertvector(v, bf16x2_t); return __builtin_bit_cast(unsigned, b); }
;     __device__ __forceinline__ void operator()(const f32x4 (&acc)[2][2][4][2], const pg8::Unit& u, int wr, int wc, int fr_, int fq_) const {
;     ...
;             for (int m = 0; m < 4; ++m) { const unsigned row = (unsigned)(u.pm * 256 + 128 * ai + 64 * wr + 16 * m + fr); float ss = 0.f;
; #pragma unroll
;                 for (int bj = 0; bj < 2; ++bj) { const unsigned o = row * 1024u + (unsigned)(u.pn * 256 + 64 * wc + 32 * bj + 8 * fq);
;                     const f32x4 r0 = *(const f32x4*)(res + o), r1 = *(const f32x4*)(res + o + 4);
;                     const f32x4 x0 = r0 + acc[ai][bj][m][0], x1 = r1 + acc[ai][bj][m][1];
;                     u32x4 w; w.x = pk2(x0[0], x0[1]); w.y = pk2(x0[2], x0[3]); w.z = pk2(x1[0], x1[1]); w.w = pk2(x1[2], x1[3]);
;                     *(u32x4*)(xb + o) = w;
;                     ss += (x0[0] * x0[0] + x0[1] * x0[1]) + (x0[2] * x0[2] + x0[3] * x0[3]) + (x1[0] * x1[0] + x1[1] * x1[1]) + (x1[2] * x1[2] + x1[3] * x1[3]); }
;                 ss += __shfl_xor(ss, 16); ss += __shfl_xor(ss, 32);
;                 if (fq == 0) atomicAdd(ssq + row, ss);
.LBB0_1185:
	s_or_b64 exec, exec, s[24:25]
	v_add_u32_e32 v32, 0xa0, v138
	v_lshl_add_u32 v80, v32, 10, v152
	v_lshl_add_u64 v[38:39], v[80:81], 2, s[8:9]
	global_load_dwordx4 v[224:227], v[232:233], off offset:144
	global_load_dwordx4 v[228:231], v[232:233], off offset:128
	s_nop 0
	s_waitcnt vmcnt(9)
	v_mov_b32_e32 v34, v172
	v_mov_b32_e32 v35, v173
	v_mov_b32_e32 v36, v174
	v_mov_b32_e32 v37, v175
	v_mov_b32_e32 v38, v176
	v_mov_b32_e32 v39, v177
	v_mov_b32_e32 v40, v178
	v_mov_b32_e32 v41, v179
	v_pk_add_f32 v[36:37], v[26:27], v[36:37]
	v_pk_add_f32 v[30:31], v[30:31], v[40:41]
	v_pk_add_f32 v[28:29], v[28:29], v[38:39]
	v_pk_add_f32 v[34:35], v[24:25], v[34:35]
	v_cvt_pk_bf16_f32 v24, v28, v29
	v_cvt_pk_bf16_f32 v25, v30, v31
	v_cvt_pk_bf16_f32 v26, v34, v35
	v_cvt_pk_bf16_f32 v27, v36, v37
	v_lshl_add_u64 v[38:39], v[80:81], 1, s[12:13]
	global_store_dwordx4 v[38:39], v[24:27], off
	v_add_u32_e32 v80, 32, v80
	s_nop 0
	v_mul_f32_e32 v24, v29, v29
	v_mul_f32_e32 v25, v31, v31
	v_fmac_f32_e32 v24, v28, v28
	v_fmac_f32_e32 v25, v30, v30
	v_add_f32_e32 v24, v24, v25
	v_mul_f32_e32 v25, v35, v35
	v_fmac_f32_e32 v25, v34, v34
	v_add_f32_e32 v24, v24, v25
	v_mul_f32_e32 v25, v37, v37
	v_fmac_f32_e32 v25, v36, v36
	v_lshl_add_u64 v[28:29], v[80:81], 2, s[8:9]
	s_waitcnt lgkmcnt(0)
	v_add_f32_e32 v33, v25, v24
	s_nop 0
	s_waitcnt vmcnt(7)
	v_mov_b32_e32 v24, v180
	v_mov_b32_e32 v25, v181
	v_mov_b32_e32 v26, v182
	v_mov_b32_e32 v27, v183
	v_mov_b32_e32 v28, v212
	v_mov_b32_e32 v29, v213
	v_mov_b32_e32 v30, v214
	v_mov_b32_e32 v31, v215
	v_pk_add_f32 v[26:27], v[18:19], v[26:27]
	v_pk_add_f32 v[22:23], v[22:23], v[30:31]
	v_pk_add_f32 v[20:21], v[20:21], v[28:29]
	v_pk_add_f32 v[24:25], v[16:17], v[24:25]
	v_cvt_pk_bf16_f32 v16, v20, v21
	v_cvt_pk_bf16_f32 v17, v22, v23
	v_cvt_pk_bf16_f32 v18, v24, v25
	v_cvt_pk_bf16_f32 v19, v26, v27
	v_lshl_add_u64 v[28:29], v[80:81], 1, s[12:13]
	global_store_dwordx4 v[28:29], v[16:19], off
	s_nop 1
	v_mul_f32_e32 v16, v21, v21
	v_mul_f32_e32 v17, v23, v23
	v_fmac_f32_e32 v16, v20, v20
	v_fmac_f32_e32 v17, v22, v22
	v_add_f32_e32 v16, v16, v17
	v_mul_f32_e32 v17, v25, v25
	v_fmac_f32_e32 v17, v24, v24
	v_add_f32_e32 v16, v16, v17
	v_mul_f32_e32 v17, v27, v27
	v_fmac_f32_e32 v17, v26, v26
	v_add_f32_e32 v16, v17, v16
	v_add_f32_e32 v16, v33, v16
	ds_bpermute_b32 v17, v145, v16
	s_waitcnt lgkmcnt(0)
	v_add_f32_e32 v16, v16, v17
	ds_bpermute_b32 v17, v144, v16
	s_and_saveexec_b64 s[24:25], vcc
	s_cbranch_execz .LBB0_1187
	v_mov_b32_e32 v33, v81
	v_lshl_add_u64 v[18:19], v[32:33], 2, s[6:7]
	s_waitcnt lgkmcnt(0)
	v_add_f32_e32 v16, v16, v17
	global_atomic_add_f32 v[18:19], v16, off
.LBB0_1187:
	s_or_b64 exec, exec, s[24:25]
	v_add_u32_e32 v16, 0xb0, v138
	v_lshl_add_u32 v80, v16, 10, v152
	v_lshl_add_u64 v[22:23], v[80:81], 2, s[8:9]
	s_nop 0
	s_waitcnt vmcnt(5)
	v_mov_b32_e32 v18, v216
	v_mov_b32_e32 v19, v217
	v_mov_b32_e32 v20, v218
	v_mov_b32_e32 v21, v219
	v_mov_b32_e32 v22, v220
	v_mov_b32_e32 v23, v221
	v_mov_b32_e32 v24, v222
	v_mov_b32_e32 v25, v223
	v_pk_add_f32 v[20:21], v[10:11], v[20:21]
	v_pk_add_f32 v[14:15], v[14:15], v[24:25]
	v_pk_add_f32 v[12:13], v[12:13], v[22:23]
	v_pk_add_f32 v[18:19], v[8:9], v[18:19]
	v_cvt_pk_bf16_f32 v8, v12, v13
	v_cvt_pk_bf16_f32 v9, v14, v15
	v_cvt_pk_bf16_f32 v10, v18, v19
	v_cvt_pk_bf16_f32 v11, v20, v21
	v_lshl_add_u64 v[22:23], v[80:81], 1, s[12:13]
	global_store_dwordx4 v[22:23], v[8:11], off
	v_add_u32_e32 v80, 32, v80
	s_nop 0
	v_mul_f32_e32 v8, v13, v13
	v_mul_f32_e32 v9, v15, v15
	v_fmac_f32_e32 v8, v12, v12
	v_fmac_f32_e32 v9, v14, v14
	v_add_f32_e32 v8, v8, v9
	v_mul_f32_e32 v9, v19, v19
	v_fmac_f32_e32 v9, v18, v18
	v_add_f32_e32 v8, v8, v9
	v_mul_f32_e32 v9, v21, v21
	v_fmac_f32_e32 v9, v20, v20
	v_lshl_add_u64 v[12:13], v[80:81], 2, s[8:9]
	s_waitcnt lgkmcnt(0)
	v_add_f32_e32 v17, v9, v8
	s_nop 0
	s_waitcnt vmcnt(3)
	v_mov_b32_e32 v8, v224
	v_mov_b32_e32 v9, v225
	v_mov_b32_e32 v10, v226
	v_mov_b32_e32 v11, v227
	v_mov_b32_e32 v12, v228
	v_mov_b32_e32 v13, v229
	v_mov_b32_e32 v14, v230
	v_mov_b32_e32 v15, v231
	v_pk_add_f32 v[10:11], v[2:3], v[10:11]
	v_pk_add_f32 v[6:7], v[6:7], v[14:15]
	v_pk_add_f32 v[4:5], v[4:5], v[12:13]
	v_pk_add_f32 v[8:9], v[0:1], v[8:9]
	v_cvt_pk_bf16_f32 v0, v4, v5
	v_cvt_pk_bf16_f32 v1, v6, v7
	v_cvt_pk_bf16_f32 v2, v8, v9
	v_cvt_pk_bf16_f32 v3, v10, v11
	v_lshl_add_u64 v[12:13], v[80:81], 1, s[12:13]
	global_store_dwordx4 v[12:13], v[0:3], off
	s_nop 1
	v_mul_f32_e32 v0, v5, v5
	v_mul_f32_e32 v1, v7, v7
	v_fmac_f32_e32 v0, v4, v4
	v_fmac_f32_e32 v1, v6, v6
	v_add_f32_e32 v0, v0, v1
	v_mul_f32_e32 v1, v9, v9
	v_fmac_f32_e32 v1, v8, v8
	v_add_f32_e32 v0, v0, v1
	v_mul_f32_e32 v1, v11, v11
	v_fmac_f32_e32 v1, v10, v10
	v_add_f32_e32 v0, v1, v0
	v_add_f32_e32 v0, v17, v0
	ds_bpermute_b32 v1, v145, v0
	s_waitcnt lgkmcnt(0)
	v_add_f32_e32 v0, v0, v1
	ds_bpermute_b32 v1, v144, v0
	s_and_saveexec_b64 s[24:25], vcc
	s_cbranch_execz .LBB0_1189
	v_mov_b32_e32 v17, v81
	v_lshl_add_u64 v[2:3], v[16:17], 2, s[6:7]
	s_waitcnt lgkmcnt(0)
	v_add_f32_e32 v0, v0, v1
	global_atomic_add_f32 v[2:3], v0, off

;     __host__ __device__ bool next(int i, Unit& u) const {
;         const long L = (long)i * G + c; if (L >= nwg) return false;
;         int wgid = (int)L; { const int q = nwg / NXCD, r = nwg % NXCD, xcd = wgid % NXCD, off = wgid / NXCD; wgid = (xcd < r ? xcd * (q + 1) : r * (q + 1) + (xcd - r) * q) + off; }
; template <class Epi, class Sched, bool ALIGN_EPI = false, bool SP2 = false>
; __device__ __forceinline__ void gemm_phase(PG8_LAS unsigned char* lds, const Gemm g, const Sched& S, const Epi& E, int tid_in) {
;     const int tid = tid_in, wid = __builtin_amdgcn_readfirstlane(tid >> 6), lane = tid & 63, wr = wid >> 2, wc = wid & 3, fr = lane & 15, fq = lane >> 4;
;     const int K = g.K, nt = K / BK;
;     unsigned voffA[2], voffB[2];
; #pragma unroll
;     for (int i = 0; i < 2; ++i) { int R, C; stage_rc(tid * 16 + i * 8192, R, C); const int Rb = Epi::PERM ? ((R & ~31) + perm32(R & 31)) : R;
;         voffA[i] = (unsigned)(R * g.lda + C) * 2u; voffB[i] = (unsigned)(Rb * g.ldb + C) * 2u; }
;     const size_t kstep = (size_t)(BK * 2);
;     const size_t hstepA = (size_t)HALF * g.lda * 2, hstepB = (size_t)HALF * g.ldb * 2;
;     const size_t tstepA = 2 * hstepA, tstepB = 2 * hstepB;
;     const unsigned ldsw = (unsigned)wid * 1024u;
;     const int aoff = lds_byte(wr * 64 + fr, fq * 8), boff = lds_byte(wc * 32 + fr, fq * 8);
;     ...
;     Unit cur, nxt; int ui = 0;
;     if (!S.next(0, cur)) return;
;     f32x4 acc[2][2][4][2];
; #pragma unroll
;     for (int a = 0; a < 2; ++a)
; #pragma unroll
;         for (int b = 0; b < 2; ++b)
; #pragma unroll
;             for (int m = 0; m < 4; ++m)
; #pragma unroll
;                 for (int n = 0; n < 2; ++n) acc[a][b][m][n] = (f32x4){0.f, 0.f, 0.f, 0.f};
;     bf16x8 At[4][2], B0[2][2], B1[2][2];
;     const char* cA = (const char*)g.A + (size_t)cur.pm * tstepA; const char* cB = (const char*)g.Bt + (size_t)cur.pn * tstepB;
;     S.a_ready(cur);
;     if constexpr (SP2) {
;         PG8_STAGE(PG8_SB(0, 0), cB, voffB); PG8_STAGE(PG8_SB(0, 1), cB + hstepB, voffB); PG8_STAGE(PG8_SA(0, 0), cA, voffA); PG8_STAGE(PG8_SA(0, 1), cA + hstepA, voffA);
;         if (wr == 1) PG8_BAR;
;         PG8_WAIT_V(2); PG8_BAR;
;         PG8_STAGE(PG8_SB(1, 0), cB + kstep, voffB); PG8_STAGE(PG8_SA(1, 0), cA + kstep, voffA); PG8_STAGE(PG8_SB(1, 1), cB + hstepB + kstep, voffB);
;         PG8_WAIT_V(6); PG8_BAR;
.LBB0_1203:
	s_nop 0
	s_or_b64 exec, exec, s[4:5]
	v_readlane_b32 s4, v255, 17
	s_barrier
	s_mov_b64 s[4:5], s[58:59]
	s_mov_b32 s30, s69
	s_mov_b32 s31, s2
	v_mov_b32_e32 v9, v146
	s_cmpk_gt_i32 s31, 0xaff
	v_readfirstlane_b32 s13, v9
	s_cbranch_scc1 .LBB0_1219
	v_lshlrev_b32_e32 v0, 4, v9
	v_add_u32_e32 v1, 0x2000, v0
	v_ashrrev_i32_e32 v2, 31, v1
	v_lshrrev_b32_e32 v2, 22, v2
	v_add_u32_e32 v2, v1, v2
	v_ashrrev_i32_e32 v8, 10, v2
	v_mul_i32_i24_e32 v3, 0x400, v8
	v_sub_u32_e32 v1, v1, v3
	v_lshrrev_b32_e32 v3, 4, v1
	v_bitop3_b32 v1, v3, v1, 32 bitop3:0x6c
	s_add_u32 s34, s4, 0x3100000
	v_ashrrev_i32_e32 v3, 31, v1
	s_addc_u32 s35, s5, 0
	v_lshrrev_b32_e32 v3, 26, v3
	s_add_u32 s36, s4, 0x1100000
	v_add_u32_e32 v3, v1, v3
	s_addc_u32 s37, s5, 0
	v_ashrrev_i32_e32 v10, 6, v3
	v_and_b32_e32 v3, 0xc0, v3
	s_ashr_i32 s39, s31, 31
	v_sub_u32_e32 v1, v1, v3
	s_lshr_b32 s6, s39, 29
	v_lshlrev_b32_e32 v2, 5, v8
	v_ashrrev_i16_sdwa v1, v164, sext(v1) dst_sel:DWORD dst_unused:UNUSED_PAD src0_sel:DWORD src1_sel:BYTE_0
	s_add_i32 s6, s31, s6
	s_ashr_i32 s14, s13, 6
	v_and_b32_e32 v2, 32, v2
	v_bfe_i32 v11, v1, 0, 16
	s_ashr_i32 s7, s6, 3
	s_and_b32 s6, s6, -8
	s_ashr_i32 s15, s13, 8
	s_lshl_b32 s38, s14, 10
	v_add_u32_e32 v1, v2, v11
	v_lshlrev_b32_e32 v2, 3, v8
	s_sub_i32 s6, s31, s6
	v_and_b32_e32 v2, 0x1ffff0, v2
	s_cmp_lt_i32 s6, 0
	s_movk_i32 s8, 0x161
	v_add_lshl_u32 v2, v10, v2, 11
	s_cselect_b32 s8, s8, 0x160
	v_lshl_add_u32 v130, v1, 1, v2
	v_bfe_i32 v2, v9, 27, 1
	s_mul_i32 s6, s6, s8
	v_lshrrev_b32_e32 v2, 22, v2
	s_add_i32 s6, s6, s7
	v_add_u32_e32 v2, v0, v2
	s_mul_hi_i32 s7, s6, 0x2e8ba2e9
	v_and_b32_e32 v2, 0xfffffc00, v2
	s_lshr_b32 s8, s7, 31
	s_ashr_i32 s7, s7, 5
	v_sub_u32_e32 v0, v0, v2
	s_add_i32 s7, s7, s8
	v_lshrrev_b32_e32 v2, 4, v0
	s_lshl_b32 s8, s7, 3
	s_mulk_i32 s7, 0xb0
	v_bitop3_b32 v0, v2, v0, 32 bitop3:0x6c
	s_sub_i32 s6, s6, s7
	v_ashrrev_i32_e32 v2, 31, v0
	s_bfe_u32 s7, s6, 0x3001c
	v_ashrrev_i32_e32 v1, 31, v9
	v_lshrrev_b32_e32 v2, 26, v2
	s_add_i32 s7, s6, s7
	v_lshrrev_b32_e32 v1, 26, v1
	v_add_u32_e32 v2, v0, v2
	s_sext_i32_i16 s9, s7
	s_and_b32 s7, s7, 0xfff8
	v_add_u32_e32 v1, v9, v1
	v_ashrrev_i32_e32 v13, 6, v2
	v_and_b32_e32 v2, 0xc0, v2
	s_sub_i32 s6, s6, s7
	v_ashrrev_i32_e32 v12, 6, v1
	v_sub_u32_e32 v0, v0, v2
	s_sext_i32_i16 s6, s6
	v_lshlrev_b32_e32 v1, 5, v12
	v_ashrrev_i16_sdwa v0, v164, sext(v0) dst_sel:DWORD dst_unused:UNUSED_PAD src0_sel:DWORD src1_sel:BYTE_0
	s_lshr_b32 s12, s9, 3
	s_add_i32 s22, s8, s6
	v_and_b32_e32 v1, 32, v1
	v_bfe_i32 v14, v0, 0, 16
	s_ashr_i32 s23, s22, 31
	s_bfe_i64 s[8:9], s[12:13], 0x100000
	v_add_u32_e32 v0, v1, v14
	v_lshlrev_b32_e32 v1, 3, v12
	s_lshl_b64 s[6:7], s[22:23], 19
	s_lshl_b64 s[8:9], s[8:9], 19
	v_and_b32_e32 v1, 0x1ffff0, v1
	s_add_u32 s26, s36, s8
	v_add_lshl_u32 v1, v13, v1, 11
	s_addc_u32 s27, s37, s9
	s_add_i32 s40, s38, 0x100
	v_lshl_add_u32 v132, v0, 1, v1
	s_add_i32 m0, s40, 0x10000
	v_mov_b32_e32 v133, v81
	global_load_lds_dwordx4 v132, s[26:27]
	s_add_i32 m0, s40, 0x12000
	s_add_u32 s8, s26, 0x40000
	global_load_lds_dwordx4 v130, s[26:27]
	s_addc_u32 s9, s27, 0
	s_add_i32 m0, s40, 0x14000
	v_mov_b32_e32 v131, v81
	global_load_lds_dwordx4 v132, s[8:9]
	s_add_i32 m0, s40, 0x16000
	s_add_u32 s24, s34, s6
	s_addc_u32 s25, s35, s7
	s_add_i32 s41, s40, 0x2000
	global_load_lds_dwordx4 v130, s[8:9]
	s_mov_b32 m0, s40
	s_add_u32 s6, s24, 0x40000
	global_load_lds_dwordx4 v132, s[24:25]
	s_mov_b32 m0, s41
	s_addc_u32 s7, s25, 0
	s_add_i32 s42, s40, 0x4000
	global_load_lds_dwordx4 v130, s[24:25]
	s_mov_b32 m0, s42
	s_add_i32 s43, s40, 0x6000
	global_load_lds_dwordx4 v132, s[6:7]
	s_mov_b32 m0, s43
	s_cmp_eq_u32 s15, 1
	global_load_lds_dwordx4 v130, s[6:7]
	v_lshl_add_u64 v[6:7], s[26:27], 0, v[132:133]
	v_lshl_add_u64 v[4:5], s[26:27], 0, v[130:131]
	v_lshl_add_u64 v[0:1], s[24:25], 0, v[132:133]
	s_cselect_b64 s[6:7], -1, 0
	s_cmp_lg_u32 s15, 1
	v_lshl_add_u64 v[2:3], s[24:25], 0, v[130:131]
	s_cbranch_scc1 .LBB0_1206
	s_barrier

; __device__ __forceinline__ unsigned pk2(float lo, float hi) { f32x2_t v = {lo, hi}; bf16x2_t b = __builtin_convertvector(v, bf16x2_t); return __builtin_bit_cast(unsigned, b); }
; __device__ __forceinline__ float sigmoidf_(float x) { return __builtin_amdgcn_rcpf(1.0f + __expf(-x)); }
;     __device__ __forceinline__ void operator()(const f32x4 (&acc)[2][2][4][2], const pg8::Unit& u, int wr, int wc, int fr_, int fq_) const {
;     ...
;             for (int m = 0; m < 4; ++m) { const unsigned row = (unsigned)(u.pm * 256 + 128 * ai + 64 * wr + 16 * m + fr);
;                 float v[8]; const float rs = __builtin_amdgcn_rsqf(ssq[row] * (1.0f / DM) + 1e-6f);
; #pragma unroll
;                 for (int n = 0; n < 2; ++n)
; #pragma unroll
;                     for (int e = 0; e < 4; ++e) { const float g = acc[ai][0][m][n][e] * rs, up = acc[ai][1][m][n][e] * rs; v[4 * n + e] = g * sigmoidf_(g) * up; }
;                 u32x4 w; w.x = pk2(v[0], v[1]); w.y = pk2(v[2], v[3]); w.z = pk2(v[4], v[5]); w.w = pk2(v[6], v[7]);
;                 *(u32x4*)(act + (row * 2816u + (unsigned)(u.pn * 128 + 32 * wc + 8 * fq))) = w; }
.LBB0_1215:
	v_mov_b32_e32 v80, v138
	v_mov_b32_e32 v142, v139
	s_lshl_b32 s15, s22, 8
	s_add_i32 s15, s15, s44
	v_add_u32_e32 v80, s15, v80
	v_lshlrev_b32_e32 v152, 3, v142
	v_lshl_add_u64 v[142:143], v[80:81], 2, s[10:11]
	v_mov_b32_e32 v252, v142
	v_mov_b32_e32 v253, v143
	global_load_dword v250, v[252:253], off
	global_load_dword v251, v[252:253], off offset:64
	s_lshl_b32 s15, s23, 7
	s_or_b32 s15, s15, s45
	v_readlane_b32 s56, v255, 10
	s_mov_b64 s[22:23], -1
	s_andn2_b64 vcc, exec, s[4:5]
	v_readlane_b32 s57, v255, 11
	v_readlane_b32 s58, v255, 12
	v_readlane_b32 s59, v255, 13
	s_waitcnt vmcnt(1)
	v_mov_b32_e32 v142, v250
	v_fmamk_f32 v142, v142, 0x3a800000, v147
	v_rsq_f32_e32 v142, v142
	s_nop 0
	v_pk_mul_f32 v[126:127], v[126:127], v[142:143] op_sel_hi:[1,0]
	s_nop 0
	v_mul_f32_e32 v143, 0xbfb8aa3b, v126
	v_exp_f32_e32 v143, v143
	s_nop 0
	v_add_f32_e32 v143, 1.0, v143
	v_rcp_f32_e32 v144, v143
	v_pk_mul_f32 v[118:119], v[118:119], v[142:143] op_sel_hi:[1,0]
	v_mul_f32_e32 v143, 0xbfb8aa3b, v127
	v_exp_f32_e32 v143, v143
	s_nop 0
	v_add_f32_e32 v143, 1.0, v143
	v_rcp_f32_e32 v145, v143
	v_pk_mul_f32 v[120:121], v[120:121], v[142:143] op_sel_hi:[1,0]
	v_pk_mul_f32 v[122:123], v[122:123], v[142:143] op_sel_hi:[1,0]
	v_pk_mul_f32 v[114:115], v[114:115], v[142:143] op_sel_hi:[1,0]
	v_pk_mul_f32 v[126:127], v[126:127], v[144:145]
	v_pk_mul_f32 v[116:117], v[116:117], v[142:143] op_sel_hi:[1,0]
	v_pk_mul_f32 v[118:119], v[118:119], v[126:127]
	v_pk_mul_f32 v[126:127], v[128:129], v[142:143] op_sel_hi:[1,0]
	s_nop 0
	v_mul_f32_e32 v128, 0xbfb8aa3b, v126
	v_mul_f32_e32 v129, 0xbfb8aa3b, v127
	v_exp_f32_e32 v128, v128
	v_exp_f32_e32 v129, v129
	v_add_f32_e32 v128, 1.0, v128
	v_add_f32_e32 v129, 1.0, v129
	v_rcp_f32_e32 v128, v128
	v_rcp_f32_e32 v129, v129
	s_nop 0
	v_pk_mul_f32 v[126:127], v[126:127], v[128:129]
	s_nop 0
	v_pk_mul_f32 v[120:121], v[120:121], v[126:127]
	v_mul_f32_e32 v126, 0xbfb8aa3b, v122
	v_mul_f32_e32 v127, 0xbfb8aa3b, v123
	v_exp_f32_e32 v126, v126
	v_exp_f32_e32 v127, v127
	v_add_f32_e32 v126, 1.0, v126
	v_add_f32_e32 v127, 1.0, v127
	v_rcp_f32_e32 v126, v126
	v_rcp_f32_e32 v127, v127
	s_nop 0
	v_pk_mul_f32 v[122:123], v[122:123], v[126:127]
	s_nop 0
	v_pk_mul_f32 v[122:123], v[114:115], v[122:123]
	v_pk_mul_f32 v[114:115], v[124:125], v[142:143] op_sel_hi:[1,0]
	s_nop 0
	v_mul_f32_e32 v124, 0xbfb8aa3b, v114
	v_mul_f32_e32 v125, 0xbfb8aa3b, v115
	v_exp_f32_e32 v124, v124
	v_exp_f32_e32 v125, v125
	v_add_f32_e32 v124, 1.0, v124
	v_add_f32_e32 v125, 1.0, v125
	v_rcp_f32_e32 v124, v124
	v_rcp_f32_e32 v125, v125
	s_nop 0
	v_pk_mul_f32 v[114:115], v[114:115], v[124:125]
	s_nop 0
	v_pk_mul_f32 v[124:125], v[116:117], v[114:115]
	v_cvt_pk_bf16_f32 v114, v118, v119
	v_mul_lo_u32 v118, v80, s81
	v_add3_u32 v118, s15, v152, v118
	v_mov_b32_e32 v119, v81
	v_cvt_pk_bf16_f32 v115, v120, v121
	v_cvt_pk_bf16_f32 v116, v122, v123
	v_cvt_pk_bf16_f32 v117, v124, v125
	v_lshl_add_u64 v[120:121], v[118:119], 1, s[8:9]
	global_store_dwordx4 v[120:121], v[114:117], off
	s_nop 1
	v_add_u32_e32 v114, 16, v80
	v_mov_b32_e32 v115, v81
	v_lshl_add_u64 v[114:115], v[114:115], 2, s[10:11]
	global_load_dword v250, v[252:253], off offset:128
	s_waitcnt vmcnt(2)
	v_mov_b32_e32 v114, v251
	v_fmamk_f32 v114, v114, 0x3a800000, v147
	v_rsq_f32_e32 v114, v114
	s_nop 0
	v_pk_mul_f32 v[110:111], v[110:111], v[114:115] op_sel_hi:[1,0]
	s_nop 0
	v_mul_f32_e32 v115, 0xbfb8aa3b, v110
	v_exp_f32_e32 v115, v115
	s_nop 0
	v_add_f32_e32 v115, 1.0, v115
	v_rcp_f32_e32 v116, v115
	v_pk_mul_f32 v[102:103], v[102:103], v[114:115] op_sel_hi:[1,0]
	v_mul_f32_e32 v115, 0xbfb8aa3b, v111
	v_exp_f32_e32 v115, v115
	s_nop 0
	v_add_f32_e32 v115, 1.0, v115
	v_rcp_f32_e32 v117, v115
	v_pk_mul_f32 v[104:105], v[104:105], v[114:115] op_sel_hi:[1,0]
	v_pk_mul_f32 v[106:107], v[106:107], v[114:115] op_sel_hi:[1,0]
	v_pk_mul_f32 v[98:99], v[98:99], v[114:115] op_sel_hi:[1,0]
	v_pk_mul_f32 v[110:111], v[110:111], v[116:117]
	v_pk_mul_f32 v[100:101], v[100:101], v[114:115] op_sel_hi:[1,0]
	v_pk_mul_f32 v[102:103], v[102:103], v[110:111]
	v_pk_mul_f32 v[110:111], v[112:113], v[114:115] op_sel_hi:[1,0]
	s_nop 0
	v_mul_f32_e32 v112, 0xbfb8aa3b, v110
	v_mul_f32_e32 v113, 0xbfb8aa3b, v111
	v_exp_f32_e32 v112, v112
	v_exp_f32_e32 v113, v113
	v_add_f32_e32 v112, 1.0, v112
	v_add_f32_e32 v113, 1.0, v113
	v_rcp_f32_e32 v112, v112
	v_rcp_f32_e32 v113, v113
	s_nop 0
	v_pk_mul_f32 v[110:111], v[110:111], v[112:113]
	s_nop 0
	v_pk_mul_f32 v[104:105], v[104:105], v[110:111]
	v_mul_f32_e32 v110, 0xbfb8aa3b, v106
	v_mul_f32_e32 v111, 0xbfb8aa3b, v107
	v_exp_f32_e32 v110, v110
	v_exp_f32_e32 v111, v111
	v_add_f32_e32 v110, 1.0, v110
	v_add_f32_e32 v111, 1.0, v111
	v_rcp_f32_e32 v110, v110
	v_rcp_f32_e32 v111, v111
	s_nop 0
	v_pk_mul_f32 v[106:107], v[106:107], v[110:111]
	s_nop 0
	v_pk_mul_f32 v[106:107], v[98:99], v[106:107]
	v_pk_mul_f32 v[98:99], v[108:109], v[114:115] op_sel_hi:[1,0]
	s_nop 0
	v_mul_f32_e32 v108, 0xbfb8aa3b, v98
	v_mul_f32_e32 v109, 0xbfb8aa3b, v99
	v_exp_f32_e32 v108, v108
	v_exp_f32_e32 v109, v109
	v_add_f32_e32 v108, 1.0, v108
	v_add_f32_e32 v109, 1.0, v109
	v_rcp_f32_e32 v108, v108
	v_rcp_f32_e32 v109, v109
	s_nop 0
	v_pk_mul_f32 v[98:99], v[98:99], v[108:109]
	s_nop 0
	v_pk_mul_f32 v[108:109], v[100:101], v[98:99]
	v_cvt_pk_bf16_f32 v98, v102, v103
	v_add_u32_e32 v102, 0xb000, v118
	v_mov_b32_e32 v103, v81
	v_cvt_pk_bf16_f32 v99, v104, v105
	v_cvt_pk_bf16_f32 v100, v106, v107
	v_cvt_pk_bf16_f32 v101, v108, v109
	v_lshl_add_u64 v[102:103], v[102:103], 1, s[8:9]
	global_store_dwordx4 v[102:103], v[98:101], off
	s_nop 1
	v_add_u32_e32 v98, 32, v80
	v_mov_b32_e32 v99, v81
	v_lshl_add_u64 v[98:99], v[98:99], 2, s[10:11]
	global_load_dword v251, v[252:253], off offset:192
	s_waitcnt vmcnt(2)
; __device__ __forceinline__ unsigned pk2(float lo, float hi) { f32x2_t v = {lo, hi}; bf16x2_t b = __builtin_convertvector(v, bf16x2_t); return __builtin_bit_cast(unsigned, b); }
; __device__ __forceinline__ float sigmoidf_(float x) { return __builtin_amdgcn_rcpf(1.0f + __expf(-x)); }
;     __device__ __forceinline__ void operator()(const f32x4 (&acc)[2][2][4][2], const pg8::Unit& u, int wr, int wc, int fr_, int fq_) const {
;     ...
;             for (int m = 0; m < 4; ++m) { const unsigned row = (unsigned)(u.pm * 256 + 128 * ai + 64 * wr + 16 * m + fr);
;                 float v[8]; const float rs = __builtin_amdgcn_rsqf(ssq[row] * (1.0f / DM) + 1e-6f);
; #pragma unroll
;                 for (int n = 0; n < 2; ++n)
; #pragma unroll
;                     for (int e = 0; e < 4; ++e) { const float g = acc[ai][0][m][n][e] * rs, up = acc[ai][1][m][n][e] * rs; v[4 * n + e] = g * sigmoidf_(g) * up; }
;                 u32x4 w; w.x = pk2(v[0], v[1]); w.y = pk2(v[2], v[3]); w.z = pk2(v[4], v[5]); w.w = pk2(v[6], v[7]);
;                 *(u32x4*)(act + (row * 2816u + (unsigned)(u.pn * 128 + 32 * wc + 8 * fq))) = w; }
	v_mov_b32_e32 v98, v250
	v_fmamk_f32 v98, v98, 0x3a800000, v147
	v_rsq_f32_e32 v98, v98
	s_nop 0
	v_pk_mul_f32 v[94:95], v[94:95], v[98:99] op_sel_hi:[1,0]
	s_nop 0
	v_mul_f32_e32 v99, 0xbfb8aa3b, v94
	v_exp_f32_e32 v99, v99
	s_nop 0
	v_add_f32_e32 v99, 1.0, v99
	v_rcp_f32_e32 v100, v99
	v_pk_mul_f32 v[86:87], v[86:87], v[98:99] op_sel_hi:[1,0]
	v_mul_f32_e32 v99, 0xbfb8aa3b, v95
	v_exp_f32_e32 v99, v99
	s_nop 0
	v_add_f32_e32 v99, 1.0, v99
	v_rcp_f32_e32 v101, v99
	v_pk_mul_f32 v[88:89], v[88:89], v[98:99] op_sel_hi:[1,0]
	v_pk_mul_f32 v[90:91], v[90:91], v[98:99] op_sel_hi:[1,0]
	v_pk_mul_f32 v[82:83], v[82:83], v[98:99] op_sel_hi:[1,0]
	v_pk_mul_f32 v[94:95], v[94:95], v[100:101]
	v_pk_mul_f32 v[84:85], v[84:85], v[98:99] op_sel_hi:[1,0]
	v_pk_mul_f32 v[86:87], v[86:87], v[94:95]
	v_pk_mul_f32 v[94:95], v[96:97], v[98:99] op_sel_hi:[1,0]
	s_nop 0
	v_mul_f32_e32 v96, 0xbfb8aa3b, v94
	v_mul_f32_e32 v97, 0xbfb8aa3b, v95
	v_exp_f32_e32 v96, v96
	v_exp_f32_e32 v97, v97
	v_add_f32_e32 v96, 1.0, v96
	v_add_f32_e32 v97, 1.0, v97
	v_rcp_f32_e32 v96, v96
	v_rcp_f32_e32 v97, v97
	s_nop 0
	v_pk_mul_f32 v[94:95], v[94:95], v[96:97]
	s_nop 0
	v_pk_mul_f32 v[88:89], v[88:89], v[94:95]
	v_mul_f32_e32 v94, 0xbfb8aa3b, v90
	v_mul_f32_e32 v95, 0xbfb8aa3b, v91
	v_exp_f32_e32 v94, v94
	v_exp_f32_e32 v95, v95
	v_add_f32_e32 v94, 1.0, v94
	v_add_f32_e32 v95, 1.0, v95
	v_rcp_f32_e32 v94, v94
	v_rcp_f32_e32 v95, v95
	s_nop 0
	v_pk_mul_f32 v[90:91], v[90:91], v[94:95]
	s_nop 0
	v_pk_mul_f32 v[90:91], v[82:83], v[90:91]
	v_pk_mul_f32 v[82:83], v[92:93], v[98:99] op_sel_hi:[1,0]
	s_nop 0
	v_mul_f32_e32 v92, 0xbfb8aa3b, v82
	v_mul_f32_e32 v93, 0xbfb8aa3b, v83
	v_exp_f32_e32 v92, v92
	v_exp_f32_e32 v93, v93
	v_add_f32_e32 v92, 1.0, v92
	v_add_f32_e32 v93, 1.0, v93
	v_rcp_f32_e32 v92, v92
	v_rcp_f32_e32 v93, v93
	s_nop 0
	v_pk_mul_f32 v[82:83], v[82:83], v[92:93]
	s_nop 0
	v_pk_mul_f32 v[92:93], v[84:85], v[82:83]
	v_cvt_pk_bf16_f32 v82, v86, v87
	v_add_u32_e32 v86, 0x16000, v118
	v_mov_b32_e32 v87, v81
	v_cvt_pk_bf16_f32 v83, v88, v89
	v_cvt_pk_bf16_f32 v84, v90, v91
	v_cvt_pk_bf16_f32 v85, v92, v93
	v_lshl_add_u64 v[86:87], v[86:87], 1, s[8:9]
	global_store_dwordx4 v[86:87], v[82:85], off
	s_nop 1
	v_add_u32_e32 v82, 48, v80
	v_mov_b32_e32 v83, v81
	v_lshl_add_u64 v[82:83], v[82:83], 2, s[10:11]
	global_load_dword v250, v[252:253], off offset:512
	s_waitcnt vmcnt(2)
	v_mov_b32_e32 v82, v251
	v_fmamk_f32 v82, v82, 0x3a800000, v147
	v_rsq_f32_e32 v82, v82
	s_nop 0
	v_pk_mul_f32 v[76:77], v[76:77], v[82:83] op_sel_hi:[1,0]
	s_nop 0
	v_mul_f32_e32 v83, 0xbfb8aa3b, v76
	v_exp_f32_e32 v83, v83
	s_nop 0
	v_add_f32_e32 v83, 1.0, v83
	v_rcp_f32_e32 v84, v83
	v_pk_mul_f32 v[68:69], v[68:69], v[82:83] op_sel_hi:[1,0]
	v_mul_f32_e32 v83, 0xbfb8aa3b, v77
	v_exp_f32_e32 v83, v83
	s_nop 0
	v_add_f32_e32 v83, 1.0, v83
	v_rcp_f32_e32 v85, v83
	v_pk_mul_f32 v[70:71], v[70:71], v[82:83] op_sel_hi:[1,0]
	v_pk_mul_f32 v[72:73], v[72:73], v[82:83] op_sel_hi:[1,0]
	v_pk_mul_f32 v[64:65], v[64:65], v[82:83] op_sel_hi:[1,0]
	v_pk_mul_f32 v[76:77], v[76:77], v[84:85]
	v_pk_mul_f32 v[66:67], v[66:67], v[82:83] op_sel_hi:[1,0]
	v_pk_mul_f32 v[68:69], v[68:69], v[76:77]
	v_pk_mul_f32 v[76:77], v[78:79], v[82:83] op_sel_hi:[1,0]
	s_nop 0
	v_mul_f32_e32 v78, 0xbfb8aa3b, v76
	v_mul_f32_e32 v79, 0xbfb8aa3b, v77
	v_exp_f32_e32 v78, v78
	v_exp_f32_e32 v79, v79
	v_add_f32_e32 v78, 1.0, v78
	v_add_f32_e32 v79, 1.0, v79
	v_rcp_f32_e32 v78, v78
	v_rcp_f32_e32 v79, v79
	s_nop 0
	v_pk_mul_f32 v[76:77], v[76:77], v[78:79]
	s_nop 0
	v_pk_mul_f32 v[70:71], v[70:71], v[76:77]
	v_mul_f32_e32 v76, 0xbfb8aa3b, v72
	v_mul_f32_e32 v77, 0xbfb8aa3b, v73
	v_exp_f32_e32 v76, v76
	v_exp_f32_e32 v77, v77
	v_add_f32_e32 v76, 1.0, v76
	v_add_f32_e32 v77, 1.0, v77
	v_rcp_f32_e32 v76, v76
	v_rcp_f32_e32 v77, v77
	s_nop 0
	v_pk_mul_f32 v[72:73], v[72:73], v[76:77]
	s_nop 0
	v_pk_mul_f32 v[72:73], v[64:65], v[72:73]
	v_pk_mul_f32 v[64:65], v[74:75], v[82:83] op_sel_hi:[1,0]
	s_nop 0
	v_mul_f32_e32 v74, 0xbfb8aa3b, v64
	v_mul_f32_e32 v75, 0xbfb8aa3b, v65
	v_exp_f32_e32 v74, v74
	v_exp_f32_e32 v75, v75
	v_add_f32_e32 v74, 1.0, v74
	v_add_f32_e32 v75, 1.0, v75
	v_rcp_f32_e32 v74, v74
	v_rcp_f32_e32 v75, v75
	s_nop 0
	v_pk_mul_f32 v[64:65], v[64:65], v[74:75]
	s_nop 0
	v_pk_mul_f32 v[74:75], v[66:67], v[64:65]
	v_cvt_pk_bf16_f32 v64, v68, v69
	v_add_u32_e32 v68, 0x21000, v118
	v_mov_b32_e32 v69, v81
	v_cvt_pk_bf16_f32 v65, v70, v71
	v_cvt_pk_bf16_f32 v66, v72, v73
	v_cvt_pk_bf16_f32 v67, v74, v75
	v_lshl_add_u64 v[68:69], v[68:69], 1, s[8:9]
	global_store_dwordx4 v[68:69], v[64:67], off
	s_nop 1
	v_add_u32_e32 v64, 0x80, v80
	v_mov_b32_e32 v65, v81
	v_lshl_add_u64 v[64:65], v[64:65], 2, s[10:11]
	global_load_dword v251, v[252:253], off offset:576
	s_waitcnt vmcnt(2)
; __device__ __forceinline__ unsigned pk2(float lo, float hi) { f32x2_t v = {lo, hi}; bf16x2_t b = __builtin_convertvector(v, bf16x2_t); return __builtin_bit_cast(unsigned, b); }
; __device__ __forceinline__ float sigmoidf_(float x) { return __builtin_amdgcn_rcpf(1.0f + __expf(-x)); }
;     __device__ __forceinline__ void operator()(const f32x4 (&acc)[2][2][4][2], const pg8::Unit& u, int wr, int wc, int fr_, int fq_) const {
;     ...
;             for (int m = 0; m < 4; ++m) { const unsigned row = (unsigned)(u.pm * 256 + 128 * ai + 64 * wr + 16 * m + fr);
;                 float v[8]; const float rs = __builtin_amdgcn_rsqf(ssq[row] * (1.0f / DM) + 1e-6f);
; #pragma unroll
;                 for (int n = 0; n < 2; ++n)
; #pragma unroll
;                     for (int e = 0; e < 4; ++e) { const float g = acc[ai][0][m][n][e] * rs, up = acc[ai][1][m][n][e] * rs; v[4 * n + e] = g * sigmoidf_(g) * up; }
;                 u32x4 w; w.x = pk2(v[0], v[1]); w.y = pk2(v[2], v[3]); w.z = pk2(v[4], v[5]); w.w = pk2(v[6], v[7]);
;                 *(u32x4*)(act + (row * 2816u + (unsigned)(u.pn * 128 + 32 * wc + 8 * fq))) = w; }
	v_mov_b32_e32 v64, v250
	v_fmamk_f32 v64, v64, 0x3a800000, v147
	v_rsq_f32_e32 v64, v64
	s_nop 0
	v_pk_mul_f32 v[60:61], v[60:61], v[64:65] op_sel_hi:[1,0]
	s_nop 0
	v_mul_f32_e32 v65, 0xbfb8aa3b, v60
	v_exp_f32_e32 v65, v65
	s_nop 0
	v_add_f32_e32 v65, 1.0, v65
	v_rcp_f32_e32 v66, v65
	v_pk_mul_f32 v[52:53], v[52:53], v[64:65] op_sel_hi:[1,0]
	v_mul_f32_e32 v65, 0xbfb8aa3b, v61
	v_exp_f32_e32 v65, v65
	s_nop 0
	v_add_f32_e32 v65, 1.0, v65
	v_rcp_f32_e32 v67, v65
	v_pk_mul_f32 v[54:55], v[54:55], v[64:65] op_sel_hi:[1,0]
	v_pk_mul_f32 v[56:57], v[56:57], v[64:65] op_sel_hi:[1,0]
	v_pk_mul_f32 v[48:49], v[48:49], v[64:65] op_sel_hi:[1,0]
	v_pk_mul_f32 v[60:61], v[60:61], v[66:67]
	v_pk_mul_f32 v[50:51], v[50:51], v[64:65] op_sel_hi:[1,0]
	v_pk_mul_f32 v[52:53], v[52:53], v[60:61]
	v_pk_mul_f32 v[60:61], v[62:63], v[64:65] op_sel_hi:[1,0]
	s_nop 0
	v_mul_f32_e32 v62, 0xbfb8aa3b, v60
	v_mul_f32_e32 v63, 0xbfb8aa3b, v61
	v_exp_f32_e32 v62, v62
	v_exp_f32_e32 v63, v63
	v_add_f32_e32 v62, 1.0, v62
	v_add_f32_e32 v63, 1.0, v63
	v_rcp_f32_e32 v62, v62
	v_rcp_f32_e32 v63, v63
	s_nop 0
	v_pk_mul_f32 v[60:61], v[60:61], v[62:63]
	s_nop 0
	v_pk_mul_f32 v[54:55], v[54:55], v[60:61]
	v_mul_f32_e32 v60, 0xbfb8aa3b, v56
	v_mul_f32_e32 v61, 0xbfb8aa3b, v57
	v_exp_f32_e32 v60, v60
	v_exp_f32_e32 v61, v61
	v_add_f32_e32 v60, 1.0, v60
	v_add_f32_e32 v61, 1.0, v61
	v_rcp_f32_e32 v60, v60
	v_rcp_f32_e32 v61, v61
	s_nop 0
	v_pk_mul_f32 v[56:57], v[56:57], v[60:61]
	s_nop 0
	v_pk_mul_f32 v[56:57], v[48:49], v[56:57]
	v_pk_mul_f32 v[48:49], v[58:59], v[64:65] op_sel_hi:[1,0]
	s_nop 0
	v_mul_f32_e32 v58, 0xbfb8aa3b, v48
	v_mul_f32_e32 v59, 0xbfb8aa3b, v49
	v_exp_f32_e32 v58, v58
	v_exp_f32_e32 v59, v59
	v_add_f32_e32 v58, 1.0, v58
	v_add_f32_e32 v59, 1.0, v59
	v_rcp_f32_e32 v58, v58
	v_rcp_f32_e32 v59, v59
	s_nop 0
	v_pk_mul_f32 v[48:49], v[48:49], v[58:59]
	s_nop 0
	v_pk_mul_f32 v[58:59], v[50:51], v[48:49]
	v_cvt_pk_bf16_f32 v48, v52, v53
	v_add_u32_e32 v52, 0x58000, v118
	v_mov_b32_e32 v53, v81
	v_cvt_pk_bf16_f32 v49, v54, v55
	v_cvt_pk_bf16_f32 v50, v56, v57
	v_cvt_pk_bf16_f32 v51, v58, v59
	v_lshl_add_u64 v[52:53], v[52:53], 1, s[8:9]
	global_store_dwordx4 v[52:53], v[48:51], off
	s_nop 1
	v_add_u32_e32 v48, 0x90, v80
	v_mov_b32_e32 v49, v81
	v_lshl_add_u64 v[48:49], v[48:49], 2, s[10:11]
	global_load_dword v250, v[252:253], off offset:640
	s_waitcnt vmcnt(2)
	v_mov_b32_e32 v48, v251
	v_fmamk_f32 v48, v48, 0x3a800000, v147
	v_rsq_f32_e32 v48, v48
	s_nop 0
	v_pk_mul_f32 v[44:45], v[44:45], v[48:49] op_sel_hi:[1,0]
	s_nop 0
	v_mul_f32_e32 v49, 0xbfb8aa3b, v44
	v_exp_f32_e32 v49, v49
	s_nop 0
	v_add_f32_e32 v49, 1.0, v49
	v_rcp_f32_e32 v50, v49
	v_pk_mul_f32 v[36:37], v[36:37], v[48:49] op_sel_hi:[1,0]
	v_mul_f32_e32 v49, 0xbfb8aa3b, v45
	v_exp_f32_e32 v49, v49
	s_nop 0
	v_add_f32_e32 v49, 1.0, v49
	v_rcp_f32_e32 v51, v49
	v_pk_mul_f32 v[38:39], v[38:39], v[48:49] op_sel_hi:[1,0]
	v_pk_mul_f32 v[40:41], v[40:41], v[48:49] op_sel_hi:[1,0]
	v_pk_mul_f32 v[32:33], v[32:33], v[48:49] op_sel_hi:[1,0]
	v_pk_mul_f32 v[44:45], v[44:45], v[50:51]
	v_pk_mul_f32 v[34:35], v[34:35], v[48:49] op_sel_hi:[1,0]
	v_pk_mul_f32 v[36:37], v[36:37], v[44:45]
	v_pk_mul_f32 v[44:45], v[46:47], v[48:49] op_sel_hi:[1,0]
	s_nop 0
	v_mul_f32_e32 v46, 0xbfb8aa3b, v44
	v_mul_f32_e32 v47, 0xbfb8aa3b, v45
	v_exp_f32_e32 v46, v46
	v_exp_f32_e32 v47, v47
	v_add_f32_e32 v46, 1.0, v46
	v_add_f32_e32 v47, 1.0, v47
	v_rcp_f32_e32 v46, v46
	v_rcp_f32_e32 v47, v47
	s_nop 0
	v_pk_mul_f32 v[44:45], v[44:45], v[46:47]
	s_nop 0
	v_pk_mul_f32 v[38:39], v[38:39], v[44:45]
	v_mul_f32_e32 v44, 0xbfb8aa3b, v40
	v_mul_f32_e32 v45, 0xbfb8aa3b, v41
	v_exp_f32_e32 v44, v44
	v_exp_f32_e32 v45, v45
	v_add_f32_e32 v44, 1.0, v44
	v_add_f32_e32 v45, 1.0, v45
	v_rcp_f32_e32 v44, v44
	v_rcp_f32_e32 v45, v45
	s_nop 0
	v_pk_mul_f32 v[40:41], v[40:41], v[44:45]
	s_nop 0
	v_pk_mul_f32 v[40:41], v[32:33], v[40:41]
	v_pk_mul_f32 v[32:33], v[42:43], v[48:49] op_sel_hi:[1,0]
	s_nop 0
	v_mul_f32_e32 v42, 0xbfb8aa3b, v32
	v_mul_f32_e32 v43, 0xbfb8aa3b, v33
	v_exp_f32_e32 v42, v42
	v_exp_f32_e32 v43, v43
	v_add_f32_e32 v42, 1.0, v42
	v_add_f32_e32 v43, 1.0, v43
	v_rcp_f32_e32 v42, v42
	v_rcp_f32_e32 v43, v43
	s_nop 0
	v_pk_mul_f32 v[32:33], v[32:33], v[42:43]
	s_nop 0
	v_pk_mul_f32 v[42:43], v[34:35], v[32:33]
	v_cvt_pk_bf16_f32 v32, v36, v37
	v_add_u32_e32 v36, 0x63000, v118
	v_mov_b32_e32 v37, v81
	v_cvt_pk_bf16_f32 v33, v38, v39
	v_cvt_pk_bf16_f32 v34, v40, v41
	v_cvt_pk_bf16_f32 v35, v42, v43
	v_lshl_add_u64 v[36:37], v[36:37], 1, s[8:9]
	global_store_dwordx4 v[36:37], v[32:35], off
	s_nop 1
	v_add_u32_e32 v32, 0xa0, v80
	v_mov_b32_e32 v33, v81
	v_lshl_add_u64 v[32:33], v[32:33], 2, s[10:11]
	global_load_dword v251, v[252:253], off offset:704
	v_add_u32_e32 v80, 0xb0, v80
	s_waitcnt vmcnt(2)
; __device__ __forceinline__ unsigned pk2(float lo, float hi) { f32x2_t v = {lo, hi}; bf16x2_t b = __builtin_convertvector(v, bf16x2_t); return __builtin_bit_cast(unsigned, b); }
; __device__ __forceinline__ float sigmoidf_(float x) { return __builtin_amdgcn_rcpf(1.0f + __expf(-x)); }
;     __device__ __forceinline__ void operator()(const f32x4 (&acc)[2][2][4][2], const pg8::Unit& u, int wr, int wc, int fr_, int fq_) const {
;     ...
;             for (int m = 0; m < 4; ++m) { const unsigned row = (unsigned)(u.pm * 256 + 128 * ai + 64 * wr + 16 * m + fr);
;                 float v[8]; const float rs = __builtin_amdgcn_rsqf(ssq[row] * (1.0f / DM) + 1e-6f);
; #pragma unroll
;                 for (int n = 0; n < 2; ++n)
; #pragma unroll
;                     for (int e = 0; e < 4; ++e) { const float g = acc[ai][0][m][n][e] * rs, up = acc[ai][1][m][n][e] * rs; v[4 * n + e] = g * sigmoidf_(g) * up; }
;                 u32x4 w; w.x = pk2(v[0], v[1]); w.y = pk2(v[2], v[3]); w.z = pk2(v[4], v[5]); w.w = pk2(v[6], v[7]);
;                 *(u32x4*)(act + (row * 2816u + (unsigned)(u.pn * 128 + 32 * wc + 8 * fq))) = w; }
	v_mov_b32_e32 v32, v250
	v_fmamk_f32 v32, v32, 0x3a800000, v147
	v_rsq_f32_e32 v32, v32
	s_nop 0
	v_pk_mul_f32 v[28:29], v[28:29], v[32:33] op_sel_hi:[1,0]
	s_nop 0
	v_mul_f32_e32 v33, 0xbfb8aa3b, v28
	v_exp_f32_e32 v33, v33
	s_nop 0
	v_add_f32_e32 v33, 1.0, v33
	v_rcp_f32_e32 v34, v33
	v_pk_mul_f32 v[20:21], v[20:21], v[32:33] op_sel_hi:[1,0]
	v_mul_f32_e32 v33, 0xbfb8aa3b, v29
	v_exp_f32_e32 v33, v33
	s_nop 0
	v_add_f32_e32 v33, 1.0, v33
	v_rcp_f32_e32 v35, v33
	v_pk_mul_f32 v[22:23], v[22:23], v[32:33] op_sel_hi:[1,0]
	v_pk_mul_f32 v[24:25], v[24:25], v[32:33] op_sel_hi:[1,0]
	v_pk_mul_f32 v[16:17], v[16:17], v[32:33] op_sel_hi:[1,0]
	v_pk_mul_f32 v[28:29], v[28:29], v[34:35]
	v_pk_mul_f32 v[18:19], v[18:19], v[32:33] op_sel_hi:[1,0]
	v_pk_mul_f32 v[20:21], v[20:21], v[28:29]
	v_pk_mul_f32 v[28:29], v[30:31], v[32:33] op_sel_hi:[1,0]
	s_nop 0
	v_mul_f32_e32 v30, 0xbfb8aa3b, v28
	v_mul_f32_e32 v31, 0xbfb8aa3b, v29
	v_exp_f32_e32 v30, v30
	v_exp_f32_e32 v31, v31
	v_add_f32_e32 v30, 1.0, v30
	v_add_f32_e32 v31, 1.0, v31
	v_rcp_f32_e32 v30, v30
	v_rcp_f32_e32 v31, v31
	s_nop 0
	v_pk_mul_f32 v[28:29], v[28:29], v[30:31]
	s_nop 0
	v_pk_mul_f32 v[22:23], v[22:23], v[28:29]
	v_mul_f32_e32 v28, 0xbfb8aa3b, v24
	v_mul_f32_e32 v29, 0xbfb8aa3b, v25
	v_exp_f32_e32 v28, v28
	v_exp_f32_e32 v29, v29
	v_add_f32_e32 v28, 1.0, v28
	v_add_f32_e32 v29, 1.0, v29
	v_rcp_f32_e32 v28, v28
	v_rcp_f32_e32 v29, v29
	s_nop 0
	v_pk_mul_f32 v[24:25], v[24:25], v[28:29]
	s_nop 0
	v_pk_mul_f32 v[24:25], v[16:17], v[24:25]
	v_pk_mul_f32 v[16:17], v[26:27], v[32:33] op_sel_hi:[1,0]
	s_nop 0
	v_mul_f32_e32 v26, 0xbfb8aa3b, v16
	v_mul_f32_e32 v27, 0xbfb8aa3b, v17
	v_exp_f32_e32 v26, v26
	v_exp_f32_e32 v27, v27
	v_add_f32_e32 v26, 1.0, v26
	v_add_f32_e32 v27, 1.0, v27
	v_rcp_f32_e32 v26, v26
	v_rcp_f32_e32 v27, v27
	s_nop 0
	v_pk_mul_f32 v[16:17], v[16:17], v[26:27]
	s_nop 0
	v_pk_mul_f32 v[26:27], v[18:19], v[16:17]
	v_cvt_pk_bf16_f32 v16, v20, v21
	v_add_u32_e32 v20, 0x6e000, v118
	v_mov_b32_e32 v21, v81
	v_cvt_pk_bf16_f32 v17, v22, v23
	v_cvt_pk_bf16_f32 v18, v24, v25
	v_cvt_pk_bf16_f32 v19, v26, v27
	v_lshl_add_u64 v[20:21], v[20:21], 1, s[8:9]
	global_store_dwordx4 v[20:21], v[16:19], off
	s_nop 1
	v_lshl_add_u64 v[16:17], v[80:81], 2, s[10:11]
	v_add_u32_e32 v80, 0x79000, v118
	s_waitcnt vmcnt(1)
	v_mov_b32_e32 v16, v251
	v_fmamk_f32 v16, v16, 0x3a800000, v147
	v_rsq_f32_e32 v16, v16
	s_nop 0
	v_pk_mul_f32 v[12:13], v[12:13], v[16:17] op_sel_hi:[1,0]
	s_nop 0
	v_mul_f32_e32 v17, 0xbfb8aa3b, v12
	v_exp_f32_e32 v17, v17
	s_nop 0
	v_add_f32_e32 v17, 1.0, v17
	v_rcp_f32_e32 v18, v17
	v_pk_mul_f32 v[4:5], v[4:5], v[16:17] op_sel_hi:[1,0]
	v_mul_f32_e32 v17, 0xbfb8aa3b, v13
	v_exp_f32_e32 v17, v17
	s_nop 0
	v_add_f32_e32 v17, 1.0, v17
	v_rcp_f32_e32 v19, v17
	v_pk_mul_f32 v[6:7], v[6:7], v[16:17] op_sel_hi:[1,0]
	v_pk_mul_f32 v[8:9], v[8:9], v[16:17] op_sel_hi:[1,0]
	v_pk_mul_f32 v[0:1], v[0:1], v[16:17] op_sel_hi:[1,0]
	v_pk_mul_f32 v[12:13], v[12:13], v[18:19]
	v_pk_mul_f32 v[2:3], v[2:3], v[16:17] op_sel_hi:[1,0]
	v_pk_mul_f32 v[4:5], v[4:5], v[12:13]
	v_pk_mul_f32 v[12:13], v[14:15], v[16:17] op_sel_hi:[1,0]
	s_nop 0
	v_mul_f32_e32 v14, 0xbfb8aa3b, v12
	v_mul_f32_e32 v15, 0xbfb8aa3b, v13
	v_exp_f32_e32 v14, v14
	v_exp_f32_e32 v15, v15
	v_add_f32_e32 v14, 1.0, v14
	v_add_f32_e32 v15, 1.0, v15
	v_rcp_f32_e32 v14, v14
	v_rcp_f32_e32 v15, v15
	s_nop 0
	v_pk_mul_f32 v[12:13], v[12:13], v[14:15]
	s_nop 0
	v_pk_mul_f32 v[6:7], v[6:7], v[12:13]
	v_mul_f32_e32 v12, 0xbfb8aa3b, v8
	v_mul_f32_e32 v13, 0xbfb8aa3b, v9
	v_exp_f32_e32 v12, v12
	v_exp_f32_e32 v13, v13
	v_add_f32_e32 v12, 1.0, v12
	v_add_f32_e32 v13, 1.0, v13
	v_rcp_f32_e32 v12, v12
	v_rcp_f32_e32 v13, v13
	s_nop 0
	v_pk_mul_f32 v[8:9], v[8:9], v[12:13]
	s_nop 0
	v_pk_mul_f32 v[8:9], v[0:1], v[8:9]
	v_pk_mul_f32 v[0:1], v[10:11], v[16:17] op_sel_hi:[1,0]
	s_nop 0
	v_mul_f32_e32 v10, 0xbfb8aa3b, v0
	v_mul_f32_e32 v11, 0xbfb8aa3b, v1
	v_exp_f32_e32 v10, v10
	v_exp_f32_e32 v11, v11
	v_add_f32_e32 v10, 1.0, v10
	v_add_f32_e32 v11, 1.0, v11
	v_rcp_f32_e32 v10, v10
	v_rcp_f32_e32 v11, v11
	s_nop 0
	v_pk_mul_f32 v[0:1], v[0:1], v[10:11]
	s_nop 0
	v_pk_mul_f32 v[10:11], v[2:3], v[0:1]
	v_cvt_pk_bf16_f32 v0, v4, v5
	v_cvt_pk_bf16_f32 v1, v6, v7
	v_cvt_pk_bf16_f32 v2, v8, v9
	v_cvt_pk_bf16_f32 v3, v10, v11
	v_lshl_add_u64 v[4:5], v[80:81], 1, s[8:9]
	global_store_dwordx4 v[4:5], v[0:3], off
	s_cbranch_vccnz .LBB0_1208
	s_andn2_b64 vcc, exec, s[6:7]
	s_cbranch_vccnz .LBB0_1207
	s_barrier
	s_branch .LBB0_1207

;     __host__ __device__ bool next(int i, Unit& u) const {
;         const long L = (long)i * G + c; if (L >= nwg) return false;
;         int wgid = (int)L; { const int q = nwg / NXCD, r = nwg % NXCD, xcd = wgid % NXCD, off = wgid / NXCD; wgid = (xcd < r ? xcd * (q + 1) : r * (q + 1) + (xcd - r) * q) + off; }
;         const int nig = WGM * nN, gid = wgid / nig, fm = gid * WGM, gsz = (nM - fm) < WGM ? (nM - fm) : WGM;
;         u.pm = fm + ((wgid % nig) % gsz); u.pn = (wgid % nig) / gsz; return true;
; __global__ void __launch_bounds__(512, 2) hybrid_fwd(Params P) {
;     ...
;         { PHASE_BEGIN
;             pg8::Gemm g{(const bf16_t*)(ws + WS_A), (const bf16_t*)(ws + WS_WDN), MTOK, DM, DFF, DFF, DFF}; pg8::StaticOrder S; S.init(MTOK, DM, G, bx); if (L == 0) { EpiResNormBB E{(const bf16_t*)(ws + WS_H), (bf16_t*)POUT, (float*)(ws + WS_SMALL + 393216)};
;                 pg8::gemm_phase<EpiResNormBB, pg8::StaticOrder, true, true>(lds, g, S, E, tid); }
.LBB0_1229:
	s_nop 0
	s_nop 0
	s_nop 0
	s_nop 0
	s_nop 0
	s_nop 0
	s_or_b64 exec, exec, s[4:5]
	v_readlane_b32 s4, v255, 17
	s_mov_b64 s[12:13], s[58:59]
	s_barrier
	s_add_u32 s28, s12, 0x7100000
	s_addc_u32 s29, s13, 0
	s_add_u32 s30, s12, 0x1c00000
	s_addc_u32 s31, s13, 0
	s_add_u32 s8, s12, 0x3100000
	s_addc_u32 s9, s13, 0
	s_mov_b32 s26, s69
	s_mov_b32 s27, s2
	v_mov_b32_e32 v138, v146
	s_cmp_lg_u32 s4, 0
	s_cbranch_scc0 .LBB0_1257
	s_cmpk_gt_i32 s27, 0x1ff
	v_readfirstlane_b32 s6, v138
	s_cbranch_scc1 .LBB0_1259
	s_ashr_i32 s34, s27, 31
	s_lshr_b32 s4, s34, 29
	s_add_i32 s11, s27, s4
	s_and_b32 s4, s11, -8
	s_sub_i32 s7, s27, s4
	s_cmp_gt_i32 s7, -1
	s_mov_b64 s[4:5], -1
	s_cbranch_scc0 .LBB0_1233
	s_lshl_b32 s10, s7, 6
	s_mov_b64 s[4:5], 0

; __device__ __forceinline__ float bflo(unsigned w) { return __uint_as_float(w << 16); }
; __device__ __forceinline__ float bfhi(unsigned w) { return __uint_as_float(w & 0xffff0000u); }
;     __device__ __forceinline__ void operator()(const f32x4 (&acc)[2][2][4][2], const pg8::Unit& u, int wr, int wc, int fr_, int fq_) const {
;         int fr = fr_, fq = fq_; asm volatile("" : "+v"(fr), "+v"(fq));
; #pragma unroll
;         for (int ai = 0; ai < 2; ++ai)
; #pragma unroll
;             for (int m = 0; m < 4; ++m) { const unsigned row = (unsigned)(u.pm * 256 + 128 * ai + 64 * wr + 16 * m + fr);
; #pragma unroll
;                 for (int bj = 0; bj < 2; ++bj) { const unsigned o = row * 1024u + (unsigned)(u.pn * 256 + 64 * wc + 32 * bj + 8 * fq);
;                     const u32x4 rb = *(const u32x4*)(resb + o); const f32x4 a0 = acc[ai][bj][m][0], a1 = acc[ai][bj][m][1];
;                     f32x4 y0, y1; y0[0] = bflo(rb.x) + a0[0]; y0[1] = bfhi(rb.x) + a0[1]; y0[2] = bflo(rb.y) + a0[2]; y0[3] = bfhi(rb.y) + a0[3];
;                     y1[0] = bflo(rb.z) + a1[0]; y1[1] = bfhi(rb.z) + a1[1]; y1[2] = bflo(rb.w) + a1[2]; y1[3] = bfhi(rb.w) + a1[3];
;                     *(f32x4*)(out + o) = y0; *(f32x4*)(out + o + 4) = y1; }
;                 __builtin_amdgcn_sched_barrier(0); }
.LBB0_1254:
	v_mov_b32_e32 v80, v139
	v_mov_b32_e32 v143, v140
	s_lshl_b32 s18, s48, 8
	s_add_i32 s18, s18, s40
	s_lshl_b32 s19, s49, 8
	s_or_b32 s19, s19, s43
	v_lshlrev_b32_e32 v143, 3, v143
	v_add_lshl_u32 v80, s18, v80, 10
	v_add3_u32 v80, s19, v143, v80
	v_lshl_add_u64 v[144:145], v[80:81], 1, s[8:9]
	v_mov_b32_e32 v228, v144
	v_mov_b32_e32 v229, v145
	global_load_dwordx4 v[160:163], v[228:229], off offset:0
	global_load_dwordx4 v[172:175], v[228:229], off offset:64
	s_mov_b64 s[98:99], 0x8000
	v_lshl_add_u64 v[228:229], v[228:229], 0, s[98:99]
	global_load_dwordx4 v[176:179], v[228:229], off offset:0
	global_load_dwordx4 v[180:183], v[228:229], off offset:64
	s_mov_b64 s[98:99], 0x8000
	v_lshl_add_u64 v[228:229], v[228:229], 0, s[98:99]
	global_load_dwordx4 v[212:215], v[228:229], off offset:0
	global_load_dwordx4 v[216:219], v[228:229], off offset:64
	s_mov_b64 s[98:99], 0x8000
	v_lshl_add_u64 v[228:229], v[228:229], 0, s[98:99]
	global_load_dwordx4 v[220:223], v[228:229], off offset:0
	global_load_dwordx4 v[224:227], v[228:229], off offset:64
	s_waitcnt vmcnt(7)
	v_mov_b32_e32 v152, v160
	v_mov_b32_e32 v153, v161
	v_mov_b32_e32 v154, v162
	v_mov_b32_e32 v155, v163
	v_lshlrev_b32_e32 v144, 16, v152
	v_and_b32_e32 v145, 0xffff0000, v152
	v_pk_add_f32 v[126:127], v[126:127], v[144:145]
	v_lshlrev_b32_e32 v144, 16, v153
	v_and_b32_e32 v145, 0xffff0000, v153
	v_pk_add_f32 v[128:129], v[128:129], v[144:145]
	v_lshlrev_b32_e32 v144, 16, v154
	v_and_b32_e32 v145, 0xffff0000, v154
	v_pk_add_f32 v[122:123], v[122:123], v[144:145]
	v_lshlrev_b32_e32 v144, 16, v155
	v_and_b32_e32 v145, 0xffff0000, v155
	v_pk_add_f32 v[124:125], v[124:125], v[144:145]
	v_lshl_add_u64 v[144:145], v[80:81], 2, s[56:57]
	global_store_dwordx4 v[144:145], v[126:129], off
	global_store_dwordx4 v[144:145], v[122:125], off offset:16
	s_nop 0
	v_add_u32_e32 v126, 32, v80
	v_mov_b32_e32 v127, v81
	v_lshl_add_u64 v[122:123], v[126:127], 1, s[8:9]
	s_mov_b64 s[98:99], 0x28000
	v_lshl_add_u64 v[228:229], v[228:229], 0, s[98:99]
	global_load_dwordx4 v[160:163], v[228:229], off offset:0
	s_waitcnt vmcnt(9)
	v_mov_b32_e32 v122, v172
	v_mov_b32_e32 v123, v173
	v_mov_b32_e32 v124, v174
	v_mov_b32_e32 v125, v175
	v_lshlrev_b32_e32 v128, 16, v122
	v_and_b32_e32 v129, 0xffff0000, v122
	v_lshlrev_b32_e32 v122, 16, v123
	v_and_b32_e32 v123, 0xffff0000, v123
	v_pk_add_f32 v[120:121], v[120:121], v[122:123]
	v_lshlrev_b32_e32 v122, 16, v124
	v_and_b32_e32 v123, 0xffff0000, v124
	v_pk_add_f32 v[114:115], v[114:115], v[122:123]
	v_lshlrev_b32_e32 v122, 16, v125
	v_and_b32_e32 v123, 0xffff0000, v125
	v_pk_add_f32 v[118:119], v[118:119], v[128:129]
	v_pk_add_f32 v[116:117], v[116:117], v[122:123]
	v_lshl_add_u64 v[122:123], v[126:127], 2, s[56:57]
	global_store_dwordx4 v[122:123], v[118:121], off
	global_store_dwordx4 v[122:123], v[114:117], off offset:16
	s_nop 0
	v_add_u32_e32 v118, 0x4000, v80
	v_mov_b32_e32 v119, v81
	v_lshl_add_u64 v[114:115], v[118:119], 1, s[8:9]
	global_load_dwordx4 v[172:175], v[228:229], off offset:64
	s_waitcnt vmcnt(11)
	v_mov_b32_e32 v114, v176
	v_mov_b32_e32 v115, v177
	v_mov_b32_e32 v116, v178
	v_mov_b32_e32 v117, v179
	v_lshlrev_b32_e32 v120, 16, v114
	v_and_b32_e32 v121, 0xffff0000, v114
	v_lshlrev_b32_e32 v114, 16, v115
	v_and_b32_e32 v115, 0xffff0000, v115
	v_pk_add_f32 v[112:113], v[112:113], v[114:115]
	v_lshlrev_b32_e32 v114, 16, v116
	v_and_b32_e32 v115, 0xffff0000, v116
	v_pk_add_f32 v[106:107], v[106:107], v[114:115]
	v_lshlrev_b32_e32 v114, 16, v117
	v_and_b32_e32 v115, 0xffff0000, v117
	v_pk_add_f32 v[110:111], v[110:111], v[120:121]
	v_pk_add_f32 v[108:109], v[108:109], v[114:115]
	v_lshl_add_u64 v[114:115], v[118:119], 2, s[56:57]
	global_store_dwordx4 v[114:115], v[110:113], off
	global_store_dwordx4 v[114:115], v[106:109], off offset:16
	s_nop 0
	v_add_u32_e32 v110, 0x4020, v80
	v_mov_b32_e32 v111, v81
	v_lshl_add_u64 v[106:107], v[110:111], 1, s[8:9]
	s_mov_b64 s[98:99], 0x8000
	v_lshl_add_u64 v[228:229], v[228:229], 0, s[98:99]
	global_load_dwordx4 v[176:179], v[228:229], off offset:0
	s_waitcnt vmcnt(13)
	v_mov_b32_e32 v106, v180
	v_mov_b32_e32 v107, v181
	v_mov_b32_e32 v108, v182
	v_mov_b32_e32 v109, v183
	v_lshlrev_b32_e32 v112, 16, v106
	v_and_b32_e32 v113, 0xffff0000, v106
	v_lshlrev_b32_e32 v106, 16, v107
	v_and_b32_e32 v107, 0xffff0000, v107
	v_pk_add_f32 v[104:105], v[104:105], v[106:107]
	v_lshlrev_b32_e32 v106, 16, v108
	v_and_b32_e32 v107, 0xffff0000, v108
	v_pk_add_f32 v[98:99], v[98:99], v[106:107]
	v_lshlrev_b32_e32 v106, 16, v109
	v_and_b32_e32 v107, 0xffff0000, v109
	v_pk_add_f32 v[102:103], v[102:103], v[112:113]
	v_pk_add_f32 v[100:101], v[100:101], v[106:107]
	v_lshl_add_u64 v[106:107], v[110:111], 2, s[56:57]
	global_store_dwordx4 v[106:107], v[102:105], off
	global_store_dwordx4 v[106:107], v[98:101], off offset:16
	s_nop 0
	v_add_u32_e32 v102, 0x8000, v80
	v_mov_b32_e32 v103, v81
	v_lshl_add_u64 v[98:99], v[102:103], 1, s[8:9]
	global_load_dwordx4 v[180:183], v[228:229], off offset:64
	s_waitcnt vmcnt(15)
	v_mov_b32_e32 v98, v212
	v_mov_b32_e32 v99, v213
	v_mov_b32_e32 v100, v214
	v_mov_b32_e32 v101, v215
	v_lshlrev_b32_e32 v104, 16, v98
	v_and_b32_e32 v105, 0xffff0000, v98
	v_lshlrev_b32_e32 v98, 16, v99
	v_and_b32_e32 v99, 0xffff0000, v99
	v_pk_add_f32 v[96:97], v[96:97], v[98:99]
	v_lshlrev_b32_e32 v98, 16, v100
	v_and_b32_e32 v99, 0xffff0000, v100
	v_pk_add_f32 v[90:91], v[90:91], v[98:99]
	v_lshlrev_b32_e32 v98, 16, v101
	v_and_b32_e32 v99, 0xffff0000, v101
	v_pk_add_f32 v[94:95], v[94:95], v[104:105]
	v_pk_add_f32 v[92:93], v[92:93], v[98:99]
	v_lshl_add_u64 v[98:99], v[102:103], 2, s[56:57]
	global_store_dwordx4 v[98:99], v[94:97], off
	global_store_dwordx4 v[98:99], v[90:93], off offset:16
	s_nop 0
	v_add_u32_e32 v94, 0x8020, v80
	v_mov_b32_e32 v95, v81
	v_lshl_add_u64 v[90:91], v[94:95], 1, s[8:9]
	s_mov_b64 s[98:99], 0x8000
	v_lshl_add_u64 v[228:229], v[228:229], 0, s[98:99]
	global_load_dwordx4 v[212:215], v[228:229], off offset:0
	s_waitcnt vmcnt(17)
; __device__ __forceinline__ float bflo(unsigned w) { return __uint_as_float(w << 16); }
; __device__ __forceinline__ float bfhi(unsigned w) { return __uint_as_float(w & 0xffff0000u); }
;     __device__ __forceinline__ void operator()(const f32x4 (&acc)[2][2][4][2], const pg8::Unit& u, int wr, int wc, int fr_, int fq_) const {
;         int fr = fr_, fq = fq_; asm volatile("" : "+v"(fr), "+v"(fq));
; #pragma unroll
;         for (int ai = 0; ai < 2; ++ai)
; #pragma unroll
;             for (int m = 0; m < 4; ++m) { const unsigned row = (unsigned)(u.pm * 256 + 128 * ai + 64 * wr + 16 * m + fr);
; #pragma unroll
;                 for (int bj = 0; bj < 2; ++bj) { const unsigned o = row * 1024u + (unsigned)(u.pn * 256 + 64 * wc + 32 * bj + 8 * fq);
;                     const u32x4 rb = *(const u32x4*)(resb + o); const f32x4 a0 = acc[ai][bj][m][0], a1 = acc[ai][bj][m][1];
;                     f32x4 y0, y1; y0[0] = bflo(rb.x) + a0[0]; y0[1] = bfhi(rb.x) + a0[1]; y0[2] = bflo(rb.y) + a0[2]; y0[3] = bfhi(rb.y) + a0[3];
;                     y1[0] = bflo(rb.z) + a1[0]; y1[1] = bfhi(rb.z) + a1[1]; y1[2] = bflo(rb.w) + a1[2]; y1[3] = bfhi(rb.w) + a1[3];
;                     *(f32x4*)(out + o) = y0; *(f32x4*)(out + o + 4) = y1; }
;                 __builtin_amdgcn_sched_barrier(0); }
	v_mov_b32_e32 v90, v216
	v_mov_b32_e32 v91, v217
	v_mov_b32_e32 v92, v218
	v_mov_b32_e32 v93, v219
	v_lshlrev_b32_e32 v96, 16, v90
	v_and_b32_e32 v97, 0xffff0000, v90
	v_lshlrev_b32_e32 v90, 16, v91
	v_and_b32_e32 v91, 0xffff0000, v91
	v_pk_add_f32 v[88:89], v[88:89], v[90:91]
	v_lshlrev_b32_e32 v90, 16, v92
	v_and_b32_e32 v91, 0xffff0000, v92
	v_pk_add_f32 v[82:83], v[82:83], v[90:91]
	v_lshlrev_b32_e32 v90, 16, v93
	v_and_b32_e32 v91, 0xffff0000, v93
	v_pk_add_f32 v[86:87], v[86:87], v[96:97]
	v_pk_add_f32 v[84:85], v[84:85], v[90:91]
	v_lshl_add_u64 v[90:91], v[94:95], 2, s[56:57]
	global_store_dwordx4 v[90:91], v[86:89], off
	global_store_dwordx4 v[90:91], v[82:85], off offset:16
	s_nop 0
	v_add_u32_e32 v86, 0xc000, v80
	v_mov_b32_e32 v87, v81
	v_lshl_add_u64 v[82:83], v[86:87], 1, s[8:9]
	global_load_dwordx4 v[216:219], v[228:229], off offset:64
	s_waitcnt vmcnt(19)
	v_mov_b32_e32 v82, v220
	v_mov_b32_e32 v83, v221
	v_mov_b32_e32 v84, v222
	v_mov_b32_e32 v85, v223
	v_lshlrev_b32_e32 v88, 16, v82
	v_and_b32_e32 v89, 0xffff0000, v82
	v_lshlrev_b32_e32 v82, 16, v83
	v_and_b32_e32 v83, 0xffff0000, v83
	v_pk_add_f32 v[78:79], v[78:79], v[82:83]
	v_lshlrev_b32_e32 v82, 16, v84
	v_and_b32_e32 v83, 0xffff0000, v84
	v_pk_add_f32 v[72:73], v[72:73], v[82:83]
	v_lshlrev_b32_e32 v82, 16, v85
	v_and_b32_e32 v83, 0xffff0000, v85
	v_pk_add_f32 v[76:77], v[76:77], v[88:89]
	v_pk_add_f32 v[74:75], v[74:75], v[82:83]
	v_lshl_add_u64 v[82:83], v[86:87], 2, s[56:57]
	global_store_dwordx4 v[82:83], v[76:79], off
	global_store_dwordx4 v[82:83], v[72:75], off offset:16
	s_nop 0
	v_add_u32_e32 v76, 0xc020, v80
	v_mov_b32_e32 v77, v81
	v_lshl_add_u64 v[72:73], v[76:77], 1, s[8:9]
	s_mov_b64 s[98:99], 0x8000
	v_lshl_add_u64 v[228:229], v[228:229], 0, s[98:99]
	global_load_dwordx4 v[220:223], v[228:229], off offset:0
	s_waitcnt vmcnt(21)
	v_mov_b32_e32 v72, v224
	v_mov_b32_e32 v73, v225
	v_mov_b32_e32 v74, v226
	v_mov_b32_e32 v75, v227
	v_lshlrev_b32_e32 v78, 16, v72
	v_and_b32_e32 v79, 0xffff0000, v72
	v_lshlrev_b32_e32 v72, 16, v73
	v_and_b32_e32 v73, 0xffff0000, v73
	v_pk_add_f32 v[70:71], v[70:71], v[72:73]
	v_lshlrev_b32_e32 v72, 16, v74
	v_and_b32_e32 v73, 0xffff0000, v74
	v_pk_add_f32 v[64:65], v[64:65], v[72:73]
	v_lshlrev_b32_e32 v72, 16, v75
	v_and_b32_e32 v73, 0xffff0000, v75
	v_pk_add_f32 v[68:69], v[68:69], v[78:79]
	v_pk_add_f32 v[66:67], v[66:67], v[72:73]
	v_lshl_add_u64 v[72:73], v[76:77], 2, s[56:57]
	global_store_dwordx4 v[72:73], v[68:71], off
	global_store_dwordx4 v[72:73], v[64:67], off offset:16
	s_nop 0
	v_add_u32_e32 v68, 0x20000, v80
	v_mov_b32_e32 v69, v81
	v_lshl_add_u64 v[64:65], v[68:69], 1, s[8:9]
	global_load_dwordx4 v[224:227], v[228:229], off offset:64
	s_waitcnt vmcnt(21)
	v_mov_b32_e32 v64, v160
	v_mov_b32_e32 v65, v161
	v_mov_b32_e32 v66, v162
	v_mov_b32_e32 v67, v163
	v_lshlrev_b32_e32 v70, 16, v64
	v_and_b32_e32 v71, 0xffff0000, v64
	v_lshlrev_b32_e32 v64, 16, v65
	v_and_b32_e32 v65, 0xffff0000, v65
	v_pk_add_f32 v[62:63], v[62:63], v[64:65]
	v_lshlrev_b32_e32 v64, 16, v66
	v_and_b32_e32 v65, 0xffff0000, v66
	v_pk_add_f32 v[56:57], v[56:57], v[64:65]
	v_lshlrev_b32_e32 v64, 16, v67
	v_and_b32_e32 v65, 0xffff0000, v67
	v_pk_add_f32 v[60:61], v[60:61], v[70:71]
	v_pk_add_f32 v[58:59], v[58:59], v[64:65]
	v_lshl_add_u64 v[64:65], v[68:69], 2, s[56:57]
	global_store_dwordx4 v[64:65], v[60:63], off
	global_store_dwordx4 v[64:65], v[56:59], off offset:16
	s_nop 0
	v_add_u32_e32 v60, 0x20020, v80
	v_mov_b32_e32 v61, v81
	v_lshl_add_u64 v[56:57], v[60:61], 1, s[8:9]
	s_waitcnt vmcnt(20)
	v_mov_b32_e32 v56, v172
	v_mov_b32_e32 v57, v173
	v_mov_b32_e32 v58, v174
	v_mov_b32_e32 v59, v175
	v_lshlrev_b32_e32 v62, 16, v56
	v_and_b32_e32 v63, 0xffff0000, v56
	v_lshlrev_b32_e32 v56, 16, v57
	v_and_b32_e32 v57, 0xffff0000, v57
	v_pk_add_f32 v[54:55], v[54:55], v[56:57]
	v_lshlrev_b32_e32 v56, 16, v58
	v_and_b32_e32 v57, 0xffff0000, v58
	v_pk_add_f32 v[48:49], v[48:49], v[56:57]
	v_lshlrev_b32_e32 v56, 16, v59
	v_and_b32_e32 v57, 0xffff0000, v59
	v_pk_add_f32 v[52:53], v[52:53], v[62:63]
	v_pk_add_f32 v[50:51], v[50:51], v[56:57]
	v_lshl_add_u64 v[56:57], v[60:61], 2, s[56:57]
	global_store_dwordx4 v[56:57], v[52:55], off
	global_store_dwordx4 v[56:57], v[48:51], off offset:16
	s_nop 0
	v_add_u32_e32 v52, 0x24000, v80
	v_mov_b32_e32 v53, v81
	v_lshl_add_u64 v[48:49], v[52:53], 1, s[8:9]
	s_waitcnt vmcnt(19)
; #define PG8_BAR __builtin_amdgcn_s_barrier()
; __device__ __forceinline__ float bflo(unsigned w) { return __uint_as_float(w << 16); }
; __device__ __forceinline__ float bfhi(unsigned w) { return __uint_as_float(w & 0xffff0000u); }
; template <class Epi, class Sched, bool ALIGN_EPI = false, bool SP2 = false>
; __device__ __forceinline__ void gemm_phase(PG8_LAS unsigned char* lds, const Gemm g, const Sched& S, const Epi& E, int tid_in) {
;     ...
;         if constexpr (ALIGN_EPI) { if (wr == 0) PG8_BAR; }
;         if constexpr (!Epi::AFTER_DRAIN) { E(acc, cur, wr, wc, fr, fq); S.done(cur); }
;         if (!has_next) break;
; #pragma unroll
;         for (int a = 0; a < 2; ++a)
; #pragma unroll
;             for (int b = 0; b < 2; ++b)
; #pragma unroll
;                 for (int m = 0; m < 4; ++m)
; #pragma unroll
;                     for (int n = 0; n < 2; ++n) acc[a][b][m][n] = (f32x4){0.f, 0.f, 0.f, 0.f};
;         cur = nxt; cA = nA; cB = nB; ++ui;
;         if constexpr (ALIGN_EPI) { if (wr == 1) PG8_BAR; }
;     }
;     __device__ __forceinline__ void operator()(const f32x4 (&acc)[2][2][4][2], const pg8::Unit& u, int wr, int wc, int fr_, int fq_) const {
;         int fr = fr_, fq = fq_; asm volatile("" : "+v"(fr), "+v"(fq));
; #pragma unroll
;         for (int ai = 0; ai < 2; ++ai)
; #pragma unroll
;             for (int m = 0; m < 4; ++m) { const unsigned row = (unsigned)(u.pm * 256 + 128 * ai + 64 * wr + 16 * m + fr);
; #pragma unroll
;                 for (int bj = 0; bj < 2; ++bj) { const unsigned o = row * 1024u + (unsigned)(u.pn * 256 + 64 * wc + 32 * bj + 8 * fq);
;                     const u32x4 rb = *(const u32x4*)(resb + o); const f32x4 a0 = acc[ai][bj][m][0], a1 = acc[ai][bj][m][1];
;                     f32x4 y0, y1; y0[0] = bflo(rb.x) + a0[0]; y0[1] = bfhi(rb.x) + a0[1]; y0[2] = bflo(rb.y) + a0[2]; y0[3] = bfhi(rb.y) + a0[3];
;                     y1[0] = bflo(rb.z) + a1[0]; y1[1] = bfhi(rb.z) + a1[1]; y1[2] = bflo(rb.w) + a1[2]; y1[3] = bfhi(rb.w) + a1[3];
;                     *(f32x4*)(out + o) = y0; *(f32x4*)(out + o + 4) = y1; }
;                 __builtin_amdgcn_sched_barrier(0); }
	v_mov_b32_e32 v48, v176
	v_mov_b32_e32 v49, v177
	v_mov_b32_e32 v50, v178
	v_mov_b32_e32 v51, v179
	v_lshlrev_b32_e32 v54, 16, v48
	v_and_b32_e32 v55, 0xffff0000, v48
	v_lshlrev_b32_e32 v48, 16, v49
	v_and_b32_e32 v49, 0xffff0000, v49
	v_pk_add_f32 v[46:47], v[46:47], v[48:49]
	v_lshlrev_b32_e32 v48, 16, v50
	v_and_b32_e32 v49, 0xffff0000, v50
	v_pk_add_f32 v[40:41], v[40:41], v[48:49]
	v_lshlrev_b32_e32 v48, 16, v51
	v_and_b32_e32 v49, 0xffff0000, v51
	v_pk_add_f32 v[44:45], v[44:45], v[54:55]
	v_pk_add_f32 v[42:43], v[42:43], v[48:49]
	v_lshl_add_u64 v[48:49], v[52:53], 2, s[56:57]
	global_store_dwordx4 v[48:49], v[44:47], off
	global_store_dwordx4 v[48:49], v[40:43], off offset:16
	s_nop 0
	v_add_u32_e32 v44, 0x24020, v80
	v_mov_b32_e32 v45, v81
	v_lshl_add_u64 v[40:41], v[44:45], 1, s[8:9]
	s_waitcnt vmcnt(18)
	v_mov_b32_e32 v40, v180
	v_mov_b32_e32 v41, v181
	v_mov_b32_e32 v42, v182
	v_mov_b32_e32 v43, v183
	v_lshlrev_b32_e32 v46, 16, v40
	v_and_b32_e32 v47, 0xffff0000, v40
	v_lshlrev_b32_e32 v40, 16, v41
	v_and_b32_e32 v41, 0xffff0000, v41
	v_pk_add_f32 v[38:39], v[38:39], v[40:41]
	v_lshlrev_b32_e32 v40, 16, v42
	v_and_b32_e32 v41, 0xffff0000, v42
	v_pk_add_f32 v[32:33], v[32:33], v[40:41]
	v_lshlrev_b32_e32 v40, 16, v43
	v_and_b32_e32 v41, 0xffff0000, v43
	v_pk_add_f32 v[36:37], v[36:37], v[46:47]
	v_pk_add_f32 v[34:35], v[34:35], v[40:41]
	v_lshl_add_u64 v[40:41], v[44:45], 2, s[56:57]
	global_store_dwordx4 v[40:41], v[36:39], off
	global_store_dwordx4 v[40:41], v[32:35], off offset:16
	s_nop 0
	v_add_u32_e32 v36, 0x28000, v80
	v_mov_b32_e32 v37, v81
	v_lshl_add_u64 v[32:33], v[36:37], 1, s[8:9]
	s_waitcnt vmcnt(17)
	v_mov_b32_e32 v32, v212
	v_mov_b32_e32 v33, v213
	v_mov_b32_e32 v34, v214
	v_mov_b32_e32 v35, v215
	v_lshlrev_b32_e32 v38, 16, v32
	v_and_b32_e32 v39, 0xffff0000, v32
	v_lshlrev_b32_e32 v32, 16, v33
	v_and_b32_e32 v33, 0xffff0000, v33
	v_pk_add_f32 v[30:31], v[30:31], v[32:33]
	v_lshlrev_b32_e32 v32, 16, v34
	v_and_b32_e32 v33, 0xffff0000, v34
	v_pk_add_f32 v[24:25], v[24:25], v[32:33]
	v_lshlrev_b32_e32 v32, 16, v35
	v_and_b32_e32 v33, 0xffff0000, v35
	v_pk_add_f32 v[28:29], v[28:29], v[38:39]
	v_pk_add_f32 v[26:27], v[26:27], v[32:33]
	v_lshl_add_u64 v[32:33], v[36:37], 2, s[56:57]
	global_store_dwordx4 v[32:33], v[28:31], off
	global_store_dwordx4 v[32:33], v[24:27], off offset:16
	s_nop 0
	v_add_u32_e32 v28, 0x28020, v80
	v_mov_b32_e32 v29, v81
	v_lshl_add_u64 v[24:25], v[28:29], 1, s[8:9]
	s_waitcnt vmcnt(16)
	v_mov_b32_e32 v24, v216
	v_mov_b32_e32 v25, v217
	v_mov_b32_e32 v26, v218
	v_mov_b32_e32 v27, v219
	v_lshlrev_b32_e32 v30, 16, v24
	v_and_b32_e32 v31, 0xffff0000, v24
	v_lshlrev_b32_e32 v24, 16, v25
	v_and_b32_e32 v25, 0xffff0000, v25
	v_pk_add_f32 v[22:23], v[22:23], v[24:25]
	v_lshlrev_b32_e32 v24, 16, v26
	v_and_b32_e32 v25, 0xffff0000, v26
	v_pk_add_f32 v[16:17], v[16:17], v[24:25]
	v_lshlrev_b32_e32 v24, 16, v27
	v_and_b32_e32 v25, 0xffff0000, v27
	v_pk_add_f32 v[20:21], v[20:21], v[30:31]
	v_pk_add_f32 v[18:19], v[18:19], v[24:25]
	v_lshl_add_u64 v[24:25], v[28:29], 2, s[56:57]
	global_store_dwordx4 v[24:25], v[20:23], off
	global_store_dwordx4 v[24:25], v[16:19], off offset:16
	s_nop 0
	v_add_u32_e32 v20, 0x2c000, v80
	v_mov_b32_e32 v21, v81
	v_lshl_add_u64 v[16:17], v[20:21], 1, s[8:9]
	v_add_u32_e32 v80, 0x2c020, v80
	s_waitcnt vmcnt(15)
	v_mov_b32_e32 v16, v220
	v_mov_b32_e32 v17, v221
	v_mov_b32_e32 v18, v222
	v_mov_b32_e32 v19, v223
	v_lshlrev_b32_e32 v22, 16, v16
	v_and_b32_e32 v23, 0xffff0000, v16
	v_lshlrev_b32_e32 v16, 16, v17
	v_and_b32_e32 v17, 0xffff0000, v17
	v_pk_add_f32 v[14:15], v[14:15], v[16:17]
	v_lshlrev_b32_e32 v16, 16, v18
	v_and_b32_e32 v17, 0xffff0000, v18
	v_pk_add_f32 v[8:9], v[8:9], v[16:17]
	v_lshlrev_b32_e32 v16, 16, v19
	v_and_b32_e32 v17, 0xffff0000, v19
	v_pk_add_f32 v[12:13], v[12:13], v[22:23]
	v_pk_add_f32 v[10:11], v[10:11], v[16:17]
	v_lshl_add_u64 v[16:17], v[20:21], 2, s[56:57]
	global_store_dwordx4 v[16:17], v[12:15], off
	global_store_dwordx4 v[16:17], v[8:11], off offset:16
	s_nop 1
	v_lshl_add_u64 v[8:9], v[80:81], 1, s[8:9]
	s_waitcnt vmcnt(14)
	v_mov_b32_e32 v8, v224
	v_mov_b32_e32 v9, v225
	v_mov_b32_e32 v10, v226
	v_mov_b32_e32 v11, v227
	v_lshlrev_b32_e32 v12, 16, v8
	v_and_b32_e32 v13, 0xffff0000, v8
	v_lshlrev_b32_e32 v8, 16, v9
	v_and_b32_e32 v9, 0xffff0000, v9
	v_pk_add_f32 v[6:7], v[6:7], v[8:9]
	v_lshlrev_b32_e32 v8, 16, v10
	v_and_b32_e32 v9, 0xffff0000, v10
	v_pk_add_f32 v[0:1], v[0:1], v[8:9]
	v_lshlrev_b32_e32 v8, 16, v11
	v_and_b32_e32 v9, 0xffff0000, v11
	v_pk_add_f32 v[4:5], v[4:5], v[12:13]
	v_pk_add_f32 v[2:3], v[2:3], v[8:9]
	v_lshl_add_u64 v[8:9], v[80:81], 2, s[56:57]
	global_store_dwordx4 v[8:9], v[4:7], off
	global_store_dwordx4 v[8:9], v[0:3], off offset:16
	s_and_b64 vcc, exec, s[4:5]
	s_mov_b64 s[4:5], -1
	s_cbranch_vccnz .LBB0_1239
	s_andn2_b64 vcc, exec, s[10:11]
	s_cbranch_vccnz .LBB0_1238
	s_barrier
	s_branch .LBB0_1238

;     __host__ __device__ bool next(int i, Unit& u) const {
;         const long L = (long)i * G + c; if (L >= nwg) return false;
;         int wgid = (int)L; { const int q = nwg / NXCD, r = nwg % NXCD, xcd = wgid % NXCD, off = wgid / NXCD; wgid = (xcd < r ? xcd * (q + 1) : r * (q + 1) + (xcd - r) * q) + off; }
;         const int nig = WGM * nN, gid = wgid / nig, fm = gid * WGM, gsz = (nM - fm) < WGM ? (nM - fm) : WGM;
;         u.pm = fm + ((wgid % nig) % gsz); u.pn = (wgid % nig) / gsz; return true;
; template <class Epi, class Sched, bool ALIGN_EPI = false, bool SP2 = false>
; __device__ __forceinline__ void gemm_phase(PG8_LAS unsigned char* lds, const Gemm g, const Sched& S, const Epi& E, int tid_in) {
;     ...
;         const bool has_next = S.next(ui + 1, nxt);
;         const char* nA = has_next ? (const char*)g.A + (size_t)nxt.pm * tstepA : cA; const char* nB = has_next ? (const char*)g.Bt + (size_t)nxt.pn * tstepB : cB;
.LBB0_1272:
	s_nop 0
	s_nop 0
	s_add_i32 s45, s45, 1
	s_mul_i32 s4, s45, s43
	s_mul_hi_u32 s5, s45, s26
	s_add_i32 s5, s5, s4
	s_mul_i32 s4, s45, s26
	s_add_u32 s4, s4, s27
	s_addc_u32 s5, s5, s44
	v_cmp_gt_i64_e32 vcc, s[4:5], v[150:151]
	v_cmp_lt_i64_e64 s[6:7], s[4:5], v[148:149]
	s_cbranch_vccnz .LBB0_1278
	s_ashr_i32 s5, s4, 31
	s_lshr_b32 s5, s5, 29
	s_add_i32 s16, s4, s5
	s_and_b32 s5, s16, -8
	s_sub_i32 s17, s4, s5
	s_cmp_gt_i32 s17, -1
	s_mov_b64 s[4:5], -1
	s_cbranch_scc0 .LBB0_1275
	s_lshl_b32 s22, s17, 6
	s_mov_b64 s[4:5], 0

; __device__ __forceinline__ unsigned pk2(float lo, float hi) { f32x2_t v = {lo, hi}; bf16x2_t b = __builtin_convertvector(v, bf16x2_t); return __builtin_bit_cast(unsigned, b); }
; __device__ __forceinline__ float bflo(unsigned w) { return __uint_as_float(w << 16); }
; __device__ __forceinline__ float bfhi(unsigned w) { return __uint_as_float(w & 0xffff0000u); }
;     __device__ __forceinline__ void operator()(const f32x4 (&acc)[2][2][4][2], const pg8::Unit& u, int wr, int wc, int fr_, int fq_) const {
;     ...
;             for (int m = 0; m < 4; ++m) { const unsigned row = (unsigned)(u.pm * 256 + 128 * ai + 64 * wr + 16 * m + fr); float ss = 0.f;
; #pragma unroll
;                 for (int bj = 0; bj < 2; ++bj) { const unsigned o = row * 1024u + (unsigned)(u.pn * 256 + 64 * wc + 32 * bj + 8 * fq);
;                     const u32x4 rb = *(const u32x4*)(resb + o); const f32x4 a0 = acc[ai][bj][m][0], a1 = acc[ai][bj][m][1];
;                     const float y0 = bflo(rb.x) + a0[0], y1 = bfhi(rb.x) + a0[1], y2 = bflo(rb.y) + a0[2], y3 = bfhi(rb.y) + a0[3];
;                     const float y4 = bflo(rb.z) + a1[0], y5 = bfhi(rb.z) + a1[1], y6 = bflo(rb.w) + a1[2], y7 = bfhi(rb.w) + a1[3];
;                     u32x4 w; w.x = pk2(y0, y1); w.y = pk2(y2, y3); w.z = pk2(y4, y5); w.w = pk2(y6, y7);
;                     *(u32x4*)(xb + o) = w;
;                     ss += (y0 * y0 + y1 * y1) + (y2 * y2 + y3 * y3) + (y4 * y4 + y5 * y5) + (y6 * y6 + y7 * y7); }
;                 ss += __shfl_xor(ss, 16); ss += __shfl_xor(ss, 32);
;                 if (fq == 0) atomicAdd(ssq + row, ss);
;                 __builtin_amdgcn_sched_barrier(0); }
.LBB0_1286:
	v_and_b32_e32 v144, 64, v195
	v_mov_b32_e32 v80, v140
	v_mov_b32_e32 v138, v141
	s_lshl_b32 s18, s49, 8
	v_xor_b32_e32 v139, 16, v195
	v_add_u32_e32 v144, 64, v144
	s_add_i32 s18, s18, s39
	v_cmp_lt_i32_e32 vcc, v139, v144
	v_add_u32_e32 v138, s18, v138
	s_lshl_b32 s18, s48, 8
	v_cndmask_b32_e32 v139, v195, v139, vcc
	s_or_b32 s18, s18, s42
	v_lshlrev_b32_e32 v145, 2, v139
	v_xor_b32_e32 v139, 32, v195
	v_lshl_add_u32 v152, v80, 3, s18
	v_cmp_lt_i32_e32 vcc, v139, v144
	s_nop 1
	v_cndmask_b32_e32 v139, v195, v139, vcc
	v_cmp_eq_u32_e32 vcc, 0, v80
	v_lshl_add_u32 v80, v138, 10, v152
	v_lshlrev_b64 v[158:159], 1, v[80:81]
	v_lshl_add_u64 v[154:155], s[8:9], 0, v[158:159]
	v_mov_b32_e32 v232, v154
	v_mov_b32_e32 v233, v155
	global_load_dwordx4 v[172:175], v[232:233], off offset:0
	global_load_dwordx4 v[176:179], v[232:233], off offset:64
	s_mov_b64 s[98:99], 0x8000
	v_lshl_add_u64 v[232:233], v[232:233], 0, s[98:99]
	global_load_dwordx4 v[180:183], v[232:233], off offset:0
	global_load_dwordx4 v[212:215], v[232:233], off offset:64
	s_mov_b64 s[98:99], 0x8000
	v_lshl_add_u64 v[232:233], v[232:233], 0, s[98:99]
	global_load_dwordx4 v[216:219], v[232:233], off offset:0
	global_load_dwordx4 v[220:223], v[232:233], off offset:64
	s_mov_b64 s[98:99], 0x8000
	v_lshl_add_u64 v[232:233], v[232:233], 0, s[98:99]
	global_load_dwordx4 v[224:227], v[232:233], off offset:0
	global_load_dwordx4 v[228:231], v[232:233], off offset:64
	v_lshl_add_u64 v[158:159], s[56:57], 0, v[158:159]
	v_add_u32_e32 v80, 32, v80
	v_lshlrev_b32_e32 v144, 2, v139
	s_waitcnt vmcnt(7)
	v_mov_b32_e32 v154, v172
	v_mov_b32_e32 v155, v173
	v_mov_b32_e32 v156, v174
	v_mov_b32_e32 v157, v175
	v_lshlrev_b32_e32 v160, 16, v154
	v_and_b32_e32 v161, 0xffff0000, v154
	v_lshlrev_b32_e32 v154, 16, v155
	v_and_b32_e32 v155, 0xffff0000, v155
	v_pk_add_f32 v[128:129], v[128:129], v[154:155]
	v_lshlrev_b32_e32 v154, 16, v156
	v_and_b32_e32 v155, 0xffff0000, v156
	v_pk_add_f32 v[154:155], v[122:123], v[154:155]
	v_lshlrev_b32_e32 v122, 16, v157
	v_and_b32_e32 v123, 0xffff0000, v157
	v_pk_add_f32 v[126:127], v[126:127], v[160:161]
	v_pk_add_f32 v[156:157], v[124:125], v[122:123]
	v_cvt_pk_bf16_f32 v122, v126, v127
	v_cvt_pk_bf16_f32 v123, v128, v129
	v_cvt_pk_bf16_f32 v124, v154, v155
	v_cvt_pk_bf16_f32 v125, v156, v157
	global_store_dwordx4 v[158:159], v[122:125], off
	v_lshlrev_b64 v[158:159], 1, v[80:81]
	s_nop 0
	v_pk_mul_f32 v[122:123], v[154:155], v[154:155]
	v_lshl_add_u64 v[154:155], s[8:9], 0, v[158:159]
	v_pk_mul_f32 v[124:125], v[126:127], v[126:127]
	v_pk_mul_f32 v[126:127], v[128:129], v[128:129]
	v_pk_mul_f32 v[128:129], v[156:157], v[156:157]
	s_mov_b64 s[98:99], 0x28000
	v_lshl_add_u64 v[232:233], v[232:233], 0, s[98:99]
	global_load_dwordx4 v[172:175], v[232:233], off offset:0
	v_lshl_add_u64 v[158:159], s[56:57], 0, v[158:159]
	v_add_f32_e32 v126, v126, v127
	v_add_f32_e32 v124, v124, v125
	v_add_f32_e32 v124, v124, v126
	v_add_f32_e32 v122, v122, v123
	v_add_f32_e32 v80, v128, v129
	v_add_f32_e32 v122, v122, v124
	v_add_f32_e32 v80, v80, v122
	s_waitcnt vmcnt(8)
	v_mov_b32_e32 v154, v176
	v_mov_b32_e32 v155, v177
	v_mov_b32_e32 v156, v178
	v_mov_b32_e32 v157, v179
	v_lshlrev_b32_e32 v160, 16, v154
	v_and_b32_e32 v161, 0xffff0000, v154
	v_lshlrev_b32_e32 v154, 16, v155
	v_and_b32_e32 v155, 0xffff0000, v155
	v_pk_add_f32 v[120:121], v[120:121], v[154:155]
	v_lshlrev_b32_e32 v154, 16, v156
	v_and_b32_e32 v155, 0xffff0000, v156
	v_pk_add_f32 v[154:155], v[114:115], v[154:155]
	v_lshlrev_b32_e32 v114, 16, v157
	v_and_b32_e32 v115, 0xffff0000, v157
	v_pk_add_f32 v[118:119], v[118:119], v[160:161]
	v_pk_add_f32 v[156:157], v[116:117], v[114:115]
	v_cvt_pk_bf16_f32 v114, v118, v119
	v_cvt_pk_bf16_f32 v115, v120, v121
	v_cvt_pk_bf16_f32 v116, v154, v155
	v_cvt_pk_bf16_f32 v117, v156, v157
	global_store_dwordx4 v[158:159], v[114:117], off
	s_nop 1
	v_pk_mul_f32 v[114:115], v[118:119], v[118:119]
	v_pk_mul_f32 v[116:117], v[120:121], v[120:121]
	v_pk_mul_f32 v[118:119], v[154:155], v[154:155]
	v_add_f32_e32 v116, v116, v117
	v_add_f32_e32 v114, v114, v115
	v_pk_mul_f32 v[120:121], v[156:157], v[156:157]
	v_add_f32_e32 v114, v114, v116
	v_add_f32_e32 v115, v118, v119
	v_add_f32_e32 v120, v120, v121
	v_add_f32_e32 v114, v115, v114
	v_add_f32_e32 v114, v120, v114
	v_add_f32_e32 v80, v80, v114
	ds_bpermute_b32 v114, v145, v80
	s_waitcnt lgkmcnt(0)
	v_add_f32_e32 v80, v80, v114
	ds_bpermute_b32 v114, v144, v80
	s_and_saveexec_b64 s[18:19], vcc
	s_cbranch_execz .LBB0_1288
	v_mov_b32_e32 v139, v81
	v_lshl_add_u64 v[116:117], v[138:139], 2, s[12:13]
	s_waitcnt lgkmcnt(0)
	v_add_f32_e32 v80, v80, v114
	global_atomic_add_f32 v[116:117], v80, off
; __device__ __forceinline__ unsigned pk2(float lo, float hi) { f32x2_t v = {lo, hi}; bf16x2_t b = __builtin_convertvector(v, bf16x2_t); return __builtin_bit_cast(unsigned, b); }
; __device__ __forceinline__ float bflo(unsigned w) { return __uint_as_float(w << 16); }
; __device__ __forceinline__ float bfhi(unsigned w) { return __uint_as_float(w & 0xffff0000u); }
;     __device__ __forceinline__ void operator()(const f32x4 (&acc)[2][2][4][2], const pg8::Unit& u, int wr, int wc, int fr_, int fq_) const {
;     ...
;             for (int m = 0; m < 4; ++m) { const unsigned row = (unsigned)(u.pm * 256 + 128 * ai + 64 * wr + 16 * m + fr); float ss = 0.f;
; #pragma unroll
;                 for (int bj = 0; bj < 2; ++bj) { const unsigned o = row * 1024u + (unsigned)(u.pn * 256 + 64 * wc + 32 * bj + 8 * fq);
;                     const u32x4 rb = *(const u32x4*)(resb + o); const f32x4 a0 = acc[ai][bj][m][0], a1 = acc[ai][bj][m][1];
;                     const float y0 = bflo(rb.x) + a0[0], y1 = bfhi(rb.x) + a0[1], y2 = bflo(rb.y) + a0[2], y3 = bfhi(rb.y) + a0[3];
;                     const float y4 = bflo(rb.z) + a1[0], y5 = bfhi(rb.z) + a1[1], y6 = bflo(rb.w) + a1[2], y7 = bfhi(rb.w) + a1[3];
;                     u32x4 w; w.x = pk2(y0, y1); w.y = pk2(y2, y3); w.z = pk2(y4, y5); w.w = pk2(y6, y7);
;                     *(u32x4*)(xb + o) = w;
;                     ss += (y0 * y0 + y1 * y1) + (y2 * y2 + y3 * y3) + (y4 * y4 + y5 * y5) + (y6 * y6 + y7 * y7); }
;                 ss += __shfl_xor(ss, 16); ss += __shfl_xor(ss, 32);
;                 if (fq == 0) atomicAdd(ssq + row, ss);
;                 __builtin_amdgcn_sched_barrier(0); }
.LBB0_1288:
	s_or_b64 exec, exec, s[18:19]
	s_waitcnt lgkmcnt(0)
	v_add_u32_e32 v114, 16, v138
	v_lshl_add_u32 v80, v114, 10, v152
	v_lshlrev_b64 v[120:121], 1, v[80:81]
	v_lshl_add_u64 v[116:117], s[8:9], 0, v[120:121]
	global_load_dwordx4 v[176:179], v[232:233], off offset:64
	v_lshl_add_u64 v[120:121], s[56:57], 0, v[120:121]
	v_add_u32_e32 v80, 32, v80
	s_waitcnt vmcnt(9)
	v_mov_b32_e32 v116, v180
	v_mov_b32_e32 v117, v181
	v_mov_b32_e32 v118, v182
	v_mov_b32_e32 v119, v183
	v_lshlrev_b32_e32 v122, 16, v116
	v_and_b32_e32 v123, 0xffff0000, v116
	v_lshlrev_b32_e32 v116, 16, v117
	v_and_b32_e32 v117, 0xffff0000, v117
	v_pk_add_f32 v[112:113], v[112:113], v[116:117]
	v_lshlrev_b32_e32 v116, 16, v118
	v_and_b32_e32 v117, 0xffff0000, v118
	v_pk_add_f32 v[116:117], v[106:107], v[116:117]
	v_lshlrev_b32_e32 v106, 16, v119
	v_and_b32_e32 v107, 0xffff0000, v119
	v_pk_add_f32 v[110:111], v[110:111], v[122:123]
	v_pk_add_f32 v[118:119], v[108:109], v[106:107]
	v_cvt_pk_bf16_f32 v106, v110, v111
	v_cvt_pk_bf16_f32 v107, v112, v113
	v_cvt_pk_bf16_f32 v108, v116, v117
	v_cvt_pk_bf16_f32 v109, v118, v119
	global_store_dwordx4 v[120:121], v[106:109], off
	v_lshlrev_b64 v[120:121], 1, v[80:81]
	v_pk_mul_f32 v[110:111], v[110:111], v[110:111]
	v_pk_mul_f32 v[108:109], v[116:117], v[116:117]
	v_lshl_add_u64 v[116:117], s[8:9], 0, v[120:121]
	v_pk_mul_f32 v[106:107], v[118:119], v[118:119]
	s_mov_b64 s[98:99], 0x8000
	v_lshl_add_u64 v[232:233], v[232:233], 0, s[98:99]
	global_load_dwordx4 v[180:183], v[232:233], off offset:0
	v_lshl_add_u64 v[120:121], s[56:57], 0, v[120:121]
	v_pk_mul_f32 v[112:113], v[112:113], v[112:113]
	v_add_f32_e32 v110, v110, v111
	v_add_f32_e32 v80, v112, v113
	v_add_f32_e32 v80, v110, v80
	v_add_f32_e32 v108, v108, v109
	v_add_f32_e32 v80, v108, v80
	v_add_f32_e32 v106, v106, v107
	v_add_f32_e32 v80, v106, v80
	s_waitcnt vmcnt(10)
	v_mov_b32_e32 v116, v212
	v_mov_b32_e32 v117, v213
	v_mov_b32_e32 v118, v214
	v_mov_b32_e32 v119, v215
	v_lshlrev_b32_e32 v122, 16, v116
	v_and_b32_e32 v123, 0xffff0000, v116
	v_lshlrev_b32_e32 v116, 16, v117
	v_and_b32_e32 v117, 0xffff0000, v117
	v_pk_add_f32 v[104:105], v[104:105], v[116:117]
	v_lshlrev_b32_e32 v116, 16, v118
	v_and_b32_e32 v117, 0xffff0000, v118
	v_pk_add_f32 v[116:117], v[98:99], v[116:117]
	v_lshlrev_b32_e32 v98, 16, v119
	v_and_b32_e32 v99, 0xffff0000, v119
	v_pk_add_f32 v[102:103], v[102:103], v[122:123]
	v_pk_add_f32 v[118:119], v[100:101], v[98:99]
	v_cvt_pk_bf16_f32 v98, v102, v103
	v_cvt_pk_bf16_f32 v99, v104, v105
	v_cvt_pk_bf16_f32 v100, v116, v117
	v_cvt_pk_bf16_f32 v101, v118, v119
	global_store_dwordx4 v[120:121], v[98:101], off
	s_nop 1
	v_pk_mul_f32 v[98:99], v[102:103], v[102:103]
	v_pk_mul_f32 v[100:101], v[104:105], v[104:105]
	v_pk_mul_f32 v[102:103], v[116:117], v[116:117]
	v_add_f32_e32 v100, v100, v101
	v_add_f32_e32 v98, v98, v99
	v_pk_mul_f32 v[104:105], v[118:119], v[118:119]
	v_add_f32_e32 v98, v98, v100
	v_add_f32_e32 v99, v102, v103
	v_add_f32_e32 v98, v99, v98
	v_add_f32_e32 v99, v104, v105
	v_add_f32_e32 v98, v99, v98
	v_add_f32_e32 v80, v80, v98
	ds_bpermute_b32 v98, v145, v80
	s_waitcnt lgkmcnt(0)
	v_add_f32_e32 v80, v80, v98
	ds_bpermute_b32 v98, v144, v80
	s_and_saveexec_b64 s[18:19], vcc
	s_cbranch_execz .LBB0_1290
	v_mov_b32_e32 v115, v81
	v_lshl_add_u64 v[100:101], v[114:115], 2, s[12:13]
	s_waitcnt lgkmcnt(0)
	v_add_f32_e32 v80, v80, v98
	global_atomic_add_f32 v[100:101], v80, off
.LBB0_1290:
	s_or_b64 exec, exec, s[18:19]
	s_waitcnt lgkmcnt(0)
	v_add_u32_e32 v98, 32, v138
	v_lshl_add_u32 v80, v98, 10, v152
	v_lshlrev_b64 v[104:105], 1, v[80:81]
	v_lshl_add_u64 v[100:101], s[8:9], 0, v[104:105]
	global_load_dwordx4 v[212:215], v[232:233], off offset:64
	v_lshl_add_u64 v[104:105], s[56:57], 0, v[104:105]
	v_add_u32_e32 v80, 32, v80
	s_waitcnt vmcnt(11)
	v_mov_b32_e32 v100, v216
	v_mov_b32_e32 v101, v217
	v_mov_b32_e32 v102, v218
	v_mov_b32_e32 v103, v219
	v_lshlrev_b32_e32 v106, 16, v100
	v_and_b32_e32 v107, 0xffff0000, v100
	v_lshlrev_b32_e32 v100, 16, v101
	v_and_b32_e32 v101, 0xffff0000, v101
	v_pk_add_f32 v[96:97], v[96:97], v[100:101]
	v_lshlrev_b32_e32 v100, 16, v102
	v_and_b32_e32 v101, 0xffff0000, v102
	v_pk_add_f32 v[100:101], v[90:91], v[100:101]
	v_lshlrev_b32_e32 v90, 16, v103
	v_and_b32_e32 v91, 0xffff0000, v103
	v_pk_add_f32 v[94:95], v[94:95], v[106:107]
	v_pk_add_f32 v[102:103], v[92:93], v[90:91]
	v_cvt_pk_bf16_f32 v90, v94, v95
	v_cvt_pk_bf16_f32 v91, v96, v97
	v_cvt_pk_bf16_f32 v92, v100, v101
	v_cvt_pk_bf16_f32 v93, v102, v103
	global_store_dwordx4 v[104:105], v[90:93], off
	v_lshlrev_b64 v[104:105], 1, v[80:81]
	v_pk_mul_f32 v[94:95], v[94:95], v[94:95]
	v_pk_mul_f32 v[92:93], v[100:101], v[100:101]
	v_lshl_add_u64 v[100:101], s[8:9], 0, v[104:105]
	v_pk_mul_f32 v[90:91], v[102:103], v[102:103]
	s_mov_b64 s[98:99], 0x8000
	v_lshl_add_u64 v[232:233], v[232:233], 0, s[98:99]
	global_load_dwordx4 v[216:219], v[232:233], off offset:0
	v_lshl_add_u64 v[104:105], s[56:57], 0, v[104:105]
	v_pk_mul_f32 v[96:97], v[96:97], v[96:97]
	v_add_f32_e32 v94, v94, v95
	v_add_f32_e32 v80, v96, v97
	v_add_f32_e32 v80, v94, v80
	v_add_f32_e32 v92, v92, v93
	v_add_f32_e32 v80, v92, v80
	v_add_f32_e32 v90, v90, v91
	v_add_f32_e32 v80, v90, v80
	s_waitcnt vmcnt(12)
	v_mov_b32_e32 v100, v220
	v_mov_b32_e32 v101, v221
	v_mov_b32_e32 v102, v222
	v_mov_b32_e32 v103, v223
	v_lshlrev_b32_e32 v106, 16, v100
	v_and_b32_e32 v107, 0xffff0000, v100
	v_lshlrev_b32_e32 v100, 16, v101
	v_and_b32_e32 v101, 0xffff0000, v101
	v_pk_add_f32 v[88:89], v[88:89], v[100:101]
	v_lshlrev_b32_e32 v100, 16, v102
	v_and_b32_e32 v101, 0xffff0000, v102
	v_pk_add_f32 v[100:101], v[82:83], v[100:101]
	v_lshlrev_b32_e32 v82, 16, v103
	v_and_b32_e32 v83, 0xffff0000, v103
	v_pk_add_f32 v[86:87], v[86:87], v[106:107]
	v_pk_add_f32 v[102:103], v[84:85], v[82:83]
	v_cvt_pk_bf16_f32 v82, v86, v87
	v_cvt_pk_bf16_f32 v83, v88, v89
	v_cvt_pk_bf16_f32 v84, v100, v101
	v_cvt_pk_bf16_f32 v85, v102, v103
	global_store_dwordx4 v[104:105], v[82:85], off
	s_nop 1
	v_pk_mul_f32 v[82:83], v[86:87], v[86:87]
	v_pk_mul_f32 v[84:85], v[88:89], v[88:89]
	v_pk_mul_f32 v[86:87], v[100:101], v[100:101]
	v_add_f32_e32 v84, v84, v85
	v_add_f32_e32 v82, v82, v83
	v_pk_mul_f32 v[88:89], v[102:103], v[102:103]
	v_add_f32_e32 v82, v82, v84
	v_add_f32_e32 v83, v86, v87
	v_add_f32_e32 v82, v83, v82
	v_add_f32_e32 v83, v88, v89
	v_add_f32_e32 v82, v83, v82
	v_add_f32_e32 v80, v80, v82
	ds_bpermute_b32 v82, v145, v80
	s_waitcnt lgkmcnt(0)
	v_add_f32_e32 v80, v80, v82
	ds_bpermute_b32 v82, v144, v80
	s_and_saveexec_b64 s[18:19], vcc
	s_cbranch_execz .LBB0_1292
	v_mov_b32_e32 v99, v81
	v_lshl_add_u64 v[84:85], v[98:99], 2, s[12:13]
	s_waitcnt lgkmcnt(0)
	v_add_f32_e32 v80, v80, v82
	global_atomic_add_f32 v[84:85], v80, off
; __device__ __forceinline__ unsigned pk2(float lo, float hi) { f32x2_t v = {lo, hi}; bf16x2_t b = __builtin_convertvector(v, bf16x2_t); return __builtin_bit_cast(unsigned, b); }
; __device__ __forceinline__ float bflo(unsigned w) { return __uint_as_float(w << 16); }
; __device__ __forceinline__ float bfhi(unsigned w) { return __uint_as_float(w & 0xffff0000u); }
;     __device__ __forceinline__ void operator()(const f32x4 (&acc)[2][2][4][2], const pg8::Unit& u, int wr, int wc, int fr_, int fq_) const {
;     ...
;             for (int m = 0; m < 4; ++m) { const unsigned row = (unsigned)(u.pm * 256 + 128 * ai + 64 * wr + 16 * m + fr); float ss = 0.f;
; #pragma unroll
;                 for (int bj = 0; bj < 2; ++bj) { const unsigned o = row * 1024u + (unsigned)(u.pn * 256 + 64 * wc + 32 * bj + 8 * fq);
;                     const u32x4 rb = *(const u32x4*)(resb + o); const f32x4 a0 = acc[ai][bj][m][0], a1 = acc[ai][bj][m][1];
;                     const float y0 = bflo(rb.x) + a0[0], y1 = bfhi(rb.x) + a0[1], y2 = bflo(rb.y) + a0[2], y3 = bfhi(rb.y) + a0[3];
;                     const float y4 = bflo(rb.z) + a1[0], y5 = bfhi(rb.z) + a1[1], y6 = bflo(rb.w) + a1[2], y7 = bfhi(rb.w) + a1[3];
;                     u32x4 w; w.x = pk2(y0, y1); w.y = pk2(y2, y3); w.z = pk2(y4, y5); w.w = pk2(y6, y7);
;                     *(u32x4*)(xb + o) = w;
;                     ss += (y0 * y0 + y1 * y1) + (y2 * y2 + y3 * y3) + (y4 * y4 + y5 * y5) + (y6 * y6 + y7 * y7); }
;                 ss += __shfl_xor(ss, 16); ss += __shfl_xor(ss, 32);
;                 if (fq == 0) atomicAdd(ssq + row, ss);
;                 __builtin_amdgcn_sched_barrier(0); }
.LBB0_1292:
	s_or_b64 exec, exec, s[18:19]
	s_waitcnt lgkmcnt(0)
	v_add_u32_e32 v82, 48, v138
	v_lshl_add_u32 v80, v82, 10, v152
	v_lshlrev_b64 v[88:89], 1, v[80:81]
	v_lshl_add_u64 v[84:85], s[8:9], 0, v[88:89]
	global_load_dwordx4 v[220:223], v[232:233], off offset:64
	v_lshl_add_u64 v[88:89], s[56:57], 0, v[88:89]
	v_add_u32_e32 v80, 32, v80
	s_waitcnt vmcnt(13)
	v_mov_b32_e32 v84, v224
	v_mov_b32_e32 v85, v225
	v_mov_b32_e32 v86, v226
	v_mov_b32_e32 v87, v227
	v_lshlrev_b32_e32 v90, 16, v84
	v_and_b32_e32 v91, 0xffff0000, v84
	v_lshlrev_b32_e32 v84, 16, v85
	v_and_b32_e32 v85, 0xffff0000, v85
	v_pk_add_f32 v[78:79], v[78:79], v[84:85]
	v_lshlrev_b32_e32 v84, 16, v86
	v_and_b32_e32 v85, 0xffff0000, v86
	v_pk_add_f32 v[84:85], v[72:73], v[84:85]
	v_lshlrev_b32_e32 v72, 16, v87
	v_and_b32_e32 v73, 0xffff0000, v87
	v_pk_add_f32 v[76:77], v[76:77], v[90:91]
	v_pk_add_f32 v[86:87], v[74:75], v[72:73]
	v_cvt_pk_bf16_f32 v72, v76, v77
	v_cvt_pk_bf16_f32 v73, v78, v79
	v_cvt_pk_bf16_f32 v74, v84, v85
	v_cvt_pk_bf16_f32 v75, v86, v87
	global_store_dwordx4 v[88:89], v[72:75], off
	v_lshlrev_b64 v[88:89], 1, v[80:81]
	v_pk_mul_f32 v[76:77], v[76:77], v[76:77]
	v_pk_mul_f32 v[74:75], v[84:85], v[84:85]
	v_lshl_add_u64 v[84:85], s[8:9], 0, v[88:89]
	v_pk_mul_f32 v[72:73], v[86:87], v[86:87]
	s_mov_b64 s[98:99], 0x8000
	v_lshl_add_u64 v[232:233], v[232:233], 0, s[98:99]
	global_load_dwordx4 v[224:227], v[232:233], off offset:0
	v_lshl_add_u64 v[88:89], s[56:57], 0, v[88:89]
	v_pk_mul_f32 v[78:79], v[78:79], v[78:79]
	v_add_f32_e32 v76, v76, v77
	v_add_f32_e32 v78, v78, v79
	v_add_f32_e32 v76, v76, v78
	v_add_f32_e32 v74, v74, v75
	v_add_f32_e32 v74, v74, v76
	v_add_f32_e32 v72, v72, v73
	v_add_f32_e32 v72, v72, v74
	s_waitcnt vmcnt(14)
	v_mov_b32_e32 v84, v228
	v_mov_b32_e32 v85, v229
	v_mov_b32_e32 v86, v230
	v_mov_b32_e32 v87, v231
	v_lshlrev_b32_e32 v90, 16, v84
	v_and_b32_e32 v91, 0xffff0000, v84
	v_lshlrev_b32_e32 v84, 16, v85
	v_and_b32_e32 v85, 0xffff0000, v85
	v_pk_add_f32 v[70:71], v[70:71], v[84:85]
	v_lshlrev_b32_e32 v84, 16, v86
	v_and_b32_e32 v85, 0xffff0000, v86
	v_pk_add_f32 v[84:85], v[64:65], v[84:85]
	v_lshlrev_b32_e32 v64, 16, v87
	v_and_b32_e32 v65, 0xffff0000, v87
	v_pk_add_f32 v[68:69], v[68:69], v[90:91]
	v_pk_add_f32 v[86:87], v[66:67], v[64:65]
	v_cvt_pk_bf16_f32 v64, v68, v69
	v_cvt_pk_bf16_f32 v65, v70, v71
	v_cvt_pk_bf16_f32 v66, v84, v85
	v_cvt_pk_bf16_f32 v67, v86, v87
	global_store_dwordx4 v[88:89], v[64:67], off
	s_nop 1
	v_pk_mul_f32 v[64:65], v[68:69], v[68:69]
	v_pk_mul_f32 v[66:67], v[70:71], v[70:71]
	v_pk_mul_f32 v[68:69], v[84:85], v[84:85]
	v_add_f32_e32 v66, v66, v67
	v_add_f32_e32 v64, v64, v65
	v_pk_mul_f32 v[70:71], v[86:87], v[86:87]
	v_add_f32_e32 v64, v64, v66
	v_add_f32_e32 v65, v68, v69
	v_add_f32_e32 v64, v65, v64
	v_add_f32_e32 v65, v70, v71
	v_add_f32_e32 v64, v65, v64
	v_add_f32_e32 v64, v72, v64
	ds_bpermute_b32 v65, v145, v64
	s_waitcnt lgkmcnt(0)
	v_add_f32_e32 v64, v64, v65
	ds_bpermute_b32 v65, v144, v64
	s_and_saveexec_b64 s[18:19], vcc
	s_cbranch_execz .LBB0_1294
	v_mov_b32_e32 v83, v81
	v_lshl_add_u64 v[66:67], v[82:83], 2, s[12:13]
	s_waitcnt lgkmcnt(0)
	v_add_f32_e32 v64, v64, v65
	global_atomic_add_f32 v[66:67], v64, off
.LBB0_1294:
	s_or_b64 exec, exec, s[18:19]
	v_add_u32_e32 v64, 0x80, v138
	v_lshl_add_u32 v80, v64, 10, v152
	v_lshlrev_b64 v[70:71], 1, v[80:81]
	v_lshl_add_u64 v[66:67], s[8:9], 0, v[70:71]
	global_load_dwordx4 v[228:231], v[232:233], off offset:64
	v_lshl_add_u64 v[70:71], s[56:57], 0, v[70:71]
	v_add_u32_e32 v80, 32, v80
	s_waitcnt vmcnt(14)
	v_mov_b32_e32 v66, v172
	v_mov_b32_e32 v67, v173
	v_mov_b32_e32 v68, v174
	v_mov_b32_e32 v69, v175
	v_lshlrev_b32_e32 v72, 16, v66
	v_and_b32_e32 v73, 0xffff0000, v66
	v_lshlrev_b32_e32 v66, 16, v67
	v_and_b32_e32 v67, 0xffff0000, v67
	v_pk_add_f32 v[62:63], v[62:63], v[66:67]
	v_lshlrev_b32_e32 v66, 16, v68
	v_and_b32_e32 v67, 0xffff0000, v68
	v_pk_add_f32 v[66:67], v[56:57], v[66:67]
	v_lshlrev_b32_e32 v56, 16, v69
	v_and_b32_e32 v57, 0xffff0000, v69
	v_pk_add_f32 v[60:61], v[60:61], v[72:73]
	v_pk_add_f32 v[68:69], v[58:59], v[56:57]
	v_cvt_pk_bf16_f32 v56, v60, v61
	v_cvt_pk_bf16_f32 v57, v62, v63
	v_cvt_pk_bf16_f32 v58, v66, v67
	v_cvt_pk_bf16_f32 v59, v68, v69
	global_store_dwordx4 v[70:71], v[56:59], off
	v_lshlrev_b64 v[70:71], 1, v[80:81]
	v_pk_mul_f32 v[60:61], v[60:61], v[60:61]
	v_pk_mul_f32 v[58:59], v[66:67], v[66:67]
	v_lshl_add_u64 v[66:67], s[8:9], 0, v[70:71]
	v_pk_mul_f32 v[56:57], v[68:69], v[68:69]
	v_lshl_add_u64 v[70:71], s[56:57], 0, v[70:71]
	v_pk_mul_f32 v[62:63], v[62:63], v[62:63]
	v_add_f32_e32 v60, v60, v61
	v_add_f32_e32 v62, v62, v63
	v_add_f32_e32 v60, v60, v62
	v_add_f32_e32 v58, v58, v59
	v_add_f32_e32 v58, v58, v60
	v_add_f32_e32 v56, v56, v57
	v_add_f32_e32 v56, v56, v58
	s_waitcnt vmcnt(13)
	v_mov_b32_e32 v66, v176
	v_mov_b32_e32 v67, v177
	v_mov_b32_e32 v68, v178
	v_mov_b32_e32 v69, v179
	v_lshlrev_b32_e32 v72, 16, v66
	v_and_b32_e32 v73, 0xffff0000, v66
	v_lshlrev_b32_e32 v66, 16, v67
	v_and_b32_e32 v67, 0xffff0000, v67
	v_pk_add_f32 v[54:55], v[54:55], v[66:67]
	v_lshlrev_b32_e32 v66, 16, v68
	v_and_b32_e32 v67, 0xffff0000, v68
	v_pk_add_f32 v[66:67], v[48:49], v[66:67]
	v_lshlrev_b32_e32 v48, 16, v69
	v_and_b32_e32 v49, 0xffff0000, v69
	v_pk_add_f32 v[52:53], v[52:53], v[72:73]
	v_pk_add_f32 v[68:69], v[50:51], v[48:49]
	v_cvt_pk_bf16_f32 v48, v52, v53
	v_cvt_pk_bf16_f32 v49, v54, v55
	v_cvt_pk_bf16_f32 v50, v66, v67
	v_cvt_pk_bf16_f32 v51, v68, v69
	global_store_dwordx4 v[70:71], v[48:51], off
	s_nop 1
	v_pk_mul_f32 v[48:49], v[52:53], v[52:53]
	v_pk_mul_f32 v[50:51], v[54:55], v[54:55]
	v_pk_mul_f32 v[52:53], v[66:67], v[66:67]
	v_add_f32_e32 v50, v50, v51
	v_add_f32_e32 v48, v48, v49
	v_pk_mul_f32 v[54:55], v[68:69], v[68:69]
	v_add_f32_e32 v48, v48, v50
	v_add_f32_e32 v49, v52, v53
	v_add_f32_e32 v48, v49, v48
	v_add_f32_e32 v49, v54, v55
	v_add_f32_e32 v48, v49, v48
	v_add_f32_e32 v48, v56, v48
	ds_bpermute_b32 v49, v145, v48
	s_waitcnt lgkmcnt(0)
	v_add_f32_e32 v48, v48, v49
	ds_bpermute_b32 v49, v144, v48
	s_and_saveexec_b64 s[18:19], vcc
	s_cbranch_execz .LBB0_1296
	v_mov_b32_e32 v65, v81
	v_lshl_add_u64 v[50:51], v[64:65], 2, s[12:13]
	s_waitcnt lgkmcnt(0)
	v_add_f32_e32 v48, v48, v49
	global_atomic_add_f32 v[50:51], v48, off
; __device__ __forceinline__ unsigned pk2(float lo, float hi) { f32x2_t v = {lo, hi}; bf16x2_t b = __builtin_convertvector(v, bf16x2_t); return __builtin_bit_cast(unsigned, b); }
; __device__ __forceinline__ float bflo(unsigned w) { return __uint_as_float(w << 16); }
; __device__ __forceinline__ float bfhi(unsigned w) { return __uint_as_float(w & 0xffff0000u); }
;     __device__ __forceinline__ void operator()(const f32x4 (&acc)[2][2][4][2], const pg8::Unit& u, int wr, int wc, int fr_, int fq_) const {
;     ...
;             for (int m = 0; m < 4; ++m) { const unsigned row = (unsigned)(u.pm * 256 + 128 * ai + 64 * wr + 16 * m + fr); float ss = 0.f;
; #pragma unroll
;                 for (int bj = 0; bj < 2; ++bj) { const unsigned o = row * 1024u + (unsigned)(u.pn * 256 + 64 * wc + 32 * bj + 8 * fq);
;                     const u32x4 rb = *(const u32x4*)(resb + o); const f32x4 a0 = acc[ai][bj][m][0], a1 = acc[ai][bj][m][1];
;                     const float y0 = bflo(rb.x) + a0[0], y1 = bfhi(rb.x) + a0[1], y2 = bflo(rb.y) + a0[2], y3 = bfhi(rb.y) + a0[3];
;                     const float y4 = bflo(rb.z) + a1[0], y5 = bfhi(rb.z) + a1[1], y6 = bflo(rb.w) + a1[2], y7 = bfhi(rb.w) + a1[3];
;                     u32x4 w; w.x = pk2(y0, y1); w.y = pk2(y2, y3); w.z = pk2(y4, y5); w.w = pk2(y6, y7);
;                     *(u32x4*)(xb + o) = w;
;                     ss += (y0 * y0 + y1 * y1) + (y2 * y2 + y3 * y3) + (y4 * y4 + y5 * y5) + (y6 * y6 + y7 * y7); }
;                 ss += __shfl_xor(ss, 16); ss += __shfl_xor(ss, 32);
;                 if (fq == 0) atomicAdd(ssq + row, ss);
;                 __builtin_amdgcn_sched_barrier(0); }
.LBB0_1296:
	s_or_b64 exec, exec, s[18:19]
	v_add_u32_e32 v48, 0x90, v138
	v_lshl_add_u32 v80, v48, 10, v152
	v_lshlrev_b64 v[54:55], 1, v[80:81]
	v_lshl_add_u64 v[50:51], s[8:9], 0, v[54:55]
	v_lshl_add_u64 v[54:55], s[56:57], 0, v[54:55]
	v_add_u32_e32 v80, 32, v80
	s_waitcnt vmcnt(12)
	v_mov_b32_e32 v50, v180
	v_mov_b32_e32 v51, v181
	v_mov_b32_e32 v52, v182
	v_mov_b32_e32 v53, v183
	v_lshlrev_b32_e32 v56, 16, v50
	v_and_b32_e32 v57, 0xffff0000, v50
	v_lshlrev_b32_e32 v50, 16, v51
	v_and_b32_e32 v51, 0xffff0000, v51
	v_pk_add_f32 v[46:47], v[46:47], v[50:51]
	v_lshlrev_b32_e32 v50, 16, v52
	v_and_b32_e32 v51, 0xffff0000, v52
	v_pk_add_f32 v[50:51], v[40:41], v[50:51]
	v_lshlrev_b32_e32 v40, 16, v53
	v_and_b32_e32 v41, 0xffff0000, v53
	v_pk_add_f32 v[44:45], v[44:45], v[56:57]
	v_pk_add_f32 v[52:53], v[42:43], v[40:41]
	v_cvt_pk_bf16_f32 v40, v44, v45
	v_cvt_pk_bf16_f32 v41, v46, v47
	v_cvt_pk_bf16_f32 v42, v50, v51
	v_cvt_pk_bf16_f32 v43, v52, v53
	global_store_dwordx4 v[54:55], v[40:43], off
	v_lshlrev_b64 v[54:55], 1, v[80:81]
	v_pk_mul_f32 v[44:45], v[44:45], v[44:45]
	v_pk_mul_f32 v[42:43], v[50:51], v[50:51]
	v_lshl_add_u64 v[50:51], s[8:9], 0, v[54:55]
	v_pk_mul_f32 v[40:41], v[52:53], v[52:53]
	v_lshl_add_u64 v[54:55], s[56:57], 0, v[54:55]
	v_pk_mul_f32 v[46:47], v[46:47], v[46:47]
	v_add_f32_e32 v44, v44, v45
	v_add_f32_e32 v46, v46, v47
	v_add_f32_e32 v44, v44, v46
	v_add_f32_e32 v42, v42, v43
	v_add_f32_e32 v42, v42, v44
	v_add_f32_e32 v40, v40, v41
	v_add_f32_e32 v40, v40, v42
	s_waitcnt vmcnt(11)
	v_mov_b32_e32 v50, v212
	v_mov_b32_e32 v51, v213
	v_mov_b32_e32 v52, v214
	v_mov_b32_e32 v53, v215
	v_lshlrev_b32_e32 v56, 16, v50
	v_and_b32_e32 v57, 0xffff0000, v50
	v_lshlrev_b32_e32 v50, 16, v51
	v_and_b32_e32 v51, 0xffff0000, v51
	v_pk_add_f32 v[38:39], v[38:39], v[50:51]
	v_lshlrev_b32_e32 v50, 16, v52
	v_and_b32_e32 v51, 0xffff0000, v52
	v_pk_add_f32 v[50:51], v[32:33], v[50:51]
	v_lshlrev_b32_e32 v32, 16, v53
	v_and_b32_e32 v33, 0xffff0000, v53
	v_pk_add_f32 v[36:37], v[36:37], v[56:57]
	v_pk_add_f32 v[52:53], v[34:35], v[32:33]
	v_cvt_pk_bf16_f32 v32, v36, v37
	v_cvt_pk_bf16_f32 v33, v38, v39
	v_cvt_pk_bf16_f32 v34, v50, v51
	v_cvt_pk_bf16_f32 v35, v52, v53
	global_store_dwordx4 v[54:55], v[32:35], off
	s_nop 1
	v_pk_mul_f32 v[32:33], v[36:37], v[36:37]
	v_pk_mul_f32 v[34:35], v[38:39], v[38:39]
	v_pk_mul_f32 v[36:37], v[50:51], v[50:51]
	v_add_f32_e32 v34, v34, v35
	v_add_f32_e32 v32, v32, v33
	v_pk_mul_f32 v[38:39], v[52:53], v[52:53]
	v_add_f32_e32 v32, v32, v34
	v_add_f32_e32 v33, v36, v37
	v_add_f32_e32 v32, v33, v32
	v_add_f32_e32 v33, v38, v39
	v_add_f32_e32 v32, v33, v32
	v_add_f32_e32 v32, v40, v32
	ds_bpermute_b32 v33, v145, v32
	s_waitcnt lgkmcnt(0)
	v_add_f32_e32 v32, v32, v33
	ds_bpermute_b32 v33, v144, v32
	s_and_saveexec_b64 s[18:19], vcc
	s_cbranch_execz .LBB0_1298
	v_mov_b32_e32 v49, v81
	v_lshl_add_u64 v[34:35], v[48:49], 2, s[12:13]
	s_waitcnt lgkmcnt(0)
	v_add_f32_e32 v32, v32, v33
	global_atomic_add_f32 v[34:35], v32, off
; __device__ __forceinline__ unsigned pk2(float lo, float hi) { f32x2_t v = {lo, hi}; bf16x2_t b = __builtin_convertvector(v, bf16x2_t); return __builtin_bit_cast(unsigned, b); }
; __device__ __forceinline__ float bflo(unsigned w) { return __uint_as_float(w << 16); }
; __device__ __forceinline__ float bfhi(unsigned w) { return __uint_as_float(w & 0xffff0000u); }
;     __device__ __forceinline__ void operator()(const f32x4 (&acc)[2][2][4][2], const pg8::Unit& u, int wr, int wc, int fr_, int fq_) const {
;     ...
;             for (int m = 0; m < 4; ++m) { const unsigned row = (unsigned)(u.pm * 256 + 128 * ai + 64 * wr + 16 * m + fr); float ss = 0.f;
; #pragma unroll
;                 for (int bj = 0; bj < 2; ++bj) { const unsigned o = row * 1024u + (unsigned)(u.pn * 256 + 64 * wc + 32 * bj + 8 * fq);
;                     const u32x4 rb = *(const u32x4*)(resb + o); const f32x4 a0 = acc[ai][bj][m][0], a1 = acc[ai][bj][m][1];
;                     const float y0 = bflo(rb.x) + a0[0], y1 = bfhi(rb.x) + a0[1], y2 = bflo(rb.y) + a0[2], y3 = bfhi(rb.y) + a0[3];
;                     const float y4 = bflo(rb.z) + a1[0], y5 = bfhi(rb.z) + a1[1], y6 = bflo(rb.w) + a1[2], y7 = bfhi(rb.w) + a1[3];
;                     u32x4 w; w.x = pk2(y0, y1); w.y = pk2(y2, y3); w.z = pk2(y4, y5); w.w = pk2(y6, y7);
;                     *(u32x4*)(xb + o) = w;
;                     ss += (y0 * y0 + y1 * y1) + (y2 * y2 + y3 * y3) + (y4 * y4 + y5 * y5) + (y6 * y6 + y7 * y7); }
;                 ss += __shfl_xor(ss, 16); ss += __shfl_xor(ss, 32);
;                 if (fq == 0) atomicAdd(ssq + row, ss);
;                 __builtin_amdgcn_sched_barrier(0); }
.LBB0_1298:
	s_or_b64 exec, exec, s[18:19]
	v_add_u32_e32 v32, 0xa0, v138
	v_lshl_add_u32 v80, v32, 10, v152
	v_lshlrev_b64 v[38:39], 1, v[80:81]
	v_lshl_add_u64 v[34:35], s[8:9], 0, v[38:39]
	v_lshl_add_u64 v[38:39], s[56:57], 0, v[38:39]
	v_add_u32_e32 v80, 32, v80
	s_waitcnt vmcnt(10)
	v_mov_b32_e32 v34, v216
	v_mov_b32_e32 v35, v217
	v_mov_b32_e32 v36, v218
	v_mov_b32_e32 v37, v219
	v_lshlrev_b32_e32 v40, 16, v34
	v_and_b32_e32 v41, 0xffff0000, v34
	v_lshlrev_b32_e32 v34, 16, v35
	v_and_b32_e32 v35, 0xffff0000, v35
	v_pk_add_f32 v[30:31], v[30:31], v[34:35]
	v_lshlrev_b32_e32 v34, 16, v36
	v_and_b32_e32 v35, 0xffff0000, v36
	v_pk_add_f32 v[34:35], v[24:25], v[34:35]
	v_lshlrev_b32_e32 v24, 16, v37
	v_and_b32_e32 v25, 0xffff0000, v37
	v_pk_add_f32 v[28:29], v[28:29], v[40:41]
	v_pk_add_f32 v[36:37], v[26:27], v[24:25]
	v_cvt_pk_bf16_f32 v24, v28, v29
	v_cvt_pk_bf16_f32 v25, v30, v31
	v_cvt_pk_bf16_f32 v26, v34, v35
	v_cvt_pk_bf16_f32 v27, v36, v37
	global_store_dwordx4 v[38:39], v[24:27], off
	v_lshlrev_b64 v[38:39], 1, v[80:81]
	v_pk_mul_f32 v[28:29], v[28:29], v[28:29]
	v_pk_mul_f32 v[26:27], v[34:35], v[34:35]
	v_lshl_add_u64 v[34:35], s[8:9], 0, v[38:39]
	v_pk_mul_f32 v[24:25], v[36:37], v[36:37]
	v_lshl_add_u64 v[38:39], s[56:57], 0, v[38:39]
	v_pk_mul_f32 v[30:31], v[30:31], v[30:31]
	v_add_f32_e32 v28, v28, v29
	v_add_f32_e32 v30, v30, v31
	v_add_f32_e32 v28, v28, v30
	v_add_f32_e32 v26, v26, v27
	v_add_f32_e32 v26, v26, v28
	v_add_f32_e32 v24, v24, v25
	v_add_f32_e32 v24, v24, v26
	s_waitcnt vmcnt(9)
	v_mov_b32_e32 v34, v220
	v_mov_b32_e32 v35, v221
	v_mov_b32_e32 v36, v222
	v_mov_b32_e32 v37, v223
	v_lshlrev_b32_e32 v40, 16, v34
	v_and_b32_e32 v41, 0xffff0000, v34
	v_lshlrev_b32_e32 v34, 16, v35
	v_and_b32_e32 v35, 0xffff0000, v35
	v_pk_add_f32 v[22:23], v[22:23], v[34:35]
	v_lshlrev_b32_e32 v34, 16, v36
	v_and_b32_e32 v35, 0xffff0000, v36
	v_pk_add_f32 v[34:35], v[16:17], v[34:35]
	v_lshlrev_b32_e32 v16, 16, v37
	v_and_b32_e32 v17, 0xffff0000, v37
	v_pk_add_f32 v[20:21], v[20:21], v[40:41]
	v_pk_add_f32 v[36:37], v[18:19], v[16:17]
	v_cvt_pk_bf16_f32 v16, v20, v21
	v_cvt_pk_bf16_f32 v17, v22, v23
	v_cvt_pk_bf16_f32 v18, v34, v35
	v_cvt_pk_bf16_f32 v19, v36, v37
	global_store_dwordx4 v[38:39], v[16:19], off
	s_nop 1
	v_pk_mul_f32 v[16:17], v[20:21], v[20:21]
	v_pk_mul_f32 v[18:19], v[22:23], v[22:23]
	v_pk_mul_f32 v[20:21], v[34:35], v[34:35]
	v_add_f32_e32 v18, v18, v19
	v_add_f32_e32 v16, v16, v17
	v_pk_mul_f32 v[22:23], v[36:37], v[36:37]
	v_add_f32_e32 v16, v16, v18
	v_add_f32_e32 v17, v20, v21
	v_add_f32_e32 v16, v17, v16
	v_add_f32_e32 v17, v22, v23
	v_add_f32_e32 v16, v17, v16
	v_add_f32_e32 v16, v24, v16
	ds_bpermute_b32 v17, v145, v16
	s_waitcnt lgkmcnt(0)
	v_add_f32_e32 v16, v16, v17
	ds_bpermute_b32 v17, v144, v16
	s_and_saveexec_b64 s[18:19], vcc
	s_cbranch_execz .LBB0_1300
	v_mov_b32_e32 v33, v81
	v_lshl_add_u64 v[18:19], v[32:33], 2, s[12:13]
	s_waitcnt lgkmcnt(0)
	v_add_f32_e32 v16, v16, v17
	global_atomic_add_f32 v[18:19], v16, off
.LBB0_1300:
	s_or_b64 exec, exec, s[18:19]
	v_add_u32_e32 v16, 0xb0, v138
	v_lshl_add_u32 v80, v16, 10, v152
	v_lshlrev_b64 v[22:23], 1, v[80:81]
	v_lshl_add_u64 v[18:19], s[8:9], 0, v[22:23]
	v_lshl_add_u64 v[22:23], s[56:57], 0, v[22:23]
	v_add_u32_e32 v80, 32, v80
	s_waitcnt vmcnt(8)
	v_mov_b32_e32 v18, v224
	v_mov_b32_e32 v19, v225
	v_mov_b32_e32 v20, v226
	v_mov_b32_e32 v21, v227
	v_lshlrev_b32_e32 v24, 16, v18
	v_and_b32_e32 v25, 0xffff0000, v18
	v_lshlrev_b32_e32 v18, 16, v19
	v_and_b32_e32 v19, 0xffff0000, v19
	v_pk_add_f32 v[14:15], v[14:15], v[18:19]
	v_lshlrev_b32_e32 v18, 16, v20
	v_and_b32_e32 v19, 0xffff0000, v20
	v_pk_add_f32 v[18:19], v[8:9], v[18:19]
	v_lshlrev_b32_e32 v8, 16, v21
	v_and_b32_e32 v9, 0xffff0000, v21
	v_pk_add_f32 v[12:13], v[12:13], v[24:25]
	v_pk_add_f32 v[20:21], v[10:11], v[8:9]
	v_cvt_pk_bf16_f32 v8, v12, v13
	v_cvt_pk_bf16_f32 v9, v14, v15
	v_cvt_pk_bf16_f32 v10, v18, v19
	v_cvt_pk_bf16_f32 v11, v20, v21
	global_store_dwordx4 v[22:23], v[8:11], off
	v_lshlrev_b64 v[22:23], 1, v[80:81]
	v_pk_mul_f32 v[12:13], v[12:13], v[12:13]
	v_pk_mul_f32 v[10:11], v[18:19], v[18:19]
	v_lshl_add_u64 v[18:19], s[8:9], 0, v[22:23]
	v_pk_mul_f32 v[8:9], v[20:21], v[20:21]
	v_lshl_add_u64 v[22:23], s[56:57], 0, v[22:23]
	v_pk_mul_f32 v[14:15], v[14:15], v[14:15]
	v_add_f32_e32 v12, v12, v13
	v_add_f32_e32 v14, v14, v15
	v_add_f32_e32 v12, v12, v14
	v_add_f32_e32 v10, v10, v11
	v_add_f32_e32 v10, v10, v12
	v_add_f32_e32 v8, v8, v9
	v_add_f32_e32 v8, v8, v10
	s_waitcnt vmcnt(7)
	v_mov_b32_e32 v18, v228
	v_mov_b32_e32 v19, v229
	v_mov_b32_e32 v20, v230
	v_mov_b32_e32 v21, v231
	v_lshlrev_b32_e32 v24, 16, v18
	v_and_b32_e32 v25, 0xffff0000, v18
	v_lshlrev_b32_e32 v18, 16, v19
	v_and_b32_e32 v19, 0xffff0000, v19
	v_pk_add_f32 v[6:7], v[6:7], v[18:19]
	v_lshlrev_b32_e32 v18, 16, v20
	v_and_b32_e32 v19, 0xffff0000, v20
	v_pk_add_f32 v[18:19], v[0:1], v[18:19]
	v_lshlrev_b32_e32 v0, 16, v21
	v_and_b32_e32 v1, 0xffff0000, v21
	v_pk_add_f32 v[4:5], v[4:5], v[24:25]
	v_pk_add_f32 v[20:21], v[2:3], v[0:1]
	v_cvt_pk_bf16_f32 v0, v4, v5
	v_cvt_pk_bf16_f32 v1, v6, v7
	v_cvt_pk_bf16_f32 v2, v18, v19
	v_cvt_pk_bf16_f32 v3, v20, v21
	global_store_dwordx4 v[22:23], v[0:3], off
	s_nop 1
	v_pk_mul_f32 v[0:1], v[4:5], v[4:5]
	v_pk_mul_f32 v[2:3], v[6:7], v[6:7]
	v_pk_mul_f32 v[4:5], v[18:19], v[18:19]
	v_add_f32_e32 v2, v2, v3
	v_add_f32_e32 v0, v0, v1
	v_pk_mul_f32 v[6:7], v[20:21], v[20:21]
	v_add_f32_e32 v0, v0, v2
	v_add_f32_e32 v1, v4, v5
	v_add_f32_e32 v0, v1, v0
	v_add_f32_e32 v1, v6, v7
	v_add_f32_e32 v0, v1, v0
	v_add_f32_e32 v0, v8, v0
	ds_bpermute_b32 v1, v145, v0
	s_waitcnt lgkmcnt(0)
	v_add_f32_e32 v0, v0, v1
	ds_bpermute_b32 v1, v144, v0
	s_and_saveexec_b64 s[18:19], vcc
	s_cbranch_execz .LBB0_1302
	v_mov_b32_e32 v17, v81
	v_lshl_add_u64 v[2:3], v[16:17], 2, s[12:13]
	s_waitcnt lgkmcnt(0)
	v_add_f32_e32 v0, v0, v1
	global_atomic_add_f32 v[2:3], v0, off
